# attention: pipelined QK LDS reads + counted vmcnt at tile barriers + epilogue lone-load de-serialization
# baseline (speedup 1.0000x reference)
.LBB0_879:
	s_waitcnt vmcnt(0)
	v_mov_b32_e32 v2, v198
	s_barrier
	v_readlane_b32 s0, v254, 1
	v_bfe_u32 v4, v2, 5, 1
	v_and_b32_e32 v3, 0x3fffffc0, v2
	v_and_b32_e32 v0, 31, v2
	v_lshl_add_u32 v5, v3, 2, s0
	v_cmp_eq_u32_e32 vcc, 0, v4
	s_and_saveexec_b64 s[0:1], vcc
	v_lshl_add_u32 v3, v0, 2, v5
	ds_write_b32 v3, v153
	s_or_b64 exec, exec, s[0:1]
	v_readlane_b32 s0, v253, 12
	v_lshlrev_b32_e32 v0, 1, v0
	v_readlane_b32 s1, v253, 13
	v_ashrrev_i32_e32 v2, 1, v2
	v_and_b32_e32 v8, 0xffffffe0, v2
	v_lshl_add_u64 v[6:7], s[0:1], 0, v[0:1]
	v_readlane_b32 s0, v253, 14
	v_readlane_b32 s1, v253, 15
	s_waitcnt lgkmcnt(0)
	v_lshl_add_u32 v90, v4, 4, v5
	ds_read_b128 v[80:83], v90
	ds_read_b128 v[98:101], v90 offset:32
	v_lshl_add_u64 v[2:3], s[0:1], 0, v[0:1]
	v_lshl_or_b32 v0, v4, 2, v8
	v_readlane_b32 s0, v253, 6
	v_mov_b32_e32 v5, v1
	s_waitcnt lgkmcnt(1)
	v_rcp_f32_e32 v107, v80
	v_add_u32_e32 v8, s0, v0
	s_movk_i32 s0, 0x1100
	v_mul_lo_u32 v0, v8, s0
	v_add_u32_e32 v4, 0x1100, v0
	v_lshl_add_u64 v[10:11], v[4:5], 1, v[6:7]
	v_add_u32_e32 v4, 0x2200, v0
	v_lshl_add_u64 v[12:13], v[4:5], 1, v[6:7]
	v_add_u32_e32 v4, 0x3300, v0
	v_lshl_add_u64 v[14:15], v[4:5], 1, v[6:7]
	v_add_u32_e32 v4, 0x8800, v0
	v_rcp_f32_e32 v102, v81
	v_lshl_add_u64 v[80:81], v[4:5], 1, v[6:7]
	v_add_u32_e32 v4, 0x9900, v0
	v_rcp_f32_e32 v97, v82
	v_rcp_f32_e32 v95, v83
	v_lshl_add_u64 v[82:83], v[4:5], 1, v[6:7]
	v_add_u32_e32 v4, 0xaa00, v0
	v_lshl_add_u64 v[84:85], v[4:5], 1, v[6:7]
	v_add_u32_e32 v4, 0xbb00, v0
	s_movk_i32 s0, 0xa00
	v_lshl_add_u64 v[88:89], v[0:1], 1, v[6:7]
	v_lshl_add_u64 v[86:87], v[4:5], 1, v[6:7]
	v_mul_lo_u32 v4, v8, s0
	v_lshl_add_u64 v[8:9], v[4:5], 1, v[2:3]
	v_mul_f32_e32 v5, v64, v107
	global_load_ushort v201, v[88:89], off
	s_waitcnt lgkmcnt(0)
	v_rcp_f32_e32 v94, v98
	v_rcp_f32_e32 v93, v99
	v_rcp_f32_e32 v92, v100
	v_rcp_f32_e32 v91, v101
	v_mul_f32_e32 v48, v48, v107
	v_mul_f32_e32 v32, v32, v107
	v_mul_f32_e32 v16, v16, v107
	v_mov_b32_e32 v200, v5
	global_load_ushort v110, v[88:89], off offset:64
	global_load_ushort v111, v[88:89], off offset:128
	global_load_ushort v112, v[88:89], off offset:192
	global_load_ushort v113, v[10:11], off
	global_load_ushort v114, v[10:11], off offset:64
	global_load_ushort v115, v[10:11], off offset:128
	global_load_ushort v116, v[10:11], off offset:192
	global_load_ushort v117, v[12:13], off
	global_load_ushort v118, v[12:13], off offset:64
	global_load_ushort v108, v[12:13], off offset:128
	global_load_ushort v106, v[12:13], off offset:192
	global_load_ushort v105, v[14:15], off
	global_load_ushort v104, v[14:15], off offset:64
	global_load_ushort v103, v[14:15], off offset:128
	global_load_ushort v101, v[14:15], off offset:192
	global_load_ushort v100, v[80:81], off
	global_load_ushort v99, v[80:81], off offset:64
	global_load_ushort v98, v[80:81], off offset:128
	global_load_ushort v96, v[80:81], off offset:192
	global_load_ushort v89, v[82:83], off
	global_load_ushort v88, v[82:83], off offset:64
	s_nop 0
	global_load_ushort v81, v[82:83], off offset:128
	global_load_ushort v80, v[82:83], off offset:192
	global_load_ushort v64, v[84:85], off
	global_load_ushort v15, v[84:85], off offset:64
	global_load_ushort v14, v[84:85], off offset:128
	global_load_ushort v13, v[84:85], off offset:192
	global_load_ushort v12, v[86:87], off
	global_load_ushort v11, v[86:87], off offset:64
	global_load_ushort v10, v[86:87], off offset:128
	global_load_ushort v5, v[86:87], off offset:192
	s_waitcnt vmcnt(31)
	v_lshlrev_b32_e32 v201, 16, v201
	v_mul_f32_e32 v200, v200, v201
	v_mul_f32_e32 v201, 0xbfb8aa3b, v201
	v_exp_f32_e32 v201, v201
	s_nop 0
	v_add_f32_e32 v201, 1.0, v201
	v_rcp_f32_e32 v201, v201
	s_nop 0
	v_mul_f32_e32 v109, v200, v201
	v_cvt_pk_bf16_f32 v82, v109, v109
	global_store_short v[8:9], v82, off
	s_waitcnt vmcnt(31)
	v_lshlrev_b32_e32 v82, 16, v110
	v_mul_f32_e32 v48, v48, v82
	v_mul_f32_e32 v82, 0xbfb8aa3b, v82
	v_exp_f32_e32 v82, v82
	s_waitcnt vmcnt(7)
	v_lshlrev_b32_e32 v15, 16, v15
	v_add_f32_e32 v82, 1.0, v82
	v_rcp_f32_e32 v82, v82
	s_waitcnt vmcnt(6)
	v_lshlrev_b32_e32 v14, 16, v14
	s_waitcnt vmcnt(5)
	v_lshlrev_b32_e32 v13, 16, v13
	s_waitcnt vmcnt(4)
	v_lshlrev_b32_e32 v12, 16, v12
	v_mul_f32_e32 v48, v48, v82
	v_cvt_pk_bf16_f32 v48, v48, v48
	global_store_short v[8:9], v48, off offset:64
	v_lshlrev_b32_e32 v48, 16, v111
	v_mul_f32_e32 v32, v32, v48
	v_mul_f32_e32 v48, 0xbfb8aa3b, v48
	v_exp_f32_e32 v48, v48
	s_waitcnt vmcnt(4)
	v_lshlrev_b32_e32 v11, 16, v11
	s_waitcnt vmcnt(3)
	v_lshlrev_b32_e32 v10, 16, v10
	s_waitcnt vmcnt(2)
	v_lshlrev_b32_e32 v5, 16, v5
	v_add_f32_e32 v48, 1.0, v48
	v_rcp_f32_e32 v48, v48
	s_nop 0
	v_mul_f32_e32 v32, v32, v48
	v_cvt_pk_bf16_f32 v32, v32, v32
	global_store_short v[8:9], v32, off offset:128
	v_lshlrev_b32_e32 v32, 16, v112
	v_mul_f32_e32 v16, v16, v32
	v_mul_f32_e32 v32, 0xbfb8aa3b, v32
	v_exp_f32_e32 v32, v32
	s_nop 0
	v_add_f32_e32 v32, 1.0, v32
	v_rcp_f32_e32 v32, v32
	s_nop 0
	v_mul_f32_e32 v16, v16, v32
	v_cvt_pk_bf16_f32 v16, v16, v16
	global_store_short v[8:9], v16, off offset:192
	v_mul_f32_e32 v16, v65, v102
	v_lshlrev_b32_e32 v32, 16, v113
	v_mul_f32_e32 v16, v16, v32
	v_mul_f32_e32 v32, 0xbfb8aa3b, v32
	v_exp_f32_e32 v32, v32
	v_add_u32_e32 v8, 0xa00, v4
	v_mov_b32_e32 v9, v1
	v_lshl_add_u64 v[8:9], v[8:9], 1, v[2:3]
	v_add_f32_e32 v32, 1.0, v32
	v_rcp_f32_e32 v32, v32
	s_nop 0
	v_mul_f32_e32 v16, v16, v32
	v_cvt_pk_bf16_f32 v16, v16, v16
	global_store_short v[8:9], v16, off
	v_mul_f32_e32 v16, v49, v102
	v_lshlrev_b32_e32 v32, 16, v114
	v_mul_f32_e32 v16, v16, v32
	v_mul_f32_e32 v32, 0xbfb8aa3b, v32
	v_exp_f32_e32 v32, v32
	s_nop 0
	v_add_f32_e32 v32, 1.0, v32
	v_rcp_f32_e32 v32, v32
	s_nop 0
	v_mul_f32_e32 v16, v16, v32
	v_cvt_pk_bf16_f32 v16, v16, v16
	global_store_short v[8:9], v16, off offset:64
	v_mul_f32_e32 v16, v33, v102
	v_lshlrev_b32_e32 v32, 16, v115
	v_mul_f32_e32 v16, v16, v32
	v_mul_f32_e32 v32, 0xbfb8aa3b, v32
	v_exp_f32_e32 v32, v32
	s_nop 0
	v_add_f32_e32 v32, 1.0, v32
	v_rcp_f32_e32 v32, v32
	s_nop 0
	v_mul_f32_e32 v16, v16, v32
	v_cvt_pk_bf16_f32 v16, v16, v16
	global_store_short v[8:9], v16, off offset:128
	v_mul_f32_e32 v16, v17, v102
	v_lshlrev_b32_e32 v17, 16, v116
	v_mul_f32_e32 v16, v16, v17
	v_mul_f32_e32 v17, 0xbfb8aa3b, v17
	v_exp_f32_e32 v17, v17
	s_nop 0
	v_add_f32_e32 v17, 1.0, v17
	v_rcp_f32_e32 v17, v17
	s_nop 0
	v_mul_f32_e32 v16, v16, v17
	v_cvt_pk_bf16_f32 v16, v16, v16
	global_store_short v[8:9], v16, off offset:192
	v_mul_f32_e32 v16, v66, v97
	v_lshlrev_b32_e32 v17, 16, v117
	v_mul_f32_e32 v16, v16, v17
	v_mul_f32_e32 v17, 0xbfb8aa3b, v17
	v_exp_f32_e32 v17, v17
	v_add_u32_e32 v8, 0x1400, v4
	v_mov_b32_e32 v9, v1
	v_lshl_add_u64 v[8:9], v[8:9], 1, v[2:3]
	v_add_f32_e32 v17, 1.0, v17
	v_rcp_f32_e32 v17, v17
	s_nop 0
	v_mul_f32_e32 v16, v16, v17
	v_cvt_pk_bf16_f32 v16, v16, v16
	global_store_short v[8:9], v16, off
	v_mul_f32_e32 v16, v50, v97
	v_lshlrev_b32_e32 v17, 16, v118
	v_mul_f32_e32 v16, v16, v17
	v_mul_f32_e32 v17, 0xbfb8aa3b, v17
	v_exp_f32_e32 v17, v17
	s_nop 0
	v_add_f32_e32 v17, 1.0, v17
	v_rcp_f32_e32 v17, v17
	s_nop 0
	v_mul_f32_e32 v16, v16, v17
	v_cvt_pk_bf16_f32 v16, v16, v16
	global_store_short v[8:9], v16, off offset:64
	v_mul_f32_e32 v16, v34, v97
	v_lshlrev_b32_e32 v17, 16, v108
	v_mul_f32_e32 v16, v16, v17
	v_mul_f32_e32 v17, 0xbfb8aa3b, v17
	v_exp_f32_e32 v17, v17
	s_nop 0
	v_add_f32_e32 v17, 1.0, v17
	v_rcp_f32_e32 v17, v17
	s_nop 0
	v_mul_f32_e32 v16, v16, v17
	v_cvt_pk_bf16_f32 v16, v16, v16
	global_store_short v[8:9], v16, off offset:128
	v_mul_f32_e32 v16, v18, v97
	v_lshlrev_b32_e32 v17, 16, v106
	v_mul_f32_e32 v16, v16, v17
	v_mul_f32_e32 v17, 0xbfb8aa3b, v17
	v_exp_f32_e32 v17, v17
	s_nop 0
	v_add_f32_e32 v17, 1.0, v17
	v_rcp_f32_e32 v17, v17
	s_nop 0
	v_mul_f32_e32 v16, v16, v17
	v_cvt_pk_bf16_f32 v16, v16, v16
	global_store_short v[8:9], v16, off offset:192
	v_mul_f32_e32 v16, v67, v95
	v_lshlrev_b32_e32 v17, 16, v105
	v_mul_f32_e32 v16, v16, v17
	v_mul_f32_e32 v17, 0xbfb8aa3b, v17
	v_exp_f32_e32 v17, v17
	v_add_u32_e32 v8, 0x1e00, v4
	v_mov_b32_e32 v9, v1
	v_lshl_add_u64 v[8:9], v[8:9], 1, v[2:3]
	v_add_f32_e32 v17, 1.0, v17
	v_rcp_f32_e32 v17, v17
	s_nop 0
	v_mul_f32_e32 v16, v16, v17
	v_cvt_pk_bf16_f32 v16, v16, v16
	global_store_short v[8:9], v16, off
	v_mul_f32_e32 v16, v51, v95
	v_lshlrev_b32_e32 v17, 16, v104
	v_mul_f32_e32 v16, v16, v17
	v_mul_f32_e32 v17, 0xbfb8aa3b, v17
	v_exp_f32_e32 v17, v17
	s_nop 0
	v_add_f32_e32 v17, 1.0, v17
	v_rcp_f32_e32 v17, v17
	s_nop 0
	v_mul_f32_e32 v16, v16, v17
	v_cvt_pk_bf16_f32 v16, v16, v16
	global_store_short v[8:9], v16, off offset:64
	v_mul_f32_e32 v16, v35, v95
	v_lshlrev_b32_e32 v17, 16, v103
	v_mul_f32_e32 v16, v16, v17
	v_mul_f32_e32 v17, 0xbfb8aa3b, v17
	v_exp_f32_e32 v17, v17
	s_nop 0
	v_add_f32_e32 v17, 1.0, v17
	v_rcp_f32_e32 v17, v17
	s_nop 0
	v_mul_f32_e32 v16, v16, v17
	v_cvt_pk_bf16_f32 v16, v16, v16
	global_store_short v[8:9], v16, off offset:128
	v_mul_f32_e32 v16, v19, v95
	v_lshlrev_b32_e32 v17, 16, v101
	v_mul_f32_e32 v16, v16, v17
	v_mul_f32_e32 v17, 0xbfb8aa3b, v17
	v_exp_f32_e32 v17, v17
	s_nop 0
	v_add_f32_e32 v17, 1.0, v17
	v_rcp_f32_e32 v17, v17
	s_nop 0
	v_mul_f32_e32 v16, v16, v17
	v_cvt_pk_bf16_f32 v16, v16, v16
	global_store_short v[8:9], v16, off offset:192
	v_mul_f32_e32 v16, v68, v94
	v_lshlrev_b32_e32 v17, 16, v100
	v_mul_f32_e32 v16, v16, v17
	v_mul_f32_e32 v17, 0xbfb8aa3b, v17
	v_exp_f32_e32 v17, v17
	v_add_u32_e32 v8, 0x5000, v4
	v_mov_b32_e32 v9, v1
	v_lshl_add_u64 v[8:9], v[8:9], 1, v[2:3]
	v_add_f32_e32 v17, 1.0, v17
	v_rcp_f32_e32 v17, v17
	s_nop 0
	v_mul_f32_e32 v16, v16, v17
	v_cvt_pk_bf16_f32 v16, v16, v16
	global_store_short v[8:9], v16, off
	v_mul_f32_e32 v16, v52, v94
	v_lshlrev_b32_e32 v17, 16, v99
	v_mul_f32_e32 v16, v16, v17
	v_mul_f32_e32 v17, 0xbfb8aa3b, v17
	v_exp_f32_e32 v17, v17
	s_nop 0
	v_add_f32_e32 v17, 1.0, v17
	v_rcp_f32_e32 v17, v17
	s_nop 0
	v_mul_f32_e32 v16, v16, v17
	v_cvt_pk_bf16_f32 v16, v16, v16
	global_store_short v[8:9], v16, off offset:64
	v_mul_f32_e32 v16, v36, v94
	v_lshlrev_b32_e32 v17, 16, v98
	v_mul_f32_e32 v16, v16, v17
	v_mul_f32_e32 v17, 0xbfb8aa3b, v17
	v_exp_f32_e32 v17, v17
	s_nop 0
	v_add_f32_e32 v17, 1.0, v17
	v_rcp_f32_e32 v17, v17
	s_nop 0
	v_mul_f32_e32 v16, v16, v17
	v_cvt_pk_bf16_f32 v16, v16, v16
	global_store_short v[8:9], v16, off offset:128
	v_mul_f32_e32 v16, v20, v94
	v_lshlrev_b32_e32 v17, 16, v96
	v_mul_f32_e32 v16, v16, v17
	v_mul_f32_e32 v17, 0xbfb8aa3b, v17
	v_exp_f32_e32 v17, v17
	s_nop 0
	v_add_f32_e32 v17, 1.0, v17
	v_rcp_f32_e32 v17, v17
	s_nop 0
	v_mul_f32_e32 v16, v16, v17
	v_cvt_pk_bf16_f32 v16, v16, v16
	global_store_short v[8:9], v16, off offset:192
	v_mul_f32_e32 v16, v69, v93
	v_lshlrev_b32_e32 v17, 16, v89
	v_mul_f32_e32 v16, v16, v17
	v_mul_f32_e32 v17, 0xbfb8aa3b, v17
	v_exp_f32_e32 v17, v17
	v_add_u32_e32 v8, 0x5a00, v4
	v_mov_b32_e32 v9, v1
	v_lshl_add_u64 v[8:9], v[8:9], 1, v[2:3]
	v_add_f32_e32 v17, 1.0, v17
	v_rcp_f32_e32 v17, v17
	s_nop 0
	v_mul_f32_e32 v16, v16, v17
	v_cvt_pk_bf16_f32 v16, v16, v16
	global_store_short v[8:9], v16, off
	v_mul_f32_e32 v16, v53, v93
	v_lshlrev_b32_e32 v17, 16, v88
	v_mul_f32_e32 v16, v16, v17
	v_mul_f32_e32 v17, 0xbfb8aa3b, v17
	v_exp_f32_e32 v17, v17
	s_nop 0
	v_add_f32_e32 v17, 1.0, v17
	v_rcp_f32_e32 v17, v17
	s_nop 0
	v_mul_f32_e32 v16, v16, v17
	v_cvt_pk_bf16_f32 v16, v16, v16
	global_store_short v[8:9], v16, off offset:64
	v_mul_f32_e32 v16, v37, v93
	v_lshlrev_b32_e32 v17, 16, v81
	v_mul_f32_e32 v16, v16, v17
	v_mul_f32_e32 v17, 0xbfb8aa3b, v17
	v_exp_f32_e32 v17, v17
	s_nop 0
	v_add_f32_e32 v17, 1.0, v17
	v_rcp_f32_e32 v17, v17
	s_nop 0
	v_mul_f32_e32 v16, v16, v17
	v_cvt_pk_bf16_f32 v16, v16, v16
	global_store_short v[8:9], v16, off offset:128
	v_mul_f32_e32 v16, v21, v93
	v_lshlrev_b32_e32 v17, 16, v80
	v_mul_f32_e32 v16, v16, v17
	v_mul_f32_e32 v17, 0xbfb8aa3b, v17
	v_exp_f32_e32 v17, v17
	s_nop 0
	v_add_f32_e32 v17, 1.0, v17
	v_rcp_f32_e32 v17, v17
	s_nop 0
	v_mul_f32_e32 v16, v16, v17
	v_cvt_pk_bf16_f32 v16, v16, v16
	global_store_short v[8:9], v16, off offset:192
	v_mul_f32_e32 v16, v70, v92
	v_lshlrev_b32_e32 v17, 16, v64
	v_mul_f32_e32 v16, v16, v17
	v_mul_f32_e32 v17, 0xbfb8aa3b, v17
	v_exp_f32_e32 v17, v17
	v_add_u32_e32 v8, 0x6400, v4
	v_mov_b32_e32 v9, v1
	v_lshl_add_u64 v[8:9], v[8:9], 1, v[2:3]
	v_add_f32_e32 v17, 1.0, v17
	v_rcp_f32_e32 v17, v17
	s_nop 0
	v_mul_f32_e32 v16, v16, v17
	v_cvt_pk_bf16_f32 v16, v16, v16
	global_store_short v[8:9], v16, off
	v_mul_f32_e32 v16, v54, v92
	v_mul_f32_e32 v16, v16, v15
	v_mul_f32_e32 v15, 0xbfb8aa3b, v15
	v_exp_f32_e32 v15, v15
	s_nop 0
	v_add_f32_e32 v15, 1.0, v15
	v_rcp_f32_e32 v15, v15
	s_nop 0
	v_mul_f32_e32 v15, v16, v15
	v_cvt_pk_bf16_f32 v15, v15, v15
	global_store_short v[8:9], v15, off offset:64
	v_mul_f32_e32 v15, v38, v92
	v_mul_f32_e32 v15, v15, v14
	v_mul_f32_e32 v14, 0xbfb8aa3b, v14
	v_exp_f32_e32 v14, v14
	s_nop 0
	v_add_f32_e32 v14, 1.0, v14
	v_rcp_f32_e32 v14, v14
	s_nop 0
	v_mul_f32_e32 v14, v15, v14
	v_cvt_pk_bf16_f32 v14, v14, v14
	global_store_short v[8:9], v14, off offset:128
	v_mul_f32_e32 v14, v22, v92
	v_mul_f32_e32 v14, v14, v13
	v_mul_f32_e32 v13, 0xbfb8aa3b, v13
	v_exp_f32_e32 v13, v13
	s_nop 0
	v_add_f32_e32 v13, 1.0, v13
	v_rcp_f32_e32 v13, v13
	s_nop 0
	v_mul_f32_e32 v13, v14, v13
	v_cvt_pk_bf16_f32 v13, v13, v13
	global_store_short v[8:9], v13, off offset:192
	v_mul_f32_e32 v13, v71, v91
	v_mul_f32_e32 v13, v13, v12
	v_mul_f32_e32 v12, 0xbfb8aa3b, v12
	v_exp_f32_e32 v12, v12
	v_add_u32_e32 v8, 0x6e00, v4
	v_mov_b32_e32 v9, v1
	v_lshl_add_u64 v[8:9], v[8:9], 1, v[2:3]
	v_add_f32_e32 v12, 1.0, v12
	v_rcp_f32_e32 v12, v12
	s_nop 0
	v_mul_f32_e32 v12, v13, v12
	v_cvt_pk_bf16_f32 v12, v12, v12
	global_store_short v[8:9], v12, off
	v_mul_f32_e32 v12, v55, v91
	v_mul_f32_e32 v12, v12, v11
	v_mul_f32_e32 v11, 0xbfb8aa3b, v11
	v_exp_f32_e32 v11, v11
	s_nop 0
	v_add_f32_e32 v11, 1.0, v11
	v_rcp_f32_e32 v11, v11
	s_nop 0
	v_mul_f32_e32 v11, v12, v11
	v_cvt_pk_bf16_f32 v11, v11, v11
	global_store_short v[8:9], v11, off offset:64
	v_mul_f32_e32 v11, v39, v91
	v_mul_f32_e32 v11, v11, v10
	v_mul_f32_e32 v10, 0xbfb8aa3b, v10
	v_exp_f32_e32 v10, v10
	s_nop 0
	v_add_f32_e32 v10, 1.0, v10
	v_rcp_f32_e32 v10, v10
	s_nop 0
	v_mul_f32_e32 v10, v11, v10
	v_cvt_pk_bf16_f32 v10, v10, v10
	global_store_short v[8:9], v10, off offset:128
	v_mul_f32_e32 v10, v23, v91
	v_mul_f32_e32 v10, v10, v5
	v_mul_f32_e32 v5, 0xbfb8aa3b, v5
	v_exp_f32_e32 v5, v5
	s_nop 0
	v_add_f32_e32 v5, 1.0, v5
	v_rcp_f32_e32 v5, v5
	s_nop 0
	v_mul_f32_e32 v5, v10, v5
	v_cvt_pk_bf16_f32 v5, v5, v5
	global_store_short v[8:9], v5, off offset:192
	v_add_u32_e32 v8, 0x11000, v0
	v_mov_b32_e32 v9, v1
	v_lshl_add_u64 v[34:35], v[8:9], 1, v[6:7]
	ds_read_b128 v[12:15], v90 offset:64
	ds_read_b128 v[50:53], v90 offset:96
	global_load_ushort v200, v[34:35], off
	v_add_u32_e32 v8, 0x12100, v0
	v_lshl_add_u64 v[20:21], v[8:9], 1, v[6:7]
	v_add_u32_e32 v8, 0x13200, v0
	v_lshl_add_u64 v[10:11], v[8:9], 1, v[6:7]
	v_add_u32_e32 v8, 0x14300, v0
	s_waitcnt lgkmcnt(1)
	v_rcp_f32_e32 v54, v12
	v_rcp_f32_e32 v49, v13
	v_lshl_add_u64 v[12:13], v[8:9], 1, v[6:7]
	v_add_u32_e32 v8, 0x19800, v0
	v_rcp_f32_e32 v36, v14
	v_rcp_f32_e32 v33, v15
	v_lshl_add_u64 v[14:15], v[8:9], 1, v[6:7]
	v_add_u32_e32 v8, 0x1a900, v0
	v_lshl_add_u64 v[16:17], v[8:9], 1, v[6:7]
	v_add_u32_e32 v8, 0x1ba00, v0
	v_add_u32_e32 v0, 0x1cb00, v0
	v_lshl_add_u64 v[18:19], v[8:9], 1, v[6:7]
	v_lshl_add_u64 v[8:9], v[0:1], 1, v[6:7]
	v_add_u32_e32 v0, 0xa000, v4
	v_lshl_add_u64 v[6:7], v[0:1], 1, v[2:3]
	v_mul_f32_e32 v0, v72, v54
	s_waitcnt lgkmcnt(0)
	v_rcp_f32_e32 v32, v50
	v_rcp_f32_e32 v23, v51
	v_rcp_f32_e32 v22, v52
	v_rcp_f32_e32 v5, v53
	global_load_ushort v64, v[34:35], off offset:64
	global_load_ushort v65, v[34:35], off offset:128
	global_load_ushort v66, v[34:35], off offset:192
	global_load_ushort v67, v[20:21], off
	global_load_ushort v68, v[20:21], off offset:64
	global_load_ushort v69, v[20:21], off offset:128
	global_load_ushort v70, v[20:21], off offset:192
	global_load_ushort v71, v[10:11], off
	global_load_ushort v72, v[10:11], off offset:64
	global_load_ushort v55, v[10:11], off offset:128
	global_load_ushort v53, v[10:11], off offset:192
	global_load_ushort v52, v[12:13], off
	global_load_ushort v51, v[12:13], off offset:64
	global_load_ushort v50, v[12:13], off offset:128
	global_load_ushort v48, v[12:13], off offset:192
	global_load_ushort v39, v[14:15], off
	global_load_ushort v38, v[14:15], off offset:64
	global_load_ushort v37, v[14:15], off offset:128
	global_load_ushort v35, v[14:15], off offset:192
	global_load_ushort v34, v[16:17], off
	global_load_ushort v21, v[16:17], off offset:64
	global_load_ushort v20, v[16:17], off offset:128
	s_nop 0
	global_load_ushort v17, v[16:17], off offset:192
	s_nop 0
	global_load_ushort v16, v[18:19], off
	global_load_ushort v15, v[18:19], off offset:64
	global_load_ushort v14, v[18:19], off offset:128
	global_load_ushort v13, v[18:19], off offset:192
	global_load_ushort v12, v[8:9], off
	global_load_ushort v11, v[8:9], off offset:64
	global_load_ushort v10, v[8:9], off offset:128
	s_nop 0
	global_load_ushort v8, v[8:9], off offset:192
	s_waitcnt vmcnt(31)
	v_lshlrev_b32_e32 v200, 16, v200
	v_mul_f32_e32 v0, v0, v200
	v_mul_f32_e32 v200, 0xbfb8aa3b, v200
	v_exp_f32_e32 v200, v200
	s_nop 0
	v_add_f32_e32 v200, 1.0, v200
	v_rcp_f32_e32 v200, v200
	s_nop 0
	v_mul_f32_e32 v0, v0, v200
	v_cvt_pk_bf16_f32 v0, v0, v0
	global_store_short v[6:7], v0, off
	v_mul_f32_e32 v0, v56, v54
	s_waitcnt vmcnt(31)
	v_lshlrev_b32_e32 v9, 16, v64
	v_mul_f32_e32 v0, v0, v9
	v_mul_f32_e32 v9, 0xbfb8aa3b, v9
	v_exp_f32_e32 v9, v9
	s_nop 0
	v_add_f32_e32 v9, 1.0, v9
	v_rcp_f32_e32 v9, v9
	s_nop 0
	v_mul_f32_e32 v0, v0, v9
	v_cvt_pk_bf16_f32 v0, v0, v0
	global_store_short v[6:7], v0, off offset:64
	v_mul_f32_e32 v0, v40, v54
	s_waitcnt vmcnt(31)
	v_lshlrev_b32_e32 v9, 16, v65
	v_mul_f32_e32 v0, v0, v9
	v_mul_f32_e32 v9, 0xbfb8aa3b, v9
	v_exp_f32_e32 v9, v9
	s_nop 0
	v_add_f32_e32 v9, 1.0, v9
	v_rcp_f32_e32 v9, v9
	s_nop 0
	v_mul_f32_e32 v0, v0, v9
	v_cvt_pk_bf16_f32 v0, v0, v0
	global_store_short v[6:7], v0, off offset:128
	v_mul_f32_e32 v0, v24, v54
	s_waitcnt vmcnt(31)
	v_lshlrev_b32_e32 v9, 16, v66
	v_mul_f32_e32 v0, v0, v9
	v_mul_f32_e32 v9, 0xbfb8aa3b, v9
	v_exp_f32_e32 v9, v9
	s_nop 0
	v_add_f32_e32 v9, 1.0, v9
	v_rcp_f32_e32 v9, v9
	s_nop 0
	v_mul_f32_e32 v0, v0, v9
	v_cvt_pk_bf16_f32 v0, v0, v0
	global_store_short v[6:7], v0, off offset:192
	v_add_u32_e32 v0, 0xaa00, v4
	v_lshl_add_u64 v[6:7], v[0:1], 1, v[2:3]
	v_mul_f32_e32 v0, v73, v49
	s_waitcnt vmcnt(31)
	v_lshlrev_b32_e32 v9, 16, v67
	v_mul_f32_e32 v0, v0, v9
	v_mul_f32_e32 v9, 0xbfb8aa3b, v9
	v_exp_f32_e32 v9, v9
	s_nop 0
	v_add_f32_e32 v9, 1.0, v9
	v_rcp_f32_e32 v9, v9
	s_nop 0
	v_mul_f32_e32 v0, v0, v9
	v_cvt_pk_bf16_f32 v0, v0, v0
	global_store_short v[6:7], v0, off
	v_mul_f32_e32 v0, v57, v49
	s_waitcnt vmcnt(31)
	v_lshlrev_b32_e32 v9, 16, v68
	v_mul_f32_e32 v0, v0, v9
	v_mul_f32_e32 v9, 0xbfb8aa3b, v9
	v_exp_f32_e32 v9, v9
	s_nop 0
	v_add_f32_e32 v9, 1.0, v9
	v_rcp_f32_e32 v9, v9
	s_nop 0
	v_mul_f32_e32 v0, v0, v9
	v_cvt_pk_bf16_f32 v0, v0, v0
	global_store_short v[6:7], v0, off offset:64
	v_mul_f32_e32 v0, v41, v49
	s_waitcnt vmcnt(31)
	v_lshlrev_b32_e32 v9, 16, v69
	v_mul_f32_e32 v0, v0, v9
	v_mul_f32_e32 v9, 0xbfb8aa3b, v9
	v_exp_f32_e32 v9, v9
	s_nop 0
	v_add_f32_e32 v9, 1.0, v9
	v_rcp_f32_e32 v9, v9
	s_nop 0
	v_mul_f32_e32 v0, v0, v9
	v_cvt_pk_bf16_f32 v0, v0, v0
	global_store_short v[6:7], v0, off offset:128
	v_mul_f32_e32 v0, v25, v49
	s_waitcnt vmcnt(31)
	v_lshlrev_b32_e32 v9, 16, v70
	v_mul_f32_e32 v0, v0, v9
	v_mul_f32_e32 v9, 0xbfb8aa3b, v9
	v_exp_f32_e32 v9, v9
	s_nop 0
	v_add_f32_e32 v9, 1.0, v9
	v_rcp_f32_e32 v9, v9
	s_nop 0
	v_mul_f32_e32 v0, v0, v9
	v_cvt_pk_bf16_f32 v0, v0, v0
	global_store_short v[6:7], v0, off offset:192
	v_add_u32_e32 v0, 0xb400, v4
	v_lshl_add_u64 v[6:7], v[0:1], 1, v[2:3]
	v_mul_f32_e32 v0, v74, v36
	s_waitcnt vmcnt(31)
	v_lshlrev_b32_e32 v9, 16, v71
	v_mul_f32_e32 v0, v0, v9
	v_mul_f32_e32 v9, 0xbfb8aa3b, v9
	v_exp_f32_e32 v9, v9
	s_nop 0
	v_add_f32_e32 v9, 1.0, v9
	v_rcp_f32_e32 v9, v9
	s_nop 0
	v_mul_f32_e32 v0, v0, v9
	v_cvt_pk_bf16_f32 v0, v0, v0
	global_store_short v[6:7], v0, off
	v_mul_f32_e32 v0, v58, v36
	s_waitcnt vmcnt(31)
	v_lshlrev_b32_e32 v9, 16, v72
	v_mul_f32_e32 v0, v0, v9
	v_mul_f32_e32 v9, 0xbfb8aa3b, v9
	v_exp_f32_e32 v9, v9
	s_nop 0
	v_add_f32_e32 v9, 1.0, v9
	v_rcp_f32_e32 v9, v9
	s_nop 0
	v_mul_f32_e32 v0, v0, v9
	v_cvt_pk_bf16_f32 v0, v0, v0
	global_store_short v[6:7], v0, off offset:64
	v_mul_f32_e32 v0, v42, v36
	s_waitcnt vmcnt(31)
	v_lshlrev_b32_e32 v9, 16, v55
	v_mul_f32_e32 v0, v0, v9
	v_mul_f32_e32 v9, 0xbfb8aa3b, v9
	v_exp_f32_e32 v9, v9
	s_nop 0
	v_add_f32_e32 v9, 1.0, v9
	v_rcp_f32_e32 v9, v9
	s_nop 0
	v_mul_f32_e32 v0, v0, v9
	v_cvt_pk_bf16_f32 v0, v0, v0
	global_store_short v[6:7], v0, off offset:128
	v_mul_f32_e32 v0, v26, v36
	s_waitcnt vmcnt(31)
	v_lshlrev_b32_e32 v9, 16, v53
	v_mul_f32_e32 v0, v0, v9
	v_mul_f32_e32 v9, 0xbfb8aa3b, v9
	v_exp_f32_e32 v9, v9
	s_nop 0
	v_add_f32_e32 v9, 1.0, v9
	v_rcp_f32_e32 v9, v9
	s_nop 0
	v_mul_f32_e32 v0, v0, v9
	v_cvt_pk_bf16_f32 v0, v0, v0
	global_store_short v[6:7], v0, off offset:192
	v_add_u32_e32 v0, 0xbe00, v4
	v_lshl_add_u64 v[6:7], v[0:1], 1, v[2:3]
	v_mul_f32_e32 v0, v75, v33
	s_waitcnt vmcnt(31)
	v_lshlrev_b32_e32 v9, 16, v52
	v_mul_f32_e32 v0, v0, v9
	v_mul_f32_e32 v9, 0xbfb8aa3b, v9
	v_exp_f32_e32 v9, v9
	s_nop 0
	v_add_f32_e32 v9, 1.0, v9
	v_rcp_f32_e32 v9, v9
	s_nop 0
	v_mul_f32_e32 v0, v0, v9
	v_cvt_pk_bf16_f32 v0, v0, v0
	global_store_short v[6:7], v0, off
	v_mul_f32_e32 v0, v59, v33
	s_waitcnt vmcnt(31)
	v_lshlrev_b32_e32 v9, 16, v51
	v_mul_f32_e32 v0, v0, v9
	v_mul_f32_e32 v9, 0xbfb8aa3b, v9
	v_exp_f32_e32 v9, v9
	s_nop 0
	v_add_f32_e32 v9, 1.0, v9
	v_rcp_f32_e32 v9, v9
	s_nop 0
	v_mul_f32_e32 v0, v0, v9
	v_cvt_pk_bf16_f32 v0, v0, v0
	global_store_short v[6:7], v0, off offset:64
	v_mul_f32_e32 v0, v43, v33
	s_waitcnt vmcnt(31)
	v_lshlrev_b32_e32 v9, 16, v50
	v_mul_f32_e32 v0, v0, v9
	v_mul_f32_e32 v9, 0xbfb8aa3b, v9
	v_exp_f32_e32 v9, v9
	s_nop 0
	v_add_f32_e32 v9, 1.0, v9
	v_rcp_f32_e32 v9, v9
	s_nop 0
	v_mul_f32_e32 v0, v0, v9
	v_cvt_pk_bf16_f32 v0, v0, v0
	global_store_short v[6:7], v0, off offset:128
	v_mul_f32_e32 v0, v27, v33
	s_waitcnt vmcnt(31)
	v_lshlrev_b32_e32 v9, 16, v48
	v_mul_f32_e32 v0, v0, v9
	v_mul_f32_e32 v9, 0xbfb8aa3b, v9
	v_exp_f32_e32 v9, v9
	s_nop 0
	v_add_f32_e32 v9, 1.0, v9
	v_rcp_f32_e32 v9, v9
	s_nop 0
	v_mul_f32_e32 v0, v0, v9
	v_cvt_pk_bf16_f32 v0, v0, v0
	global_store_short v[6:7], v0, off offset:192
	v_add_u32_e32 v0, 0xf000, v4
	v_lshl_add_u64 v[6:7], v[0:1], 1, v[2:3]
	v_mul_f32_e32 v0, v76, v32
	s_waitcnt vmcnt(31)
	v_lshlrev_b32_e32 v9, 16, v39
	v_mul_f32_e32 v0, v0, v9
	v_mul_f32_e32 v9, 0xbfb8aa3b, v9
	v_exp_f32_e32 v9, v9
	s_nop 0
	v_add_f32_e32 v9, 1.0, v9
	v_rcp_f32_e32 v9, v9
	s_nop 0
	v_mul_f32_e32 v0, v0, v9
	v_cvt_pk_bf16_f32 v0, v0, v0
	global_store_short v[6:7], v0, off
	v_mul_f32_e32 v0, v60, v32
	s_waitcnt vmcnt(31)
	v_lshlrev_b32_e32 v9, 16, v38
	v_mul_f32_e32 v0, v0, v9
	v_mul_f32_e32 v9, 0xbfb8aa3b, v9
	v_exp_f32_e32 v9, v9
	s_nop 0
	v_add_f32_e32 v9, 1.0, v9
	v_rcp_f32_e32 v9, v9
	s_nop 0
	v_mul_f32_e32 v0, v0, v9
	v_cvt_pk_bf16_f32 v0, v0, v0
	global_store_short v[6:7], v0, off offset:64
	v_mul_f32_e32 v0, v44, v32
	s_waitcnt vmcnt(31)
	v_lshlrev_b32_e32 v9, 16, v37
	v_mul_f32_e32 v0, v0, v9
	v_mul_f32_e32 v9, 0xbfb8aa3b, v9
	v_exp_f32_e32 v9, v9
	s_nop 0
	v_add_f32_e32 v9, 1.0, v9
	v_rcp_f32_e32 v9, v9
	s_nop 0
	v_mul_f32_e32 v0, v0, v9
	v_cvt_pk_bf16_f32 v0, v0, v0
	global_store_short v[6:7], v0, off offset:128
	v_mul_f32_e32 v0, v28, v32
	s_waitcnt vmcnt(31)
	v_lshlrev_b32_e32 v9, 16, v35
	v_mul_f32_e32 v0, v0, v9
	v_mul_f32_e32 v9, 0xbfb8aa3b, v9
	v_exp_f32_e32 v9, v9
	s_nop 0
	v_add_f32_e32 v9, 1.0, v9
	v_rcp_f32_e32 v9, v9
	s_nop 0
	v_mul_f32_e32 v0, v0, v9
	v_cvt_pk_bf16_f32 v0, v0, v0
	global_store_short v[6:7], v0, off offset:192
	v_add_u32_e32 v0, 0xfa00, v4
	v_lshl_add_u64 v[6:7], v[0:1], 1, v[2:3]
	v_mul_f32_e32 v0, v77, v23
	s_waitcnt vmcnt(31)
	v_lshlrev_b32_e32 v9, 16, v34
	v_mul_f32_e32 v0, v0, v9
	v_mul_f32_e32 v9, 0xbfb8aa3b, v9
	v_exp_f32_e32 v9, v9
	s_nop 0
	v_add_f32_e32 v9, 1.0, v9
	v_rcp_f32_e32 v9, v9
	s_nop 0
	v_mul_f32_e32 v0, v0, v9
	v_cvt_pk_bf16_f32 v0, v0, v0
	global_store_short v[6:7], v0, off
	v_mul_f32_e32 v0, v61, v23
	s_waitcnt vmcnt(31)
	v_lshlrev_b32_e32 v9, 16, v21
	v_mul_f32_e32 v0, v0, v9
	v_mul_f32_e32 v9, 0xbfb8aa3b, v9
	v_exp_f32_e32 v9, v9
	s_nop 0
	v_add_f32_e32 v9, 1.0, v9
	v_rcp_f32_e32 v9, v9
	s_nop 0
	v_mul_f32_e32 v0, v0, v9
	v_cvt_pk_bf16_f32 v0, v0, v0
	global_store_short v[6:7], v0, off offset:64
	v_mul_f32_e32 v0, v45, v23
	s_waitcnt vmcnt(31)
	v_lshlrev_b32_e32 v9, 16, v20
	v_mul_f32_e32 v0, v0, v9
	v_mul_f32_e32 v9, 0xbfb8aa3b, v9
	v_exp_f32_e32 v9, v9
	s_nop 0
	v_add_f32_e32 v9, 1.0, v9
	v_rcp_f32_e32 v9, v9
	s_nop 0
	v_mul_f32_e32 v0, v0, v9
	v_cvt_pk_bf16_f32 v0, v0, v0
	global_store_short v[6:7], v0, off offset:128
	v_mul_f32_e32 v0, v29, v23
	s_waitcnt vmcnt(31)
	v_lshlrev_b32_e32 v9, 16, v17
	v_mul_f32_e32 v0, v0, v9
	v_mul_f32_e32 v9, 0xbfb8aa3b, v9
	v_exp_f32_e32 v9, v9
	s_nop 0
	v_add_f32_e32 v9, 1.0, v9
	v_rcp_f32_e32 v9, v9
	s_nop 0
	v_mul_f32_e32 v0, v0, v9
	v_cvt_pk_bf16_f32 v0, v0, v0
	global_store_short v[6:7], v0, off offset:192
	v_add_u32_e32 v0, 0x10400, v4
	v_lshl_add_u64 v[6:7], v[0:1], 1, v[2:3]
	v_mul_f32_e32 v0, v78, v22
	s_waitcnt vmcnt(31)
	v_lshlrev_b32_e32 v9, 16, v16
	v_mul_f32_e32 v0, v0, v9
	v_mul_f32_e32 v9, 0xbfb8aa3b, v9
	v_exp_f32_e32 v9, v9
	s_nop 0
	v_add_f32_e32 v9, 1.0, v9
	v_rcp_f32_e32 v9, v9
	s_nop 0
	v_mul_f32_e32 v0, v0, v9
	v_cvt_pk_bf16_f32 v0, v0, v0
	global_store_short v[6:7], v0, off
	v_mul_f32_e32 v0, v62, v22
	s_waitcnt vmcnt(31)
	v_lshlrev_b32_e32 v9, 16, v15
	v_mul_f32_e32 v0, v0, v9
	v_mul_f32_e32 v9, 0xbfb8aa3b, v9
	v_exp_f32_e32 v9, v9
	s_nop 0
	v_add_f32_e32 v9, 1.0, v9
	v_rcp_f32_e32 v9, v9
	s_nop 0
	v_mul_f32_e32 v0, v0, v9
	v_cvt_pk_bf16_f32 v0, v0, v0
	global_store_short v[6:7], v0, off offset:64
	v_mul_f32_e32 v0, v46, v22
	s_waitcnt vmcnt(31)
	v_lshlrev_b32_e32 v9, 16, v14
	v_mul_f32_e32 v0, v0, v9
	v_mul_f32_e32 v9, 0xbfb8aa3b, v9
	v_exp_f32_e32 v9, v9
	s_nop 0
	v_add_f32_e32 v9, 1.0, v9
	v_rcp_f32_e32 v9, v9
	s_nop 0
	v_mul_f32_e32 v0, v0, v9
	v_cvt_pk_bf16_f32 v0, v0, v0
	global_store_short v[6:7], v0, off offset:128
	v_mul_f32_e32 v0, v30, v22
	s_waitcnt vmcnt(31)
	v_lshlrev_b32_e32 v9, 16, v13
	v_mul_f32_e32 v0, v0, v9
	v_mul_f32_e32 v9, 0xbfb8aa3b, v9
	v_exp_f32_e32 v9, v9
	s_nop 0
	v_add_f32_e32 v9, 1.0, v9
	v_rcp_f32_e32 v9, v9
	s_nop 0
	v_mul_f32_e32 v0, v0, v9
	v_cvt_pk_bf16_f32 v0, v0, v0
	global_store_short v[6:7], v0, off offset:192
	v_add_u32_e32 v0, 0x10e00, v4
	v_lshl_add_u64 v[2:3], v[0:1], 1, v[2:3]
	v_mul_f32_e32 v0, v79, v5
	s_waitcnt vmcnt(31)
	v_lshlrev_b32_e32 v4, 16, v12
	v_mul_f32_e32 v0, v0, v4
	v_mul_f32_e32 v4, 0xbfb8aa3b, v4
	v_exp_f32_e32 v4, v4
	s_nop 0
	v_add_f32_e32 v4, 1.0, v4
	v_rcp_f32_e32 v4, v4
	s_nop 0
	v_mul_f32_e32 v0, v0, v4
	v_cvt_pk_bf16_f32 v0, v0, v0
	global_store_short v[2:3], v0, off
	v_mul_f32_e32 v0, v63, v5
	s_waitcnt vmcnt(31)
	v_lshlrev_b32_e32 v4, 16, v11
	v_mul_f32_e32 v0, v0, v4
	v_mul_f32_e32 v4, 0xbfb8aa3b, v4
	v_exp_f32_e32 v4, v4
	s_nop 0
	v_add_f32_e32 v4, 1.0, v4
	v_rcp_f32_e32 v4, v4
	s_nop 0
	v_mul_f32_e32 v0, v0, v4
	v_cvt_pk_bf16_f32 v0, v0, v0
	global_store_short v[2:3], v0, off offset:64
	v_mul_f32_e32 v0, v47, v5
	s_waitcnt vmcnt(31)
	v_lshlrev_b32_e32 v4, 16, v10
	v_mul_f32_e32 v0, v0, v4
	v_mul_f32_e32 v4, 0xbfb8aa3b, v4
	v_exp_f32_e32 v4, v4
	s_nop 0
	v_add_f32_e32 v4, 1.0, v4
	v_rcp_f32_e32 v4, v4
	s_nop 0
	v_mul_f32_e32 v0, v0, v4
	v_cvt_pk_bf16_f32 v0, v0, v0
	global_store_short v[2:3], v0, off offset:128
	v_mul_f32_e32 v0, v31, v5
	s_waitcnt vmcnt(31)
	v_lshlrev_b32_e32 v4, 16, v8
	v_mul_f32_e32 v0, v0, v4
	v_mul_f32_e32 v4, 0xbfb8aa3b, v4
	v_exp_f32_e32 v4, v4
	s_nop 0
	v_add_f32_e32 v4, 1.0, v4
	v_rcp_f32_e32 v4, v4
	s_nop 0
	v_mul_f32_e32 v0, v0, v4
	v_cvt_pk_bf16_f32 v0, v0, v0
	global_store_short v[2:3], v0, off offset:192

.LBB0_995:
	s_or_b64 exec, exec, s[0:1]
	v_ashrrev_i32_e32 v2, 1, v2
	v_and_b32_e32 v8, 0xffffffe0, v2
	v_lshlrev_b32_e32 v0, 1, v0
	v_lshl_add_u64 v[6:7], s[10:11], 0, v[0:1]
	v_lshl_add_u64 v[2:3], s[12:13], 0, v[0:1]
	v_lshl_or_b32 v0, v4, 2, v8
	v_add_u32_e32 v8, s2, v0
	s_movk_i32 s25, 0x1100
	s_waitcnt lgkmcnt(0)
	v_mul_lo_u32 v0, v8, s25
	v_lshl_add_u32 v90, v4, 4, v5
	ds_read_b128 v[80:83], v90
	ds_read_b128 v[98:101], v90 offset:32
	v_add_u32_e32 v4, 0x1100, v0
	v_mov_b32_e32 v5, v1
	v_lshl_add_u64 v[10:11], v[4:5], 1, v[6:7]
	v_add_u32_e32 v4, 0x2200, v0
	v_lshl_add_u64 v[12:13], v[4:5], 1, v[6:7]
	v_add_u32_e32 v4, 0x3300, v0
	v_lshl_add_u64 v[14:15], v[4:5], 1, v[6:7]
	v_add_u32_e32 v4, 0x8800, v0
	s_waitcnt lgkmcnt(1)
	v_rcp_f32_e32 v107, v80
	v_rcp_f32_e32 v102, v81
	v_lshl_add_u64 v[80:81], v[4:5], 1, v[6:7]
	v_add_u32_e32 v4, 0x9900, v0
	v_rcp_f32_e32 v97, v82
	v_rcp_f32_e32 v95, v83
	v_lshl_add_u64 v[82:83], v[4:5], 1, v[6:7]
	v_add_u32_e32 v4, 0xaa00, v0
	v_lshl_add_u64 v[84:85], v[4:5], 1, v[6:7]
	v_add_u32_e32 v4, 0xbb00, v0
	s_movk_i32 s0, 0xa00
	v_lshl_add_u64 v[88:89], v[0:1], 1, v[6:7]
	v_lshl_add_u64 v[86:87], v[4:5], 1, v[6:7]
	v_mul_lo_u32 v4, v8, s0
	v_lshl_add_u64 v[8:9], v[4:5], 1, v[2:3]
	v_mul_f32_e32 v5, v64, v107
	global_load_ushort v201, v[88:89], off
	s_waitcnt lgkmcnt(0)
	v_rcp_f32_e32 v94, v98
	v_rcp_f32_e32 v93, v99
	v_rcp_f32_e32 v92, v100
	v_rcp_f32_e32 v91, v101
	v_mul_f32_e32 v48, v48, v107
	v_mul_f32_e32 v32, v32, v107
	v_mul_f32_e32 v16, v16, v107
	s_mov_b64 s[0:1], 0
	s_and_b64 vcc, exec, s[16:17]
	v_mov_b32_e32 v200, v5
	global_load_ushort v110, v[88:89], off offset:64
	global_load_ushort v111, v[88:89], off offset:128
	global_load_ushort v112, v[88:89], off offset:192
	global_load_ushort v113, v[10:11], off
	global_load_ushort v114, v[10:11], off offset:64
	global_load_ushort v115, v[10:11], off offset:128
	global_load_ushort v116, v[10:11], off offset:192
	global_load_ushort v117, v[12:13], off
	global_load_ushort v118, v[12:13], off offset:64
	global_load_ushort v108, v[12:13], off offset:128
	global_load_ushort v106, v[12:13], off offset:192
	global_load_ushort v105, v[14:15], off
	global_load_ushort v104, v[14:15], off offset:64
	global_load_ushort v103, v[14:15], off offset:128
	global_load_ushort v101, v[14:15], off offset:192
	global_load_ushort v100, v[80:81], off
	global_load_ushort v99, v[80:81], off offset:64
	global_load_ushort v98, v[80:81], off offset:128
	global_load_ushort v96, v[80:81], off offset:192
	global_load_ushort v89, v[82:83], off
	global_load_ushort v88, v[82:83], off offset:64
	s_nop 0
	global_load_ushort v81, v[82:83], off offset:128
	global_load_ushort v80, v[82:83], off offset:192
	global_load_ushort v64, v[84:85], off
	global_load_ushort v15, v[84:85], off offset:64
	global_load_ushort v14, v[84:85], off offset:128
	global_load_ushort v13, v[84:85], off offset:192
	global_load_ushort v12, v[86:87], off
	global_load_ushort v11, v[86:87], off offset:64
	global_load_ushort v10, v[86:87], off offset:128
	global_load_ushort v5, v[86:87], off offset:192
	s_waitcnt vmcnt(31)
	v_lshlrev_b32_e32 v201, 16, v201
	v_mul_f32_e32 v200, v200, v201
	v_mul_f32_e32 v201, 0xbfb8aa3b, v201
	v_exp_f32_e32 v201, v201
	s_nop 0
	v_add_f32_e32 v201, 1.0, v201
	v_rcp_f32_e32 v201, v201
	s_nop 0
	v_mul_f32_e32 v109, v200, v201
	v_cvt_pk_bf16_f32 v82, v109, v109
	global_store_short v[8:9], v82, off
	s_waitcnt vmcnt(31)
	v_lshlrev_b32_e32 v82, 16, v110
	v_mul_f32_e32 v48, v48, v82
	v_mul_f32_e32 v82, 0xbfb8aa3b, v82
	v_exp_f32_e32 v82, v82
	s_waitcnt vmcnt(7)
	v_lshlrev_b32_e32 v15, 16, v15
	v_add_f32_e32 v82, 1.0, v82
	v_rcp_f32_e32 v82, v82
	s_waitcnt vmcnt(6)
	v_lshlrev_b32_e32 v14, 16, v14
	s_waitcnt vmcnt(5)
	v_lshlrev_b32_e32 v13, 16, v13
	s_waitcnt vmcnt(4)
	v_lshlrev_b32_e32 v12, 16, v12
	v_mul_f32_e32 v48, v48, v82
	v_cvt_pk_bf16_f32 v48, v48, v48
	global_store_short v[8:9], v48, off offset:64
	v_lshlrev_b32_e32 v48, 16, v111
	v_mul_f32_e32 v32, v32, v48
	v_mul_f32_e32 v48, 0xbfb8aa3b, v48
	v_exp_f32_e32 v48, v48
	s_waitcnt vmcnt(4)
	v_lshlrev_b32_e32 v11, 16, v11
	s_waitcnt vmcnt(3)
	v_lshlrev_b32_e32 v10, 16, v10
	s_waitcnt vmcnt(2)
	v_lshlrev_b32_e32 v5, 16, v5
	v_add_f32_e32 v48, 1.0, v48
	v_rcp_f32_e32 v48, v48
	s_nop 0
	v_mul_f32_e32 v32, v32, v48
	v_cvt_pk_bf16_f32 v32, v32, v32
	global_store_short v[8:9], v32, off offset:128
	v_lshlrev_b32_e32 v32, 16, v112
	v_mul_f32_e32 v16, v16, v32
	v_mul_f32_e32 v32, 0xbfb8aa3b, v32
	v_exp_f32_e32 v32, v32
	s_nop 0
	v_add_f32_e32 v32, 1.0, v32
	v_rcp_f32_e32 v32, v32
	s_nop 0
	v_mul_f32_e32 v16, v16, v32
	v_cvt_pk_bf16_f32 v16, v16, v16
	global_store_short v[8:9], v16, off offset:192
	v_mul_f32_e32 v16, v65, v102
	v_lshlrev_b32_e32 v32, 16, v113
	v_mul_f32_e32 v16, v16, v32
	v_mul_f32_e32 v32, 0xbfb8aa3b, v32
	v_exp_f32_e32 v32, v32
	v_add_u32_e32 v8, 0xa00, v4
	v_mov_b32_e32 v9, v1
	v_lshl_add_u64 v[8:9], v[8:9], 1, v[2:3]
	v_add_f32_e32 v32, 1.0, v32
	v_rcp_f32_e32 v32, v32
	s_nop 0
	v_mul_f32_e32 v16, v16, v32
	v_cvt_pk_bf16_f32 v16, v16, v16
	global_store_short v[8:9], v16, off
	v_mul_f32_e32 v16, v49, v102
	v_lshlrev_b32_e32 v32, 16, v114
	v_mul_f32_e32 v16, v16, v32
	v_mul_f32_e32 v32, 0xbfb8aa3b, v32
	v_exp_f32_e32 v32, v32
	s_nop 0
	v_add_f32_e32 v32, 1.0, v32
	v_rcp_f32_e32 v32, v32
	s_nop 0
	v_mul_f32_e32 v16, v16, v32
	v_cvt_pk_bf16_f32 v16, v16, v16
	global_store_short v[8:9], v16, off offset:64
	v_mul_f32_e32 v16, v33, v102
	v_lshlrev_b32_e32 v32, 16, v115
	v_mul_f32_e32 v16, v16, v32
	v_mul_f32_e32 v32, 0xbfb8aa3b, v32
	v_exp_f32_e32 v32, v32
	s_nop 0
	v_add_f32_e32 v32, 1.0, v32
	v_rcp_f32_e32 v32, v32
	s_nop 0
	v_mul_f32_e32 v16, v16, v32
	v_cvt_pk_bf16_f32 v16, v16, v16
	global_store_short v[8:9], v16, off offset:128
	v_mul_f32_e32 v16, v17, v102
	v_lshlrev_b32_e32 v17, 16, v116
	v_mul_f32_e32 v16, v16, v17
	v_mul_f32_e32 v17, 0xbfb8aa3b, v17
	v_exp_f32_e32 v17, v17
	s_nop 0
	v_add_f32_e32 v17, 1.0, v17
	v_rcp_f32_e32 v17, v17
	s_nop 0
	v_mul_f32_e32 v16, v16, v17
	v_cvt_pk_bf16_f32 v16, v16, v16
	global_store_short v[8:9], v16, off offset:192
	v_mul_f32_e32 v16, v66, v97
	v_lshlrev_b32_e32 v17, 16, v117
	v_mul_f32_e32 v16, v16, v17
	v_mul_f32_e32 v17, 0xbfb8aa3b, v17
	v_exp_f32_e32 v17, v17
	v_add_u32_e32 v8, 0x1400, v4
	v_mov_b32_e32 v9, v1
	v_lshl_add_u64 v[8:9], v[8:9], 1, v[2:3]
	v_add_f32_e32 v17, 1.0, v17
	v_rcp_f32_e32 v17, v17
	s_nop 0
	v_mul_f32_e32 v16, v16, v17
	v_cvt_pk_bf16_f32 v16, v16, v16
	global_store_short v[8:9], v16, off
	v_mul_f32_e32 v16, v50, v97
	v_lshlrev_b32_e32 v17, 16, v118
	v_mul_f32_e32 v16, v16, v17
	v_mul_f32_e32 v17, 0xbfb8aa3b, v17
	v_exp_f32_e32 v17, v17
	s_nop 0
	v_add_f32_e32 v17, 1.0, v17
	v_rcp_f32_e32 v17, v17
	s_nop 0
	v_mul_f32_e32 v16, v16, v17
	v_cvt_pk_bf16_f32 v16, v16, v16
	global_store_short v[8:9], v16, off offset:64
	v_mul_f32_e32 v16, v34, v97
	v_lshlrev_b32_e32 v17, 16, v108
	v_mul_f32_e32 v16, v16, v17
	v_mul_f32_e32 v17, 0xbfb8aa3b, v17
	v_exp_f32_e32 v17, v17
	s_nop 0
	v_add_f32_e32 v17, 1.0, v17
	v_rcp_f32_e32 v17, v17
	s_nop 0
	v_mul_f32_e32 v16, v16, v17
	v_cvt_pk_bf16_f32 v16, v16, v16
	global_store_short v[8:9], v16, off offset:128
	v_mul_f32_e32 v16, v18, v97
	v_lshlrev_b32_e32 v17, 16, v106
	v_mul_f32_e32 v16, v16, v17
	v_mul_f32_e32 v17, 0xbfb8aa3b, v17
	v_exp_f32_e32 v17, v17
	s_nop 0
	v_add_f32_e32 v17, 1.0, v17
	v_rcp_f32_e32 v17, v17
	s_nop 0
	v_mul_f32_e32 v16, v16, v17
	v_cvt_pk_bf16_f32 v16, v16, v16
	global_store_short v[8:9], v16, off offset:192
	v_mul_f32_e32 v16, v67, v95
	v_lshlrev_b32_e32 v17, 16, v105
	v_mul_f32_e32 v16, v16, v17
	v_mul_f32_e32 v17, 0xbfb8aa3b, v17
	v_exp_f32_e32 v17, v17
	v_add_u32_e32 v8, 0x1e00, v4
	v_mov_b32_e32 v9, v1
	v_lshl_add_u64 v[8:9], v[8:9], 1, v[2:3]
	v_add_f32_e32 v17, 1.0, v17
	v_rcp_f32_e32 v17, v17
	s_nop 0
	v_mul_f32_e32 v16, v16, v17
	v_cvt_pk_bf16_f32 v16, v16, v16
	global_store_short v[8:9], v16, off
	v_mul_f32_e32 v16, v51, v95
	v_lshlrev_b32_e32 v17, 16, v104
	v_mul_f32_e32 v16, v16, v17
	v_mul_f32_e32 v17, 0xbfb8aa3b, v17
	v_exp_f32_e32 v17, v17
	s_nop 0
	v_add_f32_e32 v17, 1.0, v17
	v_rcp_f32_e32 v17, v17
	s_nop 0
	v_mul_f32_e32 v16, v16, v17
	v_cvt_pk_bf16_f32 v16, v16, v16
	global_store_short v[8:9], v16, off offset:64
	v_mul_f32_e32 v16, v35, v95
	v_lshlrev_b32_e32 v17, 16, v103
	v_mul_f32_e32 v16, v16, v17
	v_mul_f32_e32 v17, 0xbfb8aa3b, v17
	v_exp_f32_e32 v17, v17
	s_nop 0
	v_add_f32_e32 v17, 1.0, v17
	v_rcp_f32_e32 v17, v17
	s_nop 0
	v_mul_f32_e32 v16, v16, v17
	v_cvt_pk_bf16_f32 v16, v16, v16
	global_store_short v[8:9], v16, off offset:128
	v_mul_f32_e32 v16, v19, v95
	v_lshlrev_b32_e32 v17, 16, v101
	v_mul_f32_e32 v16, v16, v17
	v_mul_f32_e32 v17, 0xbfb8aa3b, v17
	v_exp_f32_e32 v17, v17
	s_nop 0
	v_add_f32_e32 v17, 1.0, v17
	v_rcp_f32_e32 v17, v17
	s_nop 0
	v_mul_f32_e32 v16, v16, v17
	v_cvt_pk_bf16_f32 v16, v16, v16
	global_store_short v[8:9], v16, off offset:192
	v_mul_f32_e32 v16, v68, v94
	v_lshlrev_b32_e32 v17, 16, v100
	v_mul_f32_e32 v16, v16, v17
	v_mul_f32_e32 v17, 0xbfb8aa3b, v17
	v_exp_f32_e32 v17, v17
	v_add_u32_e32 v8, 0x5000, v4
	v_mov_b32_e32 v9, v1
	v_lshl_add_u64 v[8:9], v[8:9], 1, v[2:3]
	v_add_f32_e32 v17, 1.0, v17
	v_rcp_f32_e32 v17, v17
	s_nop 0
	v_mul_f32_e32 v16, v16, v17
	v_cvt_pk_bf16_f32 v16, v16, v16
	global_store_short v[8:9], v16, off
	v_mul_f32_e32 v16, v52, v94
	v_lshlrev_b32_e32 v17, 16, v99
	v_mul_f32_e32 v16, v16, v17
	v_mul_f32_e32 v17, 0xbfb8aa3b, v17
	v_exp_f32_e32 v17, v17
	s_nop 0
	v_add_f32_e32 v17, 1.0, v17
	v_rcp_f32_e32 v17, v17
	s_nop 0
	v_mul_f32_e32 v16, v16, v17
	v_cvt_pk_bf16_f32 v16, v16, v16
	global_store_short v[8:9], v16, off offset:64
	v_mul_f32_e32 v16, v36, v94
	v_lshlrev_b32_e32 v17, 16, v98
	v_mul_f32_e32 v16, v16, v17
	v_mul_f32_e32 v17, 0xbfb8aa3b, v17
	v_exp_f32_e32 v17, v17
	s_nop 0
	v_add_f32_e32 v17, 1.0, v17
	v_rcp_f32_e32 v17, v17
	s_nop 0
	v_mul_f32_e32 v16, v16, v17
	v_cvt_pk_bf16_f32 v16, v16, v16
	global_store_short v[8:9], v16, off offset:128
	v_mul_f32_e32 v16, v20, v94
	v_lshlrev_b32_e32 v17, 16, v96
	v_mul_f32_e32 v16, v16, v17
	v_mul_f32_e32 v17, 0xbfb8aa3b, v17
	v_exp_f32_e32 v17, v17
	s_nop 0
	v_add_f32_e32 v17, 1.0, v17
	v_rcp_f32_e32 v17, v17
	s_nop 0
	v_mul_f32_e32 v16, v16, v17
	v_cvt_pk_bf16_f32 v16, v16, v16
	global_store_short v[8:9], v16, off offset:192
	v_mul_f32_e32 v16, v69, v93
	v_lshlrev_b32_e32 v17, 16, v89
	v_mul_f32_e32 v16, v16, v17
	v_mul_f32_e32 v17, 0xbfb8aa3b, v17
	v_exp_f32_e32 v17, v17
	v_add_u32_e32 v8, 0x5a00, v4
	v_mov_b32_e32 v9, v1
	v_lshl_add_u64 v[8:9], v[8:9], 1, v[2:3]
	v_add_f32_e32 v17, 1.0, v17
	v_rcp_f32_e32 v17, v17
	s_nop 0
	v_mul_f32_e32 v16, v16, v17
	v_cvt_pk_bf16_f32 v16, v16, v16
	global_store_short v[8:9], v16, off
	v_mul_f32_e32 v16, v53, v93
	v_lshlrev_b32_e32 v17, 16, v88
	v_mul_f32_e32 v16, v16, v17
	v_mul_f32_e32 v17, 0xbfb8aa3b, v17
	v_exp_f32_e32 v17, v17
	s_nop 0
	v_add_f32_e32 v17, 1.0, v17
	v_rcp_f32_e32 v17, v17
	s_nop 0
	v_mul_f32_e32 v16, v16, v17
	v_cvt_pk_bf16_f32 v16, v16, v16
	global_store_short v[8:9], v16, off offset:64
	v_mul_f32_e32 v16, v37, v93
	v_lshlrev_b32_e32 v17, 16, v81
	v_mul_f32_e32 v16, v16, v17
	v_mul_f32_e32 v17, 0xbfb8aa3b, v17
	v_exp_f32_e32 v17, v17
	s_nop 0
	v_add_f32_e32 v17, 1.0, v17
	v_rcp_f32_e32 v17, v17
	s_nop 0
	v_mul_f32_e32 v16, v16, v17
	v_cvt_pk_bf16_f32 v16, v16, v16
	global_store_short v[8:9], v16, off offset:128
	v_mul_f32_e32 v16, v21, v93
	v_lshlrev_b32_e32 v17, 16, v80
	v_mul_f32_e32 v16, v16, v17
	v_mul_f32_e32 v17, 0xbfb8aa3b, v17
	v_exp_f32_e32 v17, v17
	s_nop 0
	v_add_f32_e32 v17, 1.0, v17
	v_rcp_f32_e32 v17, v17
	s_nop 0
	v_mul_f32_e32 v16, v16, v17
	v_cvt_pk_bf16_f32 v16, v16, v16
	global_store_short v[8:9], v16, off offset:192
	v_mul_f32_e32 v16, v70, v92
	v_lshlrev_b32_e32 v17, 16, v64
	v_mul_f32_e32 v16, v16, v17
	v_mul_f32_e32 v17, 0xbfb8aa3b, v17
	v_exp_f32_e32 v17, v17
	v_add_u32_e32 v8, 0x6400, v4
	v_mov_b32_e32 v9, v1
	v_lshl_add_u64 v[8:9], v[8:9], 1, v[2:3]
	v_add_f32_e32 v17, 1.0, v17
	v_rcp_f32_e32 v17, v17
	s_nop 0
	v_mul_f32_e32 v16, v16, v17
	v_cvt_pk_bf16_f32 v16, v16, v16
	global_store_short v[8:9], v16, off
	v_mul_f32_e32 v16, v54, v92
	v_mul_f32_e32 v16, v16, v15
	v_mul_f32_e32 v15, 0xbfb8aa3b, v15
	v_exp_f32_e32 v15, v15
	s_nop 0
	v_add_f32_e32 v15, 1.0, v15
	v_rcp_f32_e32 v15, v15
	s_nop 0
	v_mul_f32_e32 v15, v16, v15
	v_cvt_pk_bf16_f32 v15, v15, v15
	global_store_short v[8:9], v15, off offset:64
	v_mul_f32_e32 v15, v38, v92
	v_mul_f32_e32 v15, v15, v14
	v_mul_f32_e32 v14, 0xbfb8aa3b, v14
	v_exp_f32_e32 v14, v14
	s_nop 0
	v_add_f32_e32 v14, 1.0, v14
	v_rcp_f32_e32 v14, v14
	s_nop 0
	v_mul_f32_e32 v14, v15, v14
	v_cvt_pk_bf16_f32 v14, v14, v14
	global_store_short v[8:9], v14, off offset:128
	v_mul_f32_e32 v14, v22, v92
	v_mul_f32_e32 v14, v14, v13
	v_mul_f32_e32 v13, 0xbfb8aa3b, v13
	v_exp_f32_e32 v13, v13
	s_nop 0
	v_add_f32_e32 v13, 1.0, v13
	v_rcp_f32_e32 v13, v13
	s_nop 0
	v_mul_f32_e32 v13, v14, v13
	v_cvt_pk_bf16_f32 v13, v13, v13
	global_store_short v[8:9], v13, off offset:192
	v_mul_f32_e32 v13, v71, v91
	v_mul_f32_e32 v13, v13, v12
	v_mul_f32_e32 v12, 0xbfb8aa3b, v12
	v_exp_f32_e32 v12, v12
	v_add_u32_e32 v8, 0x6e00, v4
	v_mov_b32_e32 v9, v1
	v_lshl_add_u64 v[8:9], v[8:9], 1, v[2:3]
	v_add_f32_e32 v12, 1.0, v12
	v_rcp_f32_e32 v12, v12
	s_nop 0
	v_mul_f32_e32 v12, v13, v12
	v_cvt_pk_bf16_f32 v12, v12, v12
	global_store_short v[8:9], v12, off
	v_mul_f32_e32 v12, v55, v91
	v_mul_f32_e32 v12, v12, v11
	v_mul_f32_e32 v11, 0xbfb8aa3b, v11
	v_exp_f32_e32 v11, v11
	s_nop 0
	v_add_f32_e32 v11, 1.0, v11
	v_rcp_f32_e32 v11, v11
	s_nop 0
	v_mul_f32_e32 v11, v12, v11
	v_cvt_pk_bf16_f32 v11, v11, v11
	global_store_short v[8:9], v11, off offset:64
	v_mul_f32_e32 v11, v39, v91
	v_mul_f32_e32 v11, v11, v10
	v_mul_f32_e32 v10, 0xbfb8aa3b, v10
	v_exp_f32_e32 v10, v10
	s_nop 0
	v_add_f32_e32 v10, 1.0, v10
	v_rcp_f32_e32 v10, v10
	s_nop 0
	v_mul_f32_e32 v10, v11, v10
	v_cvt_pk_bf16_f32 v10, v10, v10
	global_store_short v[8:9], v10, off offset:128
	v_mul_f32_e32 v10, v23, v91
	v_mul_f32_e32 v10, v10, v5
	v_mul_f32_e32 v5, 0xbfb8aa3b, v5
	v_exp_f32_e32 v5, v5
	s_nop 0
	v_add_f32_e32 v5, 1.0, v5
	v_rcp_f32_e32 v5, v5
	s_nop 0
	v_mul_f32_e32 v5, v10, v5
	v_cvt_pk_bf16_f32 v5, v5, v5
	global_store_short v[8:9], v5, off offset:192
	v_add_u32_e32 v8, 0x11000, v0
	v_mov_b32_e32 v9, v1
	v_lshl_add_u64 v[34:35], v[8:9], 1, v[6:7]
	ds_read_b128 v[12:15], v90 offset:64
	ds_read_b128 v[50:53], v90 offset:96
	global_load_ushort v200, v[34:35], off
	v_add_u32_e32 v8, 0x12100, v0
	v_lshl_add_u64 v[20:21], v[8:9], 1, v[6:7]
	v_add_u32_e32 v8, 0x13200, v0
	v_lshl_add_u64 v[10:11], v[8:9], 1, v[6:7]
	v_add_u32_e32 v8, 0x14300, v0
	s_waitcnt lgkmcnt(1)
	v_rcp_f32_e32 v54, v12
	v_rcp_f32_e32 v49, v13
	v_lshl_add_u64 v[12:13], v[8:9], 1, v[6:7]
	v_add_u32_e32 v8, 0x19800, v0
	v_rcp_f32_e32 v36, v14
	v_rcp_f32_e32 v33, v15
	v_lshl_add_u64 v[14:15], v[8:9], 1, v[6:7]
	v_add_u32_e32 v8, 0x1a900, v0
	v_lshl_add_u64 v[16:17], v[8:9], 1, v[6:7]
	v_add_u32_e32 v8, 0x1ba00, v0
	v_add_u32_e32 v0, 0x1cb00, v0
	v_lshl_add_u64 v[18:19], v[8:9], 1, v[6:7]
	v_lshl_add_u64 v[8:9], v[0:1], 1, v[6:7]
	v_add_u32_e32 v0, 0xa000, v4
	v_lshl_add_u64 v[6:7], v[0:1], 1, v[2:3]
	v_mul_f32_e32 v0, v72, v54
	s_waitcnt lgkmcnt(0)
	v_rcp_f32_e32 v32, v50
	v_rcp_f32_e32 v23, v51
	v_rcp_f32_e32 v22, v52
	v_rcp_f32_e32 v5, v53
	global_load_ushort v64, v[34:35], off offset:64
	global_load_ushort v65, v[34:35], off offset:128
	global_load_ushort v66, v[34:35], off offset:192
	global_load_ushort v67, v[20:21], off
	global_load_ushort v68, v[20:21], off offset:64
	global_load_ushort v69, v[20:21], off offset:128
	global_load_ushort v70, v[20:21], off offset:192
	global_load_ushort v71, v[10:11], off
	global_load_ushort v72, v[10:11], off offset:64
	global_load_ushort v55, v[10:11], off offset:128
	global_load_ushort v53, v[10:11], off offset:192
	global_load_ushort v52, v[12:13], off
	global_load_ushort v51, v[12:13], off offset:64
	global_load_ushort v50, v[12:13], off offset:128
	global_load_ushort v48, v[12:13], off offset:192
	global_load_ushort v39, v[14:15], off
	global_load_ushort v38, v[14:15], off offset:64
	global_load_ushort v37, v[14:15], off offset:128
	global_load_ushort v35, v[14:15], off offset:192
	global_load_ushort v34, v[16:17], off
	global_load_ushort v21, v[16:17], off offset:64
	global_load_ushort v20, v[16:17], off offset:128
	s_nop 0
	global_load_ushort v17, v[16:17], off offset:192
	s_nop 0
	global_load_ushort v16, v[18:19], off
	global_load_ushort v15, v[18:19], off offset:64
	global_load_ushort v14, v[18:19], off offset:128
	global_load_ushort v13, v[18:19], off offset:192
	global_load_ushort v12, v[8:9], off
	global_load_ushort v11, v[8:9], off offset:64
	global_load_ushort v10, v[8:9], off offset:128
	s_nop 0
	global_load_ushort v8, v[8:9], off offset:192
	s_waitcnt vmcnt(31)
	v_lshlrev_b32_e32 v200, 16, v200
	v_mul_f32_e32 v0, v0, v200
	v_mul_f32_e32 v200, 0xbfb8aa3b, v200
	v_exp_f32_e32 v200, v200
	s_nop 0
	v_add_f32_e32 v200, 1.0, v200
	v_rcp_f32_e32 v200, v200
	s_nop 0
	v_mul_f32_e32 v0, v0, v200
	v_cvt_pk_bf16_f32 v0, v0, v0
	global_store_short v[6:7], v0, off
	v_mul_f32_e32 v0, v56, v54
	s_waitcnt vmcnt(31)
	v_lshlrev_b32_e32 v9, 16, v64
	v_mul_f32_e32 v0, v0, v9
	v_mul_f32_e32 v9, 0xbfb8aa3b, v9
	v_exp_f32_e32 v9, v9
	s_nop 0
	v_add_f32_e32 v9, 1.0, v9
	v_rcp_f32_e32 v9, v9
	s_nop 0
	v_mul_f32_e32 v0, v0, v9
	v_cvt_pk_bf16_f32 v0, v0, v0
	global_store_short v[6:7], v0, off offset:64
	v_mul_f32_e32 v0, v40, v54
	s_waitcnt vmcnt(31)
	v_lshlrev_b32_e32 v9, 16, v65
	v_mul_f32_e32 v0, v0, v9
	v_mul_f32_e32 v9, 0xbfb8aa3b, v9
	v_exp_f32_e32 v9, v9
	s_nop 0
	v_add_f32_e32 v9, 1.0, v9
	v_rcp_f32_e32 v9, v9
	s_nop 0
	v_mul_f32_e32 v0, v0, v9
	v_cvt_pk_bf16_f32 v0, v0, v0
	global_store_short v[6:7], v0, off offset:128
	v_mul_f32_e32 v0, v24, v54
	s_waitcnt vmcnt(31)
	v_lshlrev_b32_e32 v9, 16, v66
	v_mul_f32_e32 v0, v0, v9
	v_mul_f32_e32 v9, 0xbfb8aa3b, v9
	v_exp_f32_e32 v9, v9
	s_nop 0
	v_add_f32_e32 v9, 1.0, v9
	v_rcp_f32_e32 v9, v9
	s_nop 0
	v_mul_f32_e32 v0, v0, v9
	v_cvt_pk_bf16_f32 v0, v0, v0
	global_store_short v[6:7], v0, off offset:192
	v_add_u32_e32 v0, 0xaa00, v4
	v_lshl_add_u64 v[6:7], v[0:1], 1, v[2:3]
	v_mul_f32_e32 v0, v73, v49
	s_waitcnt vmcnt(31)
	v_lshlrev_b32_e32 v9, 16, v67
	v_mul_f32_e32 v0, v0, v9
	v_mul_f32_e32 v9, 0xbfb8aa3b, v9
	v_exp_f32_e32 v9, v9
	s_nop 0
	v_add_f32_e32 v9, 1.0, v9
	v_rcp_f32_e32 v9, v9
	s_nop 0
	v_mul_f32_e32 v0, v0, v9
	v_cvt_pk_bf16_f32 v0, v0, v0
	global_store_short v[6:7], v0, off
	v_mul_f32_e32 v0, v57, v49
	s_waitcnt vmcnt(31)
	v_lshlrev_b32_e32 v9, 16, v68
	v_mul_f32_e32 v0, v0, v9
	v_mul_f32_e32 v9, 0xbfb8aa3b, v9
	v_exp_f32_e32 v9, v9
	s_nop 0
	v_add_f32_e32 v9, 1.0, v9
	v_rcp_f32_e32 v9, v9
	s_nop 0
	v_mul_f32_e32 v0, v0, v9
	v_cvt_pk_bf16_f32 v0, v0, v0
	global_store_short v[6:7], v0, off offset:64
	v_mul_f32_e32 v0, v41, v49
	s_waitcnt vmcnt(31)
	v_lshlrev_b32_e32 v9, 16, v69
	v_mul_f32_e32 v0, v0, v9
	v_mul_f32_e32 v9, 0xbfb8aa3b, v9
	v_exp_f32_e32 v9, v9
	s_nop 0
	v_add_f32_e32 v9, 1.0, v9
	v_rcp_f32_e32 v9, v9
	s_nop 0
	v_mul_f32_e32 v0, v0, v9
	v_cvt_pk_bf16_f32 v0, v0, v0
	global_store_short v[6:7], v0, off offset:128
	v_mul_f32_e32 v0, v25, v49
	s_waitcnt vmcnt(31)
	v_lshlrev_b32_e32 v9, 16, v70
	v_mul_f32_e32 v0, v0, v9
	v_mul_f32_e32 v9, 0xbfb8aa3b, v9
	v_exp_f32_e32 v9, v9
	s_nop 0
	v_add_f32_e32 v9, 1.0, v9
	v_rcp_f32_e32 v9, v9
	s_nop 0
	v_mul_f32_e32 v0, v0, v9
	v_cvt_pk_bf16_f32 v0, v0, v0
	global_store_short v[6:7], v0, off offset:192
	v_add_u32_e32 v0, 0xb400, v4
	v_lshl_add_u64 v[6:7], v[0:1], 1, v[2:3]
	v_mul_f32_e32 v0, v74, v36
	s_waitcnt vmcnt(31)
	v_lshlrev_b32_e32 v9, 16, v71
	v_mul_f32_e32 v0, v0, v9
	v_mul_f32_e32 v9, 0xbfb8aa3b, v9
	v_exp_f32_e32 v9, v9
	s_nop 0
	v_add_f32_e32 v9, 1.0, v9
	v_rcp_f32_e32 v9, v9
	s_nop 0
	v_mul_f32_e32 v0, v0, v9
	v_cvt_pk_bf16_f32 v0, v0, v0
	global_store_short v[6:7], v0, off
	v_mul_f32_e32 v0, v58, v36
	s_waitcnt vmcnt(31)
	v_lshlrev_b32_e32 v9, 16, v72
	v_mul_f32_e32 v0, v0, v9
	v_mul_f32_e32 v9, 0xbfb8aa3b, v9
	v_exp_f32_e32 v9, v9
	s_nop 0
	v_add_f32_e32 v9, 1.0, v9
	v_rcp_f32_e32 v9, v9
	s_nop 0
	v_mul_f32_e32 v0, v0, v9
	v_cvt_pk_bf16_f32 v0, v0, v0
	global_store_short v[6:7], v0, off offset:64
	v_mul_f32_e32 v0, v42, v36
	s_waitcnt vmcnt(31)
	v_lshlrev_b32_e32 v9, 16, v55
	v_mul_f32_e32 v0, v0, v9
	v_mul_f32_e32 v9, 0xbfb8aa3b, v9
	v_exp_f32_e32 v9, v9
	s_nop 0
	v_add_f32_e32 v9, 1.0, v9
	v_rcp_f32_e32 v9, v9
	s_nop 0
	v_mul_f32_e32 v0, v0, v9
	v_cvt_pk_bf16_f32 v0, v0, v0
	global_store_short v[6:7], v0, off offset:128
	v_mul_f32_e32 v0, v26, v36
	s_waitcnt vmcnt(31)
	v_lshlrev_b32_e32 v9, 16, v53
	v_mul_f32_e32 v0, v0, v9
	v_mul_f32_e32 v9, 0xbfb8aa3b, v9
	v_exp_f32_e32 v9, v9
	s_nop 0
	v_add_f32_e32 v9, 1.0, v9
	v_rcp_f32_e32 v9, v9
	s_nop 0
	v_mul_f32_e32 v0, v0, v9
	v_cvt_pk_bf16_f32 v0, v0, v0
	global_store_short v[6:7], v0, off offset:192
	v_add_u32_e32 v0, 0xbe00, v4
	v_lshl_add_u64 v[6:7], v[0:1], 1, v[2:3]
	v_mul_f32_e32 v0, v75, v33
	s_waitcnt vmcnt(31)
	v_lshlrev_b32_e32 v9, 16, v52
	v_mul_f32_e32 v0, v0, v9
	v_mul_f32_e32 v9, 0xbfb8aa3b, v9
	v_exp_f32_e32 v9, v9
	s_nop 0
	v_add_f32_e32 v9, 1.0, v9
	v_rcp_f32_e32 v9, v9
	s_nop 0
	v_mul_f32_e32 v0, v0, v9
	v_cvt_pk_bf16_f32 v0, v0, v0
	global_store_short v[6:7], v0, off
	v_mul_f32_e32 v0, v59, v33
	s_waitcnt vmcnt(31)
	v_lshlrev_b32_e32 v9, 16, v51
	v_mul_f32_e32 v0, v0, v9
	v_mul_f32_e32 v9, 0xbfb8aa3b, v9
	v_exp_f32_e32 v9, v9
	s_nop 0
	v_add_f32_e32 v9, 1.0, v9
	v_rcp_f32_e32 v9, v9
	s_nop 0
	v_mul_f32_e32 v0, v0, v9
	v_cvt_pk_bf16_f32 v0, v0, v0
	global_store_short v[6:7], v0, off offset:64
	v_mul_f32_e32 v0, v43, v33
	s_waitcnt vmcnt(31)
	v_lshlrev_b32_e32 v9, 16, v50
	v_mul_f32_e32 v0, v0, v9
	v_mul_f32_e32 v9, 0xbfb8aa3b, v9
	v_exp_f32_e32 v9, v9
	s_nop 0
	v_add_f32_e32 v9, 1.0, v9
	v_rcp_f32_e32 v9, v9
	s_nop 0
	v_mul_f32_e32 v0, v0, v9
	v_cvt_pk_bf16_f32 v0, v0, v0
	global_store_short v[6:7], v0, off offset:128
	v_mul_f32_e32 v0, v27, v33
	s_waitcnt vmcnt(31)
	v_lshlrev_b32_e32 v9, 16, v48
	v_mul_f32_e32 v0, v0, v9
	v_mul_f32_e32 v9, 0xbfb8aa3b, v9
	v_exp_f32_e32 v9, v9
	s_nop 0
	v_add_f32_e32 v9, 1.0, v9
	v_rcp_f32_e32 v9, v9
	s_nop 0
	v_mul_f32_e32 v0, v0, v9
	v_cvt_pk_bf16_f32 v0, v0, v0
	global_store_short v[6:7], v0, off offset:192
	v_add_u32_e32 v0, 0xf000, v4
	v_lshl_add_u64 v[6:7], v[0:1], 1, v[2:3]
	v_mul_f32_e32 v0, v76, v32
	s_waitcnt vmcnt(31)
	v_lshlrev_b32_e32 v9, 16, v39
	v_mul_f32_e32 v0, v0, v9
	v_mul_f32_e32 v9, 0xbfb8aa3b, v9
	v_exp_f32_e32 v9, v9
	s_nop 0
	v_add_f32_e32 v9, 1.0, v9
	v_rcp_f32_e32 v9, v9
	s_nop 0
	v_mul_f32_e32 v0, v0, v9
	v_cvt_pk_bf16_f32 v0, v0, v0
	global_store_short v[6:7], v0, off
	v_mul_f32_e32 v0, v60, v32
	s_waitcnt vmcnt(31)
	v_lshlrev_b32_e32 v9, 16, v38
	v_mul_f32_e32 v0, v0, v9
	v_mul_f32_e32 v9, 0xbfb8aa3b, v9
	v_exp_f32_e32 v9, v9
	s_nop 0
	v_add_f32_e32 v9, 1.0, v9
	v_rcp_f32_e32 v9, v9
	s_nop 0
	v_mul_f32_e32 v0, v0, v9
	v_cvt_pk_bf16_f32 v0, v0, v0
	global_store_short v[6:7], v0, off offset:64
	v_mul_f32_e32 v0, v44, v32
	s_waitcnt vmcnt(31)
	v_lshlrev_b32_e32 v9, 16, v37
	v_mul_f32_e32 v0, v0, v9
	v_mul_f32_e32 v9, 0xbfb8aa3b, v9
	v_exp_f32_e32 v9, v9
	s_nop 0
	v_add_f32_e32 v9, 1.0, v9
	v_rcp_f32_e32 v9, v9
	s_nop 0
	v_mul_f32_e32 v0, v0, v9
	v_cvt_pk_bf16_f32 v0, v0, v0
	global_store_short v[6:7], v0, off offset:128
	v_mul_f32_e32 v0, v28, v32
	s_waitcnt vmcnt(31)
	v_lshlrev_b32_e32 v9, 16, v35
	v_mul_f32_e32 v0, v0, v9
	v_mul_f32_e32 v9, 0xbfb8aa3b, v9
	v_exp_f32_e32 v9, v9
	s_nop 0
	v_add_f32_e32 v9, 1.0, v9
	v_rcp_f32_e32 v9, v9
	s_nop 0
	v_mul_f32_e32 v0, v0, v9
	v_cvt_pk_bf16_f32 v0, v0, v0
	global_store_short v[6:7], v0, off offset:192
	v_add_u32_e32 v0, 0xfa00, v4
	v_lshl_add_u64 v[6:7], v[0:1], 1, v[2:3]
	v_mul_f32_e32 v0, v77, v23
	s_waitcnt vmcnt(31)
	v_lshlrev_b32_e32 v9, 16, v34
	v_mul_f32_e32 v0, v0, v9
	v_mul_f32_e32 v9, 0xbfb8aa3b, v9
	v_exp_f32_e32 v9, v9
	s_nop 0
	v_add_f32_e32 v9, 1.0, v9
	v_rcp_f32_e32 v9, v9
	s_nop 0
	v_mul_f32_e32 v0, v0, v9
	v_cvt_pk_bf16_f32 v0, v0, v0
	global_store_short v[6:7], v0, off
	v_mul_f32_e32 v0, v61, v23
	s_waitcnt vmcnt(31)
	v_lshlrev_b32_e32 v9, 16, v21
	v_mul_f32_e32 v0, v0, v9
	v_mul_f32_e32 v9, 0xbfb8aa3b, v9
	v_exp_f32_e32 v9, v9
	s_nop 0
	v_add_f32_e32 v9, 1.0, v9
	v_rcp_f32_e32 v9, v9
	s_nop 0
	v_mul_f32_e32 v0, v0, v9
	v_cvt_pk_bf16_f32 v0, v0, v0
	global_store_short v[6:7], v0, off offset:64
	v_mul_f32_e32 v0, v45, v23
	s_waitcnt vmcnt(31)
	v_lshlrev_b32_e32 v9, 16, v20
	v_mul_f32_e32 v0, v0, v9
	v_mul_f32_e32 v9, 0xbfb8aa3b, v9
	v_exp_f32_e32 v9, v9
	s_nop 0
	v_add_f32_e32 v9, 1.0, v9
	v_rcp_f32_e32 v9, v9
	s_nop 0
	v_mul_f32_e32 v0, v0, v9
	v_cvt_pk_bf16_f32 v0, v0, v0
	global_store_short v[6:7], v0, off offset:128
	v_mul_f32_e32 v0, v29, v23
	s_waitcnt vmcnt(31)
	v_lshlrev_b32_e32 v9, 16, v17
	v_mul_f32_e32 v0, v0, v9
	v_mul_f32_e32 v9, 0xbfb8aa3b, v9
	v_exp_f32_e32 v9, v9
	s_nop 0
	v_add_f32_e32 v9, 1.0, v9
	v_rcp_f32_e32 v9, v9
	s_nop 0
	v_mul_f32_e32 v0, v0, v9
	v_cvt_pk_bf16_f32 v0, v0, v0
	global_store_short v[6:7], v0, off offset:192
	v_add_u32_e32 v0, 0x10400, v4
	v_lshl_add_u64 v[6:7], v[0:1], 1, v[2:3]
	v_mul_f32_e32 v0, v78, v22
	s_waitcnt vmcnt(31)
	v_lshlrev_b32_e32 v9, 16, v16
	v_mul_f32_e32 v0, v0, v9
	v_mul_f32_e32 v9, 0xbfb8aa3b, v9
	v_exp_f32_e32 v9, v9
	s_nop 0
	v_add_f32_e32 v9, 1.0, v9
	v_rcp_f32_e32 v9, v9
	s_nop 0
	v_mul_f32_e32 v0, v0, v9
	v_cvt_pk_bf16_f32 v0, v0, v0
	global_store_short v[6:7], v0, off
	v_mul_f32_e32 v0, v62, v22
	s_waitcnt vmcnt(31)
	v_lshlrev_b32_e32 v9, 16, v15
	v_mul_f32_e32 v0, v0, v9
	v_mul_f32_e32 v9, 0xbfb8aa3b, v9
	v_exp_f32_e32 v9, v9
	s_nop 0
	v_add_f32_e32 v9, 1.0, v9
	v_rcp_f32_e32 v9, v9
	s_nop 0
	v_mul_f32_e32 v0, v0, v9
	v_cvt_pk_bf16_f32 v0, v0, v0
	global_store_short v[6:7], v0, off offset:64
	v_mul_f32_e32 v0, v46, v22
	s_waitcnt vmcnt(31)
	v_lshlrev_b32_e32 v9, 16, v14
	v_mul_f32_e32 v0, v0, v9
	v_mul_f32_e32 v9, 0xbfb8aa3b, v9
	v_exp_f32_e32 v9, v9
	s_nop 0
	v_add_f32_e32 v9, 1.0, v9
	v_rcp_f32_e32 v9, v9
	s_nop 0
	v_mul_f32_e32 v0, v0, v9
	v_cvt_pk_bf16_f32 v0, v0, v0
	global_store_short v[6:7], v0, off offset:128
	v_mul_f32_e32 v0, v30, v22
	s_waitcnt vmcnt(31)
	v_lshlrev_b32_e32 v9, 16, v13
	v_mul_f32_e32 v0, v0, v9
	v_mul_f32_e32 v9, 0xbfb8aa3b, v9
	v_exp_f32_e32 v9, v9
	s_nop 0
	v_add_f32_e32 v9, 1.0, v9
	v_rcp_f32_e32 v9, v9
	s_nop 0
	v_mul_f32_e32 v0, v0, v9
	v_cvt_pk_bf16_f32 v0, v0, v0
	global_store_short v[6:7], v0, off offset:192
	v_add_u32_e32 v0, 0x10e00, v4
	v_lshl_add_u64 v[2:3], v[0:1], 1, v[2:3]
	v_mul_f32_e32 v0, v79, v5
	s_waitcnt vmcnt(31)
	v_lshlrev_b32_e32 v4, 16, v12
	v_mul_f32_e32 v0, v0, v4
	v_mul_f32_e32 v4, 0xbfb8aa3b, v4
	v_exp_f32_e32 v4, v4
	s_nop 0
	v_add_f32_e32 v4, 1.0, v4
	v_rcp_f32_e32 v4, v4
	s_nop 0
	v_mul_f32_e32 v0, v0, v4
	v_cvt_pk_bf16_f32 v0, v0, v0
	global_store_short v[2:3], v0, off
	v_mul_f32_e32 v0, v63, v5
	s_waitcnt vmcnt(31)
	v_lshlrev_b32_e32 v4, 16, v11
	v_mul_f32_e32 v0, v0, v4
	v_mul_f32_e32 v4, 0xbfb8aa3b, v4
	v_exp_f32_e32 v4, v4
	s_nop 0
	v_add_f32_e32 v4, 1.0, v4
	v_rcp_f32_e32 v4, v4
	s_nop 0
	v_mul_f32_e32 v0, v0, v4
	v_cvt_pk_bf16_f32 v0, v0, v0
	global_store_short v[2:3], v0, off offset:64
	v_mul_f32_e32 v0, v47, v5
	s_waitcnt vmcnt(31)
	v_lshlrev_b32_e32 v4, 16, v10
	v_mul_f32_e32 v0, v0, v4
	v_mul_f32_e32 v4, 0xbfb8aa3b, v4
	v_exp_f32_e32 v4, v4
	s_nop 0
	v_add_f32_e32 v4, 1.0, v4
	v_rcp_f32_e32 v4, v4
	s_nop 0
	v_mul_f32_e32 v0, v0, v4
	v_cvt_pk_bf16_f32 v0, v0, v0
	global_store_short v[2:3], v0, off offset:128
	v_mul_f32_e32 v0, v31, v5
	s_waitcnt vmcnt(31)
	v_lshlrev_b32_e32 v4, 16, v8
	v_mul_f32_e32 v0, v0, v4
	v_mul_f32_e32 v4, 0xbfb8aa3b, v4
	v_exp_f32_e32 v4, v4
	s_nop 0
	v_add_f32_e32 v4, 1.0, v4
	v_rcp_f32_e32 v4, v4
	s_nop 0
	v_mul_f32_e32 v0, v0, v4
	v_cvt_pk_bf16_f32 v0, v0, v0
	global_store_short v[2:3], v0, off offset:192
	s_cbranch_vccnz .LBB0_993
.LBB0_996:
	s_xor_b64 s[16:17], s[0:1], -1
	s_and_b64 s[0:1], s[0:1], exec
	s_cselect_b32 s0, s36, s35
	s_lshl_b32 s7, s0, 8
	s_or_b32 s2, s7, s6
	v_add_u32_e32 v2, s2, v175
	s_movk_i32 s1, 0x1800
	v_mad_i64_i32 v[46:47], s[4:5], v2, s1, v[168:169]
	global_load_dwordx4 v[18:21], v[46:47], off
	global_load_dwordx4 v[22:25], v[46:47], off offset:32
	global_load_dwordx4 v[26:29], v[46:47], off offset:64
	global_load_dwordx4 v[30:33], v[46:47], off offset:96
	v_ashrrev_i32_e32 v3, 31, v2
	v_lshlrev_b64 v[50:51], 8, v[2:3]
	global_load_dwordx4 v[10:13], v[46:47], off offset:256
	global_load_dwordx4 v[2:5], v[46:47], off offset:288
	global_load_dwordx4 v[14:17], v[46:47], off offset:320
	global_load_dwordx4 v[6:9], v[46:47], off offset:352
	global_load_dwordx4 v[34:37], v[46:47], off offset:128
	global_load_dwordx4 v[38:41], v[46:47], off offset:160
	global_load_dwordx4 v[42:45], v[46:47], off offset:192
	s_nop 0
	global_load_dwordx4 v[46:49], v[46:47], off offset:224
	s_lshl_b32 s38, s0, 2
	v_mov_b32_e32 v171, v1
	s_mov_b64 s[20:21], 0x100
	s_add_i32 s38, s38, 4
	v_add_u32_e32 v181, s7, v174
	s_mov_b32 s42, 2
	v_or_b32_e32 v182, 31, v181
	s_mov_b32 s43, 0
	v_mov_b32_e32 v180, 0
	v_mov_b32_e32 v186, 0xf149f2ca
	s_movk_i32 s44, 0xff00
	s_mov_b32 s45, 0
	s_mov_b32 s37, 0
	s_waitcnt vmcnt(11)
	v_lshlrev_b32_e32 v0, 16, v18
	v_and_b32_e32 v18, 0xffff0000, v18
	v_lshlrev_b32_e32 v52, 16, v19
	v_and_b32_e32 v19, 0xffff0000, v19
	v_lshlrev_b32_e32 v53, 16, v20
	v_and_b32_e32 v20, 0xffff0000, v20
	v_mul_f32_e32 v18, 0x3dd53b94, v18
	v_mul_f32_e32 v19, 0x3dd53b94, v19
	v_mul_f32_e32 v20, 0x3dd53b94, v20
	v_lshlrev_b32_e32 v54, 16, v21
	v_and_b32_e32 v21, 0xffff0000, v21
	s_waitcnt vmcnt(10)
	v_lshlrev_b32_e32 v55, 16, v22
	v_and_b32_e32 v22, 0xffff0000, v22
	v_lshlrev_b32_e32 v56, 16, v23
	v_and_b32_e32 v23, 0xffff0000, v23
	v_lshlrev_b32_e32 v57, 16, v24
	v_and_b32_e32 v24, 0xffff0000, v24
	v_mul_f32_e32 v0, 0x3dd53b94, v0
	v_mul_f32_e32 v52, 0x3dd53b94, v52
	v_mul_f32_e32 v53, 0x3dd53b94, v53
	v_cvt_pk_bf16_f32 v112, v0, v18
	v_cvt_pk_bf16_f32 v113, v52, v19
	v_cvt_pk_bf16_f32 v114, v53, v20
	s_waitcnt vmcnt(8)
	v_and_b32_e32 v18, 0xffff0000, v32
	v_lshlrev_b32_e32 v19, 16, v33
	v_and_b32_e32 v20, 0xffff0000, v33
	v_lshlrev_b32_e32 v58, 16, v25
	v_and_b32_e32 v25, 0xffff0000, v25
	v_lshlrev_b32_e32 v59, 16, v26
	v_and_b32_e32 v26, 0xffff0000, v26
	v_lshlrev_b32_e32 v60, 16, v27
	v_and_b32_e32 v27, 0xffff0000, v27
	v_lshlrev_b32_e32 v61, 16, v28
	v_and_b32_e32 v28, 0xffff0000, v28
	v_lshlrev_b32_e32 v62, 16, v29
	v_and_b32_e32 v29, 0xffff0000, v29
	v_lshlrev_b32_e32 v63, 16, v30
	v_and_b32_e32 v30, 0xffff0000, v30
	v_lshlrev_b32_e32 v64, 16, v31
	v_and_b32_e32 v31, 0xffff0000, v31
	v_mul_f32_e32 v21, 0x3dd53b94, v21
	v_mul_f32_e32 v22, 0x3dd53b94, v22
	v_mul_f32_e32 v23, 0x3dd53b94, v23
	v_mul_f32_e32 v24, 0x3dd53b94, v24
	v_lshlrev_b32_e32 v0, 16, v32
	v_mul_f32_e32 v18, 0x3dd53b94, v18
	v_mul_f32_e32 v19, 0x3dd53b94, v19
	v_mul_f32_e32 v20, 0x3dd53b94, v20
	v_mul_f32_e32 v54, 0x3dd53b94, v54
	v_mul_f32_e32 v55, 0x3dd53b94, v55
	v_mul_f32_e32 v56, 0x3dd53b94, v56
	v_mul_f32_e32 v57, 0x3dd53b94, v57
	v_mul_f32_e32 v58, 0x3dd53b94, v58
	v_mul_f32_e32 v25, 0x3dd53b94, v25
	v_mul_f32_e32 v59, 0x3dd53b94, v59
	v_mul_f32_e32 v26, 0x3dd53b94, v26
	v_mul_f32_e32 v60, 0x3dd53b94, v60
	v_mul_f32_e32 v27, 0x3dd53b94, v27
	v_mul_f32_e32 v61, 0x3dd53b94, v61
	v_mul_f32_e32 v28, 0x3dd53b94, v28
	v_mul_f32_e32 v62, 0x3dd53b94, v62
	v_mul_f32_e32 v29, 0x3dd53b94, v29
	v_mul_f32_e32 v63, 0x3dd53b94, v63
	v_mul_f32_e32 v30, 0x3dd53b94, v30
	v_mul_f32_e32 v64, 0x3dd53b94, v64
	v_mul_f32_e32 v31, 0x3dd53b94, v31
	v_cvt_pk_bf16_f32 v115, v54, v21
	v_cvt_pk_bf16_f32 v116, v55, v22
	v_cvt_pk_bf16_f32 v117, v56, v23
	v_cvt_pk_bf16_f32 v118, v57, v24
	v_cvt_pk_bf16_f32 v119, v58, v25
	v_cvt_pk_bf16_f32 v120, v59, v26
	v_cvt_pk_bf16_f32 v121, v60, v27
	v_cvt_pk_bf16_f32 v122, v61, v28
	v_cvt_pk_bf16_f32 v123, v62, v29
	v_mul_f32_e32 v0, 0x3dd53b94, v0
	v_cvt_pk_bf16_f32 v124, v63, v30
	v_cvt_pk_bf16_f32 v125, v64, v31
	v_cvt_pk_bf16_f32 v126, v0, v18
	v_cvt_pk_bf16_f32 v127, v19, v20
	s_waitcnt vmcnt(3)
	v_and_b32_e32 v18, 0xffff0000, v34
	v_lshlrev_b32_e32 v19, 16, v35
	v_and_b32_e32 v20, 0xffff0000, v35
	v_lshlrev_b32_e32 v21, 16, v36
	v_and_b32_e32 v22, 0xffff0000, v36
	v_lshlrev_b32_e32 v23, 16, v37
	v_and_b32_e32 v24, 0xffff0000, v37
	v_lshlrev_b32_e32 v0, 16, v34
	v_mul_f32_e32 v18, 0x3dd53b94, v18
	v_mul_f32_e32 v19, 0x3dd53b94, v19
	v_mul_f32_e32 v20, 0x3dd53b94, v20
	v_mul_f32_e32 v21, 0x3dd53b94, v21
	v_mul_f32_e32 v22, 0x3dd53b94, v22
	v_mul_f32_e32 v23, 0x3dd53b94, v23
	v_mul_f32_e32 v24, 0x3dd53b94, v24
	v_mul_f32_e32 v0, 0x3dd53b94, v0
	v_cvt_pk_bf16_f32 v128, v0, v18
	v_cvt_pk_bf16_f32 v129, v19, v20
	v_cvt_pk_bf16_f32 v130, v21, v22
	v_cvt_pk_bf16_f32 v131, v23, v24
	s_waitcnt vmcnt(2)
	v_and_b32_e32 v18, 0xffff0000, v38
	v_lshlrev_b32_e32 v19, 16, v39
	v_and_b32_e32 v20, 0xffff0000, v39
	v_lshlrev_b32_e32 v21, 16, v40
	v_and_b32_e32 v22, 0xffff0000, v40
	v_lshlrev_b32_e32 v23, 16, v41
	v_and_b32_e32 v24, 0xffff0000, v41
	v_lshlrev_b32_e32 v0, 16, v38
	v_mul_f32_e32 v18, 0x3dd53b94, v18
	v_mul_f32_e32 v19, 0x3dd53b94, v19
	v_mul_f32_e32 v20, 0x3dd53b94, v20
	v_mul_f32_e32 v21, 0x3dd53b94, v21
	v_mul_f32_e32 v22, 0x3dd53b94, v22
	v_mul_f32_e32 v23, 0x3dd53b94, v23
	v_mul_f32_e32 v24, 0x3dd53b94, v24
	v_mul_f32_e32 v0, 0x3dd53b94, v0
	v_cvt_pk_bf16_f32 v132, v0, v18
	v_cvt_pk_bf16_f32 v133, v19, v20
	v_cvt_pk_bf16_f32 v134, v21, v22
	v_cvt_pk_bf16_f32 v135, v23, v24
	s_waitcnt vmcnt(1)
	v_and_b32_e32 v18, 0xffff0000, v42
	v_lshlrev_b32_e32 v19, 16, v43
	v_and_b32_e32 v20, 0xffff0000, v43
	v_lshlrev_b32_e32 v21, 16, v44
	v_and_b32_e32 v22, 0xffff0000, v44
	v_lshlrev_b32_e32 v23, 16, v45
	v_and_b32_e32 v24, 0xffff0000, v45
	v_lshlrev_b32_e32 v0, 16, v42
	v_mul_f32_e32 v18, 0x3dd53b94, v18
	v_mul_f32_e32 v19, 0x3dd53b94, v19
	v_mul_f32_e32 v20, 0x3dd53b94, v20
	v_mul_f32_e32 v21, 0x3dd53b94, v21
	v_mul_f32_e32 v22, 0x3dd53b94, v22
	v_mul_f32_e32 v23, 0x3dd53b94, v23
	v_mul_f32_e32 v24, 0x3dd53b94, v24
	v_mul_f32_e32 v0, 0x3dd53b94, v0
	v_cvt_pk_bf16_f32 v136, v0, v18
	v_cvt_pk_bf16_f32 v137, v19, v20
	v_cvt_pk_bf16_f32 v138, v21, v22
	v_cvt_pk_bf16_f32 v139, v23, v24
	s_waitcnt vmcnt(0)
	v_and_b32_e32 v18, 0xffff0000, v46
	v_lshlrev_b32_e32 v19, 16, v47
	v_and_b32_e32 v20, 0xffff0000, v47
	v_lshlrev_b32_e32 v21, 16, v48
	v_and_b32_e32 v22, 0xffff0000, v48
	v_lshlrev_b32_e32 v23, 16, v49
	v_and_b32_e32 v24, 0xffff0000, v49
	v_lshlrev_b32_e32 v0, 16, v46
	v_mul_f32_e32 v18, 0x3dd53b94, v18
	v_mul_f32_e32 v19, 0x3dd53b94, v19
	v_mul_f32_e32 v20, 0x3dd53b94, v20
	v_mul_f32_e32 v21, 0x3dd53b94, v21
	v_mul_f32_e32 v22, 0x3dd53b94, v22
	v_mul_f32_e32 v23, 0x3dd53b94, v23
	v_mul_f32_e32 v24, 0x3dd53b94, v24
	v_lshl_add_u64 v[34:35], v[164:165], 0, v[50:51]
	v_mul_f32_e32 v0, 0x3dd53b94, v0
	v_cvt_pk_bf16_f32 v140, v0, v18
	v_cvt_pk_bf16_f32 v141, v19, v20
	v_cvt_pk_bf16_f32 v142, v21, v22
	v_cvt_pk_bf16_f32 v143, v23, v24
	global_load_dwordx4 v[18:21], v[34:35], off
	global_load_dwordx4 v[22:25], v[34:35], off offset:16
	global_load_dwordx4 v[26:29], v[34:35], off offset:32
	global_load_dwordx4 v[30:33], v[34:35], off offset:48
	v_lshlrev_b32_e32 v37, 16, v10
	v_lshlrev_b32_e32 v36, 16, v14
	s_waitcnt vmcnt(3)
	v_pk_mul_f32 v[38:39], v[18:19], v[36:37] op_sel:[0,1] op_sel_hi:[1,0]
	v_pk_mul_f32 v[18:19], v[18:19], v[36:37]
	v_sub_f32_e32 v0, v38, v39
	v_add_f32_e32 v18, v18, v19
	v_mul_f32_e32 v38, 0x3dd53b94, v18
	v_and_b32_e32 v19, 0xffff0000, v10
	v_and_b32_e32 v18, 0xffff0000, v14
	v_pk_mul_f32 v[36:37], v[20:21], v[18:19] op_sel:[0,1] op_sel_hi:[1,0]
	v_pk_mul_f32 v[18:19], v[20:21], v[18:19]
	v_sub_f32_e32 v10, v36, v37
	v_mul_f32_e32 v36, 0x3dd53b94, v10
	v_add_f32_e32 v10, v18, v19
	v_lshlrev_b32_e32 v19, 16, v11
	v_lshlrev_b32_e32 v18, 16, v15
	s_waitcnt vmcnt(2)
	v_pk_mul_f32 v[20:21], v[22:23], v[18:19] op_sel:[0,1] op_sel_hi:[1,0]
	v_mul_f32_e32 v37, 0x3dd53b94, v10
	v_sub_f32_e32 v10, v20, v21
	v_pk_mul_f32 v[18:19], v[22:23], v[18:19]
	v_mul_f32_e32 v20, 0x3dd53b94, v10
	v_add_f32_e32 v10, v18, v19
	v_mul_f32_e32 v18, 0x3dd53b94, v10
	v_and_b32_e32 v11, 0xffff0000, v11
	v_and_b32_e32 v10, 0xffff0000, v15
	v_pk_mul_f32 v[14:15], v[24:25], v[10:11] op_sel:[0,1] op_sel_hi:[1,0]
	v_pk_mul_f32 v[10:11], v[24:25], v[10:11]
	v_sub_f32_e32 v14, v14, v15
	v_add_f32_e32 v10, v10, v11
	v_mul_f32_e32 v21, 0x3dd53b94, v10
	v_lshlrev_b32_e32 v11, 16, v12
	v_lshlrev_b32_e32 v10, 16, v16
	v_mul_f32_e32 v19, 0x3dd53b94, v14
	s_waitcnt vmcnt(1)
	v_pk_mul_f32 v[14:15], v[26:27], v[10:11] op_sel:[0,1] op_sel_hi:[1,0]
	v_pk_mul_f32 v[10:11], v[26:27], v[10:11]
	v_sub_f32_e32 v14, v14, v15
	v_add_f32_e32 v10, v10, v11
	v_mul_f32_e32 v23, 0x3dd53b94, v10
	v_and_b32_e32 v11, 0xffff0000, v12
	v_and_b32_e32 v10, 0xffff0000, v16
	v_mul_f32_e32 v22, 0x3dd53b94, v14
	v_pk_mul_f32 v[14:15], v[28:29], v[10:11] op_sel:[0,1] op_sel_hi:[1,0]
	v_pk_mul_f32 v[10:11], v[28:29], v[10:11]
	v_sub_f32_e32 v12, v14, v15
	v_add_f32_e32 v10, v10, v11
	v_mul_f32_e32 v24, 0x3dd53b94, v10
	v_lshlrev_b32_e32 v11, 16, v13
	v_lshlrev_b32_e32 v10, 16, v17
	s_waitcnt vmcnt(0)
	v_pk_mul_f32 v[14:15], v[30:31], v[10:11] op_sel:[0,1] op_sel_hi:[1,0]
	v_pk_mul_f32 v[10:11], v[30:31], v[10:11]
	v_mul_f32_e32 v16, 0x3dd53b94, v12
	v_add_f32_e32 v10, v10, v11
	v_sub_f32_e32 v12, v14, v15
	v_mul_f32_e32 v15, 0x3dd53b94, v10
	v_and_b32_e32 v11, 0xffff0000, v13
	v_and_b32_e32 v10, 0xffff0000, v17
	v_mul_f32_e32 v14, 0x3dd53b94, v12
	v_pk_mul_f32 v[12:13], v[32:33], v[10:11] op_sel:[0,1] op_sel_hi:[1,0]
	v_pk_mul_f32 v[10:11], v[32:33], v[10:11]
	v_sub_f32_e32 v12, v12, v13
	v_add_f32_e32 v10, v10, v11
	v_mul_f32_e32 v12, 0x3dd53b94, v12
	v_mul_f32_e32 v10, 0x3dd53b94, v10
	v_mul_f32_e32 v0, 0x3dd53b94, v0
	v_cvt_pk_bf16_f32 v144, v0, v36
	v_cvt_pk_bf16_f32 v145, v20, v19
	v_cvt_pk_bf16_f32 v146, v22, v16
	v_cvt_pk_bf16_f32 v147, v14, v12
	v_cvt_pk_bf16_f32 v148, v38, v37
	v_cvt_pk_bf16_f32 v149, v18, v21
	v_cvt_pk_bf16_f32 v150, v23, v24
	v_cvt_pk_bf16_f32 v151, v15, v10
	global_load_dwordx4 v[10:13], v[34:35], off offset:128
	global_load_dwordx4 v[14:17], v[34:35], off offset:144
	global_load_dwordx4 v[18:21], v[34:35], off offset:160
	global_load_dwordx4 v[22:25], v[34:35], off offset:176
	v_lshlrev_b32_e32 v27, 16, v2
	v_lshlrev_b32_e32 v26, 16, v6
	s_waitcnt vmcnt(3)
	v_pk_mul_f32 v[28:29], v[10:11], v[26:27] op_sel:[0,1] op_sel_hi:[1,0]
	v_pk_mul_f32 v[10:11], v[10:11], v[26:27]
	v_sub_f32_e32 v0, v28, v29
	v_add_f32_e32 v10, v10, v11
	v_mul_f32_e32 v28, 0x3dd53b94, v10
	v_and_b32_e32 v11, 0xffff0000, v2
	v_and_b32_e32 v10, 0xffff0000, v6
	v_pk_mul_f32 v[26:27], v[12:13], v[10:11] op_sel:[0,1] op_sel_hi:[1,0]
	v_pk_mul_f32 v[10:11], v[12:13], v[10:11]
	v_sub_f32_e32 v2, v26, v27
	v_mul_f32_e32 v26, 0x3dd53b94, v2
	v_add_f32_e32 v2, v10, v11
	v_lshlrev_b32_e32 v11, 16, v3
	v_lshlrev_b32_e32 v10, 16, v7
	s_waitcnt vmcnt(2)
	v_pk_mul_f32 v[12:13], v[14:15], v[10:11] op_sel:[0,1] op_sel_hi:[1,0]
	v_mul_f32_e32 v27, 0x3dd53b94, v2
	v_sub_f32_e32 v2, v12, v13
	v_pk_mul_f32 v[10:11], v[14:15], v[10:11]
	v_mul_f32_e32 v12, 0x3dd53b94, v2
	v_add_f32_e32 v2, v10, v11
	v_mul_f32_e32 v10, 0x3dd53b94, v2
	v_and_b32_e32 v3, 0xffff0000, v3
	v_and_b32_e32 v2, 0xffff0000, v7
	v_pk_mul_f32 v[6:7], v[16:17], v[2:3] op_sel:[0,1] op_sel_hi:[1,0]
	v_pk_mul_f32 v[2:3], v[16:17], v[2:3]
	v_sub_f32_e32 v6, v6, v7
	v_add_f32_e32 v2, v2, v3
	v_mul_f32_e32 v13, 0x3dd53b94, v2
	v_lshlrev_b32_e32 v3, 16, v4
	v_lshlrev_b32_e32 v2, 16, v8
	v_mul_f32_e32 v11, 0x3dd53b94, v6
	s_waitcnt vmcnt(1)
	v_pk_mul_f32 v[6:7], v[18:19], v[2:3] op_sel:[0,1] op_sel_hi:[1,0]
	v_pk_mul_f32 v[2:3], v[18:19], v[2:3]
	v_sub_f32_e32 v6, v6, v7
	v_add_f32_e32 v2, v2, v3
	v_mul_f32_e32 v15, 0x3dd53b94, v2
	v_and_b32_e32 v3, 0xffff0000, v4
	v_and_b32_e32 v2, 0xffff0000, v8
	v_mul_f32_e32 v14, 0x3dd53b94, v6
	v_pk_mul_f32 v[6:7], v[20:21], v[2:3] op_sel:[0,1] op_sel_hi:[1,0]
	v_pk_mul_f32 v[2:3], v[20:21], v[2:3]
	v_sub_f32_e32 v4, v6, v7
	v_add_f32_e32 v2, v2, v3
	v_mul_f32_e32 v16, 0x3dd53b94, v2
	v_lshlrev_b32_e32 v3, 16, v5
	v_lshlrev_b32_e32 v2, 16, v9
	s_waitcnt vmcnt(0)
	v_pk_mul_f32 v[6:7], v[22:23], v[2:3] op_sel:[0,1] op_sel_hi:[1,0]
	v_pk_mul_f32 v[2:3], v[22:23], v[2:3]
	v_mul_f32_e32 v8, 0x3dd53b94, v4
	v_add_f32_e32 v2, v2, v3
	v_sub_f32_e32 v4, v6, v7
	v_mul_f32_e32 v7, 0x3dd53b94, v2
	v_and_b32_e32 v3, 0xffff0000, v5
	v_and_b32_e32 v2, 0xffff0000, v9
	v_mul_f32_e32 v6, 0x3dd53b94, v4
	v_pk_mul_f32 v[4:5], v[24:25], v[2:3] op_sel:[0,1] op_sel_hi:[1,0]
	v_pk_mul_f32 v[2:3], v[24:25], v[2:3]
	v_sub_f32_e32 v4, v4, v5
	v_mul_f32_e32 v0, 0x3dd53b94, v0
	v_mul_f32_e32 v4, 0x3dd53b94, v4
	v_add_f32_e32 v2, v2, v3
	v_cvt_pk_bf16_f32 v152, v0, v26
	v_cvt_pk_bf16_f32 v153, v12, v11
	v_cvt_pk_bf16_f32 v154, v14, v8
	v_cvt_pk_bf16_f32 v155, v6, v4
	v_cvt_pk_bf16_f32 v156, v28, v27
	v_cvt_pk_bf16_f32 v157, v10, v13
	v_mov_b32_e32 v10, v198
	v_mul_f32_e32 v2, 0x3dd53b94, v2
	v_cvt_pk_bf16_f32 v158, v15, v16
	v_cvt_pk_bf16_f32 v159, v7, v2
	s_nop 0
	v_readfirstlane_b32 s0, v10
	v_bfe_u32 v12, v10, 4, 2
	s_ashr_i32 s4, s0, 6
	v_and_b32_e32 v2, 15, v10
	v_bitop3_b32 v4, v12, v10, 15 bitop3:0x78
	s_lshl_b32 s0, s4, 3
	v_lshlrev_b32_e32 v13, 3, v4
	v_or_b32_e32 v4, 4, v12
	v_bitop3_b32 v2, v12, v2, 4 bitop3:0x36
	v_bfe_u32 v0, v10, 2, 3
	v_lshrrev_b32_e32 v3, 1, v10
	s_lshl_b32 s1, s4, 2
	v_or_b32_e32 v4, s0, v4
	v_lshlrev_b32_e32 v14, 3, v2
	v_bfe_u32 v15, v10, 3, 3
	v_bitop3_b32 v0, s0, v204, v0 bitop3:0xc8
	v_and_b32_e32 v3, 8, v3
	s_and_b32 s1, s1, 4
	v_lshl_or_b32 v2, v4, 12, v14
	v_or_b32_e32 v4, s0, v15
	v_or3_b32 v0, v3, v0, s1
	v_lshrrev_b32_e32 v6, 1, v4
	v_lshlrev_b32_e32 v11, 3, v10
	v_lshlrev_b32_e32 v8, 12, v0
	v_or_b32_e32 v0, s0, v12
	v_xor_b32_e32 v6, v6, v10
	s_lshl_b32 s5, s4, 11
	s_add_i32 s0, 0, 0x10000
	v_and_b32_e32 v3, 32, v10
	v_and_b32_e32 v5, 24, v11
	v_lshl_or_b32 v0, v0, 12, v13
	v_lshlrev_b32_e32 v6, 3, v6
	s_add_i32 s39, s0, s5
	v_and_b32_e32 v16, 56, v6
	v_lshl_add_u64 v[6:7], v[0:1], 1, s[14:15]
	s_mov_b32 m0, s39
	v_or3_b32 v170, v3, v5, v8
	global_load_lds_dwordx4 v[6:7], off
	v_lshl_add_u64 v[6:7], v[170:171], 1, s[14:15]
	s_add_i32 s40, s5, 0
	v_lshl_add_u64 v[8:9], v[6:7], 0, s[20:21]
	s_mov_b32 m0, s40
	s_or_b32 s18, s5, 0x400
	global_load_lds_dwordx4 v[8:9], off
	s_add_i32 m0, s0, s18
	s_mov_b64 s[0:1], 0x180
	v_mov_b32_e32 v3, v1
	v_lshl_add_u64 v[6:7], v[6:7], 0, s[0:1]
	s_lshl_b32 s0, s4, 10
	v_mul_lo_u32 v4, v4, s25
	v_lshl_add_u64 v[8:9], v[2:3], 1, s[14:15]
	s_add_i32 s0, s0, 0
	v_or_b32_e32 v4, v16, v4
	global_load_lds_dwordx4 v[8:9], off
	s_add_i32 m0, s40, 0x400
	v_mov_b32_e32 v5, v1
	s_add_i32 s41, s0, 0x1c000
	global_load_lds_dwordx4 v[6:7], off
	v_lshl_add_u64 v[6:7], v[4:5], 1, s[8:9]
	s_mov_b32 m0, s41
	v_add_u32_e32 v0, 0x40000, v0
	s_add_i32 s1, 0, 0x14000
	global_load_lds_dwordx4 v[6:7], off
	v_lshl_add_u64 v[6:7], v[0:1], 1, s[14:15]
	s_add_i32 m0, s1, s5
	v_add_u32_e32 v0, 0x40000, v170
	global_load_lds_dwordx4 v[6:7], off
	v_lshl_add_u64 v[6:7], v[0:1], 1, s[14:15]
	v_lshl_add_u64 v[6:7], v[6:7], 0, s[20:21]
	s_add_i32 m0, s40, 0x4000
	v_add_u32_e32 v0, 0x40000, v2
	global_load_lds_dwordx4 v[6:7], off
	v_lshl_add_u64 v[2:3], v[0:1], 1, s[14:15]
	s_add_i32 m0, s1, s18
	v_add_u32_e32 v0, 0x40040, v170
	global_load_lds_dwordx4 v[2:3], off
	s_add_i32 m0, s40, 0x4400
	v_lshl_add_u64 v[2:3], v[0:1], 1, s[14:15]
	s_cmp_gt_i32 s4, 3
	v_lshl_add_u64 v[2:3], v[2:3], 0, s[20:21]
	s_cselect_b64 s[18:19], -1, 0
	s_cmp_lt_i32 s4, 4
	v_add_u32_e32 v0, 0x44000, v4
	global_load_lds_dwordx4 v[2:3], off
	s_cselect_b64 s[20:21], -1, 0
	v_lshl_add_u64 v[2:3], v[0:1], 1, s[8:9]
	s_add_i32 m0, s0, 0x1e000
	v_and_b32_e32 v0, 63, v10
	global_load_lds_dwordx4 v[2:3], off
	v_and_b32_e32 v4, 0x3fffffc0, v10
	v_readlane_b32 s0, v254, 1
	v_lshlrev_b32_e32 v5, 4, v10
	v_bfe_u32 v3, v10, 5, 1
	v_lshl_add_u32 v176, v4, 2, s0
	v_lshlrev_b32_e32 v4, 3, v0
	v_and_b32_e32 v6, 0xc0, v5
	v_lshlrev_b32_e32 v7, 1, v10
	v_and_or_b32 v6, v4, 24, v6
	v_and_b32_e32 v7, 32, v7
	v_and_b32_e32 v4, 0x100, v4
	v_lshlrev_b32_e32 v177, 4, v3
	s_movk_i32 s0, 0x70
	v_or3_b32 v4, v6, v7, v4
	v_and_b32_e32 v6, 0x70, v5
	v_and_b32_e32 v7, 0x70, v11
	v_bitop3_b32 v185, v177, v5, s0 bitop3:0x78
	v_bitop3_b32 v187, v177, v11, s0 bitop3:0x78
	s_movk_i32 s0, 0x60
	s_lshl_b32 s5, s4, 15
	s_mul_i32 s4, s4, 0x8800
	v_bitop3_b32 v192, v177, v6, s0 bitop3:0x36
	v_bitop3_b32 v193, v177, v7, s0 bitop3:0x36
	v_cmp_gt_u32_e64 s[0:1], 32, v0
	s_add_i32 s24, s5, 0x84000
	v_lshlrev_b32_e32 v0, 12, v12
	s_add_i32 s5, s5, 0x80000
	s_add_i32 s4, s4, 0x88000
	v_or3_b32 v195, s24, v0, v14
	v_or3_b32 v196, s5, v0, v13
	v_mov_b32_e32 v0, s4
	v_and_b32_e32 v2, 31, v10
	s_waitcnt vmcnt(5)
	v_mad_u32_u24 v0, v15, s25, v0
	v_mov_b32_e32 v14, v1
	v_mov_b32_e32 v15, v1
	v_lshlrev_b32_e32 v183, 8, v2
	v_lshlrev_b32_e32 v184, 7, v2
	v_bitop3_b32 v188, v177, v6, 32 bitop3:0x36
	v_bitop3_b32 v189, v177, v7, 32 bitop3:0x36
	v_bitop3_b32 v190, v177, v6, 64 bitop3:0x36
	v_bitop3_b32 v191, v177, v7, 64 bitop3:0x36
	v_add_u32_e32 v171, 0, v4
	v_lshl_add_u32 v179, v2, 2, v176
	v_mad_i32_i24 v194, v3, -4, v175
	v_or_b32_e32 v172, v0, v16
	v_mov_b32_e32 v0, v1
	v_mov_b32_e32 v2, v1
	v_mov_b32_e32 v3, v1
	v_mov_b32_e32 v4, v1
	v_mov_b32_e32 v5, v1
	v_mov_b32_e32 v6, v1
	v_mov_b32_e32 v7, v1
	v_mov_b32_e32 v8, v1
	v_mov_b32_e32 v9, v1
	v_mov_b32_e32 v10, v1
	v_mov_b32_e32 v11, v1
	v_mov_b32_e32 v12, v1
	v_mov_b32_e32 v13, v1
	v_mov_b64_e32 v[30:31], v[14:15]
	v_mov_b64_e32 v[46:47], v[14:15]
	v_mov_b64_e32 v[62:63], v[14:15]
	v_mov_b64_e32 v[78:79], v[14:15]
	v_mov_b64_e32 v[94:95], v[14:15]
	v_mov_b64_e32 v[110:111], v[14:15]
	s_mov_b64 s[24:25], 0
	v_mov_b64_e32 v[28:29], v[12:13]
	v_mov_b64_e32 v[26:27], v[10:11]
	v_mov_b64_e32 v[24:25], v[8:9]
	v_mov_b64_e32 v[22:23], v[6:7]
	v_mov_b64_e32 v[20:21], v[4:5]
	v_mov_b64_e32 v[18:19], v[2:3]
	v_mov_b64_e32 v[16:17], v[0:1]
	v_mov_b64_e32 v[44:45], v[12:13]
	v_mov_b64_e32 v[42:43], v[10:11]
	v_mov_b64_e32 v[40:41], v[8:9]
	v_mov_b64_e32 v[38:39], v[6:7]
	v_mov_b64_e32 v[36:37], v[4:5]
	v_mov_b64_e32 v[34:35], v[2:3]
	v_mov_b64_e32 v[32:33], v[0:1]
	v_mov_b64_e32 v[60:61], v[12:13]
	v_mov_b64_e32 v[58:59], v[10:11]
	v_mov_b64_e32 v[56:57], v[8:9]
	v_mov_b64_e32 v[54:55], v[6:7]
	v_mov_b64_e32 v[52:53], v[4:5]
	v_mov_b64_e32 v[50:51], v[2:3]
	v_mov_b64_e32 v[48:49], v[0:1]
	v_mov_b64_e32 v[76:77], v[12:13]
	v_mov_b64_e32 v[74:75], v[10:11]
	v_mov_b64_e32 v[72:73], v[8:9]
	v_mov_b64_e32 v[70:71], v[6:7]
	v_mov_b64_e32 v[68:69], v[4:5]
	v_mov_b64_e32 v[66:67], v[2:3]
	v_mov_b64_e32 v[64:65], v[0:1]
	v_mov_b64_e32 v[92:93], v[12:13]
	v_mov_b64_e32 v[90:91], v[10:11]
	v_mov_b64_e32 v[88:89], v[8:9]
	v_mov_b64_e32 v[86:87], v[6:7]
	v_mov_b64_e32 v[84:85], v[4:5]
	v_mov_b64_e32 v[82:83], v[2:3]
	v_mov_b64_e32 v[80:81], v[0:1]
	v_mov_b64_e32 v[108:109], v[12:13]
	v_mov_b64_e32 v[106:107], v[10:11]
	v_mov_b64_e32 v[104:105], v[8:9]
	v_mov_b64_e32 v[102:103], v[6:7]
	v_mov_b64_e32 v[100:101], v[4:5]
	v_mov_b64_e32 v[98:99], v[2:3]
	v_mov_b64_e32 v[96:97], v[0:1]
	s_waitcnt vmcnt(5) lgkmcnt(0)
	s_barrier
	s_branch .LBB0_998
.LBB0_997:
	s_add_i32 s4, s45, 1
	s_cmp_lg_u32 s45, 2
	s_cselect_b32 s45, s4, 0
	s_add_i32 s4, s37, 1
	s_and_b32 s37, s4, 3
	s_add_i32 s44, s44, 64
	s_add_i32 s43, s43, 0x40000
	s_add_i32 s42, s42, 1
	v_subrev_u32_e32 v194, 64, v194
	s_cmp_lg_u32 s7, s44
	v_add_u32_e32 v172, 0x44000, v172
	s_waitcnt vmcnt(5) lgkmcnt(0)
	s_barrier
	s_cbranch_scc0 .LBB0_1020

.LBB0_1039:
	s_add_i32 s18, s37, 1
	s_cmp_lg_u32 s37, 2
	s_cselect_b32 s37, s18, 0
	s_add_i32 s18, s38, 1
	s_and_b32 s38, s18, 3
	s_add_i32 s29, s29, 1
	s_add_i32 s36, s36, 64
	v_subrev_u32_e32 v216, 64, v216
	v_add_u32_e32 v217, 0x88000, v217
	v_add_u32_e32 v218, 0x88000, v218
	s_andn2_b64 vcc, exec, s[20:21]
	v_add_u32_e32 v219, 0x88000, v219
	s_waitcnt vmcnt(4) lgkmcnt(0)
	s_barrier
	s_cbranch_vccz .LBB0_1065

.LBB0_1073:
	s_or_b64 exec, exec, s[0:1]
	v_ashrrev_i32_e32 v2, 1, v2
	v_and_b32_e32 v8, 0xffffffe0, v2
	v_lshlrev_b32_e32 v0, 1, v0
	v_lshl_add_u64 v[6:7], s[8:9], 0, v[0:1]
	v_lshl_add_u64 v[2:3], s[10:11], 0, v[0:1]
	v_lshl_or_b32 v0, v4, 2, v8
	v_add_u32_e32 v8, s2, v0
	s_movk_i32 s21, 0x1a00
	s_waitcnt lgkmcnt(0)
	v_mul_lo_u32 v0, v8, s21
	v_lshl_add_u32 v90, v4, 4, v5
	ds_read_b128 v[80:83], v90
	ds_read_b128 v[98:101], v90 offset:32
	v_add_u32_e32 v4, 0x1a00, v0
	v_mov_b32_e32 v5, v1
	v_lshl_add_u64 v[10:11], v[4:5], 1, v[6:7]
	v_add_u32_e32 v4, 0x3400, v0
	v_lshl_add_u64 v[12:13], v[4:5], 1, v[6:7]
	v_add_u32_e32 v4, 0x4e00, v0
	v_lshl_add_u64 v[14:15], v[4:5], 1, v[6:7]
	v_add_u32_e32 v4, 0xd000, v0
	s_waitcnt lgkmcnt(1)
	v_rcp_f32_e32 v107, v80
	v_rcp_f32_e32 v102, v81
	v_lshl_add_u64 v[80:81], v[4:5], 1, v[6:7]
	v_add_u32_e32 v4, 0xea00, v0
	v_rcp_f32_e32 v97, v82
	v_rcp_f32_e32 v95, v83
	v_lshl_add_u64 v[82:83], v[4:5], 1, v[6:7]
	v_add_u32_e32 v4, 0x10400, v0
	v_lshl_add_u64 v[84:85], v[4:5], 1, v[6:7]
	v_add_u32_e32 v4, 0x11e00, v0
	s_movk_i32 s0, 0xa00
	v_lshl_add_u64 v[88:89], v[0:1], 1, v[6:7]
	v_lshl_add_u64 v[86:87], v[4:5], 1, v[6:7]
	v_mul_lo_u32 v4, v8, s0
	v_lshl_add_u64 v[8:9], v[4:5], 1, v[2:3]
	v_mul_f32_e32 v5, v64, v107
	global_load_ushort v211, v[88:89], off
	s_waitcnt lgkmcnt(0)
	v_rcp_f32_e32 v94, v98
	v_rcp_f32_e32 v93, v99
	v_rcp_f32_e32 v92, v100
	v_rcp_f32_e32 v91, v101
	v_mul_f32_e32 v48, v48, v107
	v_mul_f32_e32 v32, v32, v107
	v_mul_f32_e32 v16, v16, v107
	s_mov_b64 s[0:1], 0
	s_and_b64 vcc, exec, s[12:13]
	v_mov_b32_e32 v210, v5
	global_load_ushort v110, v[88:89], off offset:64
	global_load_ushort v111, v[88:89], off offset:128
	global_load_ushort v112, v[88:89], off offset:192
	global_load_ushort v113, v[10:11], off
	global_load_ushort v114, v[10:11], off offset:64
	global_load_ushort v115, v[10:11], off offset:128
	global_load_ushort v116, v[10:11], off offset:192
	global_load_ushort v117, v[12:13], off
	global_load_ushort v118, v[12:13], off offset:64
	global_load_ushort v108, v[12:13], off offset:128
	global_load_ushort v106, v[12:13], off offset:192
	global_load_ushort v105, v[14:15], off
	global_load_ushort v104, v[14:15], off offset:64
	global_load_ushort v103, v[14:15], off offset:128
	global_load_ushort v101, v[14:15], off offset:192
	global_load_ushort v100, v[80:81], off
	global_load_ushort v99, v[80:81], off offset:64
	global_load_ushort v98, v[80:81], off offset:128
	global_load_ushort v96, v[80:81], off offset:192
	global_load_ushort v89, v[82:83], off
	global_load_ushort v88, v[82:83], off offset:64
	s_nop 0
	global_load_ushort v81, v[82:83], off offset:128
	global_load_ushort v80, v[82:83], off offset:192
	global_load_ushort v64, v[84:85], off
	global_load_ushort v15, v[84:85], off offset:64
	global_load_ushort v14, v[84:85], off offset:128
	global_load_ushort v13, v[84:85], off offset:192
	global_load_ushort v12, v[86:87], off
	global_load_ushort v11, v[86:87], off offset:64
	global_load_ushort v10, v[86:87], off offset:128
	global_load_ushort v5, v[86:87], off offset:192
	s_waitcnt vmcnt(31)
	v_lshlrev_b32_e32 v211, 16, v211
	v_mul_f32_e32 v210, v210, v211
	v_mul_f32_e32 v211, 0xbfb8aa3b, v211
	v_exp_f32_e32 v211, v211
	s_nop 0
	v_add_f32_e32 v211, 1.0, v211
	v_rcp_f32_e32 v211, v211
	s_nop 0
	v_mul_f32_e32 v109, v210, v211
	v_cvt_pk_bf16_f32 v82, v109, v109
	global_store_short v[8:9], v82, off
	s_waitcnt vmcnt(31)
	v_lshlrev_b32_e32 v82, 16, v110
	v_mul_f32_e32 v48, v48, v82
	v_mul_f32_e32 v82, 0xbfb8aa3b, v82
	v_exp_f32_e32 v82, v82
	s_waitcnt vmcnt(7)
	v_lshlrev_b32_e32 v15, 16, v15
	v_add_f32_e32 v82, 1.0, v82
	v_rcp_f32_e32 v82, v82
	s_waitcnt vmcnt(6)
	v_lshlrev_b32_e32 v14, 16, v14
	s_waitcnt vmcnt(5)
	v_lshlrev_b32_e32 v13, 16, v13
	s_waitcnt vmcnt(4)
	v_lshlrev_b32_e32 v12, 16, v12
	v_mul_f32_e32 v48, v48, v82
	v_cvt_pk_bf16_f32 v48, v48, v48
	global_store_short v[8:9], v48, off offset:64
	v_lshlrev_b32_e32 v48, 16, v111
	v_mul_f32_e32 v32, v32, v48
	v_mul_f32_e32 v48, 0xbfb8aa3b, v48
	v_exp_f32_e32 v48, v48
	s_waitcnt vmcnt(4)
	v_lshlrev_b32_e32 v11, 16, v11
	s_waitcnt vmcnt(3)
	v_lshlrev_b32_e32 v10, 16, v10
	s_waitcnt vmcnt(2)
	v_lshlrev_b32_e32 v5, 16, v5
	v_add_f32_e32 v48, 1.0, v48
	v_rcp_f32_e32 v48, v48
	s_nop 0
	v_mul_f32_e32 v32, v32, v48
	v_cvt_pk_bf16_f32 v32, v32, v32
	global_store_short v[8:9], v32, off offset:128
	v_lshlrev_b32_e32 v32, 16, v112
	v_mul_f32_e32 v16, v16, v32
	v_mul_f32_e32 v32, 0xbfb8aa3b, v32
	v_exp_f32_e32 v32, v32
	s_nop 0
	v_add_f32_e32 v32, 1.0, v32
	v_rcp_f32_e32 v32, v32
	s_nop 0
	v_mul_f32_e32 v16, v16, v32
	v_cvt_pk_bf16_f32 v16, v16, v16
	global_store_short v[8:9], v16, off offset:192
	v_mul_f32_e32 v16, v65, v102
	v_lshlrev_b32_e32 v32, 16, v113
	v_mul_f32_e32 v16, v16, v32
	v_mul_f32_e32 v32, 0xbfb8aa3b, v32
	v_exp_f32_e32 v32, v32
	v_add_u32_e32 v8, 0xa00, v4
	v_mov_b32_e32 v9, v1
	v_lshl_add_u64 v[8:9], v[8:9], 1, v[2:3]
	v_add_f32_e32 v32, 1.0, v32
	v_rcp_f32_e32 v32, v32
	s_nop 0
	v_mul_f32_e32 v16, v16, v32
	v_cvt_pk_bf16_f32 v16, v16, v16
	global_store_short v[8:9], v16, off
	v_mul_f32_e32 v16, v49, v102
	v_lshlrev_b32_e32 v32, 16, v114
	v_mul_f32_e32 v16, v16, v32
	v_mul_f32_e32 v32, 0xbfb8aa3b, v32
	v_exp_f32_e32 v32, v32
	s_nop 0
	v_add_f32_e32 v32, 1.0, v32
	v_rcp_f32_e32 v32, v32
	s_nop 0
	v_mul_f32_e32 v16, v16, v32
	v_cvt_pk_bf16_f32 v16, v16, v16
	global_store_short v[8:9], v16, off offset:64
	v_mul_f32_e32 v16, v33, v102
	v_lshlrev_b32_e32 v32, 16, v115
	v_mul_f32_e32 v16, v16, v32
	v_mul_f32_e32 v32, 0xbfb8aa3b, v32
	v_exp_f32_e32 v32, v32
	s_nop 0
	v_add_f32_e32 v32, 1.0, v32
	v_rcp_f32_e32 v32, v32
	s_nop 0
	v_mul_f32_e32 v16, v16, v32
	v_cvt_pk_bf16_f32 v16, v16, v16
	global_store_short v[8:9], v16, off offset:128
	v_mul_f32_e32 v16, v17, v102
	v_lshlrev_b32_e32 v17, 16, v116
	v_mul_f32_e32 v16, v16, v17
	v_mul_f32_e32 v17, 0xbfb8aa3b, v17
	v_exp_f32_e32 v17, v17
	s_nop 0
	v_add_f32_e32 v17, 1.0, v17
	v_rcp_f32_e32 v17, v17
	s_nop 0
	v_mul_f32_e32 v16, v16, v17
	v_cvt_pk_bf16_f32 v16, v16, v16
	global_store_short v[8:9], v16, off offset:192
	v_mul_f32_e32 v16, v66, v97
	v_lshlrev_b32_e32 v17, 16, v117
	v_mul_f32_e32 v16, v16, v17
	v_mul_f32_e32 v17, 0xbfb8aa3b, v17
	v_exp_f32_e32 v17, v17
	v_add_u32_e32 v8, 0x1400, v4
	v_mov_b32_e32 v9, v1
	v_lshl_add_u64 v[8:9], v[8:9], 1, v[2:3]
	v_add_f32_e32 v17, 1.0, v17
	v_rcp_f32_e32 v17, v17
	s_nop 0
	v_mul_f32_e32 v16, v16, v17
	v_cvt_pk_bf16_f32 v16, v16, v16
	global_store_short v[8:9], v16, off
	v_mul_f32_e32 v16, v50, v97
	v_lshlrev_b32_e32 v17, 16, v118
	v_mul_f32_e32 v16, v16, v17
	v_mul_f32_e32 v17, 0xbfb8aa3b, v17
	v_exp_f32_e32 v17, v17
	s_nop 0
	v_add_f32_e32 v17, 1.0, v17
	v_rcp_f32_e32 v17, v17
	s_nop 0
	v_mul_f32_e32 v16, v16, v17
	v_cvt_pk_bf16_f32 v16, v16, v16
	global_store_short v[8:9], v16, off offset:64
	v_mul_f32_e32 v16, v34, v97
	v_lshlrev_b32_e32 v17, 16, v108
	v_mul_f32_e32 v16, v16, v17
	v_mul_f32_e32 v17, 0xbfb8aa3b, v17
	v_exp_f32_e32 v17, v17
	s_nop 0
	v_add_f32_e32 v17, 1.0, v17
	v_rcp_f32_e32 v17, v17
	s_nop 0
	v_mul_f32_e32 v16, v16, v17
	v_cvt_pk_bf16_f32 v16, v16, v16
	global_store_short v[8:9], v16, off offset:128
	v_mul_f32_e32 v16, v18, v97
	v_lshlrev_b32_e32 v17, 16, v106
	v_mul_f32_e32 v16, v16, v17
	v_mul_f32_e32 v17, 0xbfb8aa3b, v17
	v_exp_f32_e32 v17, v17
	s_nop 0
	v_add_f32_e32 v17, 1.0, v17
	v_rcp_f32_e32 v17, v17
	s_nop 0
	v_mul_f32_e32 v16, v16, v17
	v_cvt_pk_bf16_f32 v16, v16, v16
	global_store_short v[8:9], v16, off offset:192
	v_mul_f32_e32 v16, v67, v95
	v_lshlrev_b32_e32 v17, 16, v105
	v_mul_f32_e32 v16, v16, v17
	v_mul_f32_e32 v17, 0xbfb8aa3b, v17
	v_exp_f32_e32 v17, v17
	v_add_u32_e32 v8, 0x1e00, v4
	v_mov_b32_e32 v9, v1
	v_lshl_add_u64 v[8:9], v[8:9], 1, v[2:3]
	v_add_f32_e32 v17, 1.0, v17
	v_rcp_f32_e32 v17, v17
	s_nop 0
	v_mul_f32_e32 v16, v16, v17
	v_cvt_pk_bf16_f32 v16, v16, v16
	global_store_short v[8:9], v16, off
	v_mul_f32_e32 v16, v51, v95
	v_lshlrev_b32_e32 v17, 16, v104
	v_mul_f32_e32 v16, v16, v17
	v_mul_f32_e32 v17, 0xbfb8aa3b, v17
	v_exp_f32_e32 v17, v17
	s_nop 0
	v_add_f32_e32 v17, 1.0, v17
	v_rcp_f32_e32 v17, v17
	s_nop 0
	v_mul_f32_e32 v16, v16, v17
	v_cvt_pk_bf16_f32 v16, v16, v16
	global_store_short v[8:9], v16, off offset:64
	v_mul_f32_e32 v16, v35, v95
	v_lshlrev_b32_e32 v17, 16, v103
	v_mul_f32_e32 v16, v16, v17
	v_mul_f32_e32 v17, 0xbfb8aa3b, v17
	v_exp_f32_e32 v17, v17
	s_nop 0
	v_add_f32_e32 v17, 1.0, v17
	v_rcp_f32_e32 v17, v17
	s_nop 0
	v_mul_f32_e32 v16, v16, v17
	v_cvt_pk_bf16_f32 v16, v16, v16
	global_store_short v[8:9], v16, off offset:128
	v_mul_f32_e32 v16, v19, v95
	v_lshlrev_b32_e32 v17, 16, v101
	v_mul_f32_e32 v16, v16, v17
	v_mul_f32_e32 v17, 0xbfb8aa3b, v17
	v_exp_f32_e32 v17, v17
	s_nop 0
	v_add_f32_e32 v17, 1.0, v17
	v_rcp_f32_e32 v17, v17
	s_nop 0
	v_mul_f32_e32 v16, v16, v17
	v_cvt_pk_bf16_f32 v16, v16, v16
	global_store_short v[8:9], v16, off offset:192
	v_mul_f32_e32 v16, v68, v94
	v_lshlrev_b32_e32 v17, 16, v100
	v_mul_f32_e32 v16, v16, v17
	v_mul_f32_e32 v17, 0xbfb8aa3b, v17
	v_exp_f32_e32 v17, v17
	v_add_u32_e32 v8, 0x5000, v4
	v_mov_b32_e32 v9, v1
	v_lshl_add_u64 v[8:9], v[8:9], 1, v[2:3]
	v_add_f32_e32 v17, 1.0, v17
	v_rcp_f32_e32 v17, v17
	s_nop 0
	v_mul_f32_e32 v16, v16, v17
	v_cvt_pk_bf16_f32 v16, v16, v16
	global_store_short v[8:9], v16, off
	v_mul_f32_e32 v16, v52, v94
	v_lshlrev_b32_e32 v17, 16, v99
	v_mul_f32_e32 v16, v16, v17
	v_mul_f32_e32 v17, 0xbfb8aa3b, v17
	v_exp_f32_e32 v17, v17
	s_nop 0
	v_add_f32_e32 v17, 1.0, v17
	v_rcp_f32_e32 v17, v17
	s_nop 0
	v_mul_f32_e32 v16, v16, v17
	v_cvt_pk_bf16_f32 v16, v16, v16
	global_store_short v[8:9], v16, off offset:64
	v_mul_f32_e32 v16, v36, v94
	v_lshlrev_b32_e32 v17, 16, v98
	v_mul_f32_e32 v16, v16, v17
	v_mul_f32_e32 v17, 0xbfb8aa3b, v17
	v_exp_f32_e32 v17, v17
	s_nop 0
	v_add_f32_e32 v17, 1.0, v17
	v_rcp_f32_e32 v17, v17
	s_nop 0
	v_mul_f32_e32 v16, v16, v17
	v_cvt_pk_bf16_f32 v16, v16, v16
	global_store_short v[8:9], v16, off offset:128
	v_mul_f32_e32 v16, v20, v94
	v_lshlrev_b32_e32 v17, 16, v96
	v_mul_f32_e32 v16, v16, v17
	v_mul_f32_e32 v17, 0xbfb8aa3b, v17
	v_exp_f32_e32 v17, v17
	s_nop 0
	v_add_f32_e32 v17, 1.0, v17
	v_rcp_f32_e32 v17, v17
	s_nop 0
	v_mul_f32_e32 v16, v16, v17
	v_cvt_pk_bf16_f32 v16, v16, v16
	global_store_short v[8:9], v16, off offset:192
	v_mul_f32_e32 v16, v69, v93
	v_lshlrev_b32_e32 v17, 16, v89
	v_mul_f32_e32 v16, v16, v17
	v_mul_f32_e32 v17, 0xbfb8aa3b, v17
	v_exp_f32_e32 v17, v17
	v_add_u32_e32 v8, 0x5a00, v4
	v_mov_b32_e32 v9, v1
	v_lshl_add_u64 v[8:9], v[8:9], 1, v[2:3]
	v_add_f32_e32 v17, 1.0, v17
	v_rcp_f32_e32 v17, v17
	s_nop 0
	v_mul_f32_e32 v16, v16, v17
	v_cvt_pk_bf16_f32 v16, v16, v16
	global_store_short v[8:9], v16, off
	v_mul_f32_e32 v16, v53, v93
	v_lshlrev_b32_e32 v17, 16, v88
	v_mul_f32_e32 v16, v16, v17
	v_mul_f32_e32 v17, 0xbfb8aa3b, v17
	v_exp_f32_e32 v17, v17
	s_nop 0
	v_add_f32_e32 v17, 1.0, v17
	v_rcp_f32_e32 v17, v17
	s_nop 0
	v_mul_f32_e32 v16, v16, v17
	v_cvt_pk_bf16_f32 v16, v16, v16
	global_store_short v[8:9], v16, off offset:64
	v_mul_f32_e32 v16, v37, v93
	v_lshlrev_b32_e32 v17, 16, v81
	v_mul_f32_e32 v16, v16, v17
	v_mul_f32_e32 v17, 0xbfb8aa3b, v17
	v_exp_f32_e32 v17, v17
	s_nop 0
	v_add_f32_e32 v17, 1.0, v17
	v_rcp_f32_e32 v17, v17
	s_nop 0
	v_mul_f32_e32 v16, v16, v17
	v_cvt_pk_bf16_f32 v16, v16, v16
	global_store_short v[8:9], v16, off offset:128
	v_mul_f32_e32 v16, v21, v93
	v_lshlrev_b32_e32 v17, 16, v80
	v_mul_f32_e32 v16, v16, v17
	v_mul_f32_e32 v17, 0xbfb8aa3b, v17
	v_exp_f32_e32 v17, v17
	s_nop 0
	v_add_f32_e32 v17, 1.0, v17
	v_rcp_f32_e32 v17, v17
	s_nop 0
	v_mul_f32_e32 v16, v16, v17
	v_cvt_pk_bf16_f32 v16, v16, v16
	global_store_short v[8:9], v16, off offset:192
	v_mul_f32_e32 v16, v70, v92
	v_lshlrev_b32_e32 v17, 16, v64
	v_mul_f32_e32 v16, v16, v17
	v_mul_f32_e32 v17, 0xbfb8aa3b, v17
	v_exp_f32_e32 v17, v17
	v_add_u32_e32 v8, 0x6400, v4
	v_mov_b32_e32 v9, v1
	v_lshl_add_u64 v[8:9], v[8:9], 1, v[2:3]
	v_add_f32_e32 v17, 1.0, v17
	v_rcp_f32_e32 v17, v17
	s_nop 0
	v_mul_f32_e32 v16, v16, v17
	v_cvt_pk_bf16_f32 v16, v16, v16
	global_store_short v[8:9], v16, off
	v_mul_f32_e32 v16, v54, v92
	v_mul_f32_e32 v16, v16, v15
	v_mul_f32_e32 v15, 0xbfb8aa3b, v15
	v_exp_f32_e32 v15, v15
	s_nop 0
	v_add_f32_e32 v15, 1.0, v15
	v_rcp_f32_e32 v15, v15
	s_nop 0
	v_mul_f32_e32 v15, v16, v15
	v_cvt_pk_bf16_f32 v15, v15, v15
	global_store_short v[8:9], v15, off offset:64
	v_mul_f32_e32 v15, v38, v92
	v_mul_f32_e32 v15, v15, v14
	v_mul_f32_e32 v14, 0xbfb8aa3b, v14
	v_exp_f32_e32 v14, v14
	s_nop 0
	v_add_f32_e32 v14, 1.0, v14
	v_rcp_f32_e32 v14, v14
	s_nop 0
	v_mul_f32_e32 v14, v15, v14
	v_cvt_pk_bf16_f32 v14, v14, v14
	global_store_short v[8:9], v14, off offset:128
	v_mul_f32_e32 v14, v22, v92
	v_mul_f32_e32 v14, v14, v13
	v_mul_f32_e32 v13, 0xbfb8aa3b, v13
	v_exp_f32_e32 v13, v13
	s_nop 0
	v_add_f32_e32 v13, 1.0, v13
	v_rcp_f32_e32 v13, v13
	s_nop 0
	v_mul_f32_e32 v13, v14, v13
	v_cvt_pk_bf16_f32 v13, v13, v13
	global_store_short v[8:9], v13, off offset:192
	v_mul_f32_e32 v13, v71, v91
	v_mul_f32_e32 v13, v13, v12
	v_mul_f32_e32 v12, 0xbfb8aa3b, v12
	v_exp_f32_e32 v12, v12
	v_add_u32_e32 v8, 0x6e00, v4
	v_mov_b32_e32 v9, v1
	v_lshl_add_u64 v[8:9], v[8:9], 1, v[2:3]
	v_add_f32_e32 v12, 1.0, v12
	v_rcp_f32_e32 v12, v12
	s_nop 0
	v_mul_f32_e32 v12, v13, v12
	v_cvt_pk_bf16_f32 v12, v12, v12
	global_store_short v[8:9], v12, off
	v_mul_f32_e32 v12, v55, v91
	v_mul_f32_e32 v12, v12, v11
	v_mul_f32_e32 v11, 0xbfb8aa3b, v11
	v_exp_f32_e32 v11, v11
	s_nop 0
	v_add_f32_e32 v11, 1.0, v11
	v_rcp_f32_e32 v11, v11
	s_nop 0
	v_mul_f32_e32 v11, v12, v11
	v_cvt_pk_bf16_f32 v11, v11, v11
	global_store_short v[8:9], v11, off offset:64
	v_mul_f32_e32 v11, v39, v91
	v_mul_f32_e32 v11, v11, v10
	v_mul_f32_e32 v10, 0xbfb8aa3b, v10
	v_exp_f32_e32 v10, v10
	s_nop 0
	v_add_f32_e32 v10, 1.0, v10
	v_rcp_f32_e32 v10, v10
	s_nop 0
	v_mul_f32_e32 v10, v11, v10
	v_cvt_pk_bf16_f32 v10, v10, v10
	global_store_short v[8:9], v10, off offset:128
	v_mul_f32_e32 v10, v23, v91
	v_mul_f32_e32 v10, v10, v5
	v_mul_f32_e32 v5, 0xbfb8aa3b, v5
	v_exp_f32_e32 v5, v5
	s_nop 0
	v_add_f32_e32 v5, 1.0, v5
	v_rcp_f32_e32 v5, v5
	s_nop 0
	v_mul_f32_e32 v5, v10, v5
	v_cvt_pk_bf16_f32 v5, v5, v5
	global_store_short v[8:9], v5, off offset:192
	v_add_u32_e32 v8, 0x1a000, v0
	v_mov_b32_e32 v9, v1
	v_lshl_add_u64 v[34:35], v[8:9], 1, v[6:7]
	ds_read_b128 v[12:15], v90 offset:64
	ds_read_b128 v[50:53], v90 offset:96
	global_load_ushort v210, v[34:35], off
	v_add_u32_e32 v8, 0x1ba00, v0
	v_lshl_add_u64 v[20:21], v[8:9], 1, v[6:7]
	v_add_u32_e32 v8, 0x1d400, v0
	v_lshl_add_u64 v[10:11], v[8:9], 1, v[6:7]
	v_add_u32_e32 v8, 0x1ee00, v0
	s_waitcnt lgkmcnt(1)
	v_rcp_f32_e32 v54, v12
	v_rcp_f32_e32 v49, v13
	v_lshl_add_u64 v[12:13], v[8:9], 1, v[6:7]
	v_add_u32_e32 v8, 0x27000, v0
	v_rcp_f32_e32 v36, v14
	v_rcp_f32_e32 v33, v15
	v_lshl_add_u64 v[14:15], v[8:9], 1, v[6:7]
	v_add_u32_e32 v8, 0x28a00, v0
	v_lshl_add_u64 v[16:17], v[8:9], 1, v[6:7]
	v_add_u32_e32 v8, 0x2a400, v0
	v_add_u32_e32 v0, 0x2be00, v0
	v_lshl_add_u64 v[18:19], v[8:9], 1, v[6:7]
	v_lshl_add_u64 v[8:9], v[0:1], 1, v[6:7]
	v_add_u32_e32 v0, 0xa000, v4
	v_lshl_add_u64 v[6:7], v[0:1], 1, v[2:3]
	v_mul_f32_e32 v0, v72, v54
	s_waitcnt lgkmcnt(0)
	v_rcp_f32_e32 v32, v50
	v_rcp_f32_e32 v23, v51
	v_rcp_f32_e32 v22, v52
	v_rcp_f32_e32 v5, v53
	global_load_ushort v64, v[34:35], off offset:64
	global_load_ushort v65, v[34:35], off offset:128
	global_load_ushort v66, v[34:35], off offset:192
	global_load_ushort v67, v[20:21], off
	global_load_ushort v68, v[20:21], off offset:64
	global_load_ushort v69, v[20:21], off offset:128
	global_load_ushort v70, v[20:21], off offset:192
	global_load_ushort v71, v[10:11], off
	global_load_ushort v72, v[10:11], off offset:64
	global_load_ushort v55, v[10:11], off offset:128
	global_load_ushort v53, v[10:11], off offset:192
	global_load_ushort v52, v[12:13], off
	global_load_ushort v51, v[12:13], off offset:64
	global_load_ushort v50, v[12:13], off offset:128
	global_load_ushort v48, v[12:13], off offset:192
	global_load_ushort v39, v[14:15], off
	global_load_ushort v38, v[14:15], off offset:64
	global_load_ushort v37, v[14:15], off offset:128
	global_load_ushort v35, v[14:15], off offset:192
	global_load_ushort v34, v[16:17], off
	global_load_ushort v21, v[16:17], off offset:64
	global_load_ushort v20, v[16:17], off offset:128
	s_nop 0
	global_load_ushort v17, v[16:17], off offset:192
	s_nop 0
	global_load_ushort v16, v[18:19], off
	global_load_ushort v15, v[18:19], off offset:64
	global_load_ushort v14, v[18:19], off offset:128
	global_load_ushort v13, v[18:19], off offset:192
	global_load_ushort v12, v[8:9], off
	global_load_ushort v11, v[8:9], off offset:64
	global_load_ushort v10, v[8:9], off offset:128
	s_nop 0
	global_load_ushort v8, v[8:9], off offset:192
	s_waitcnt vmcnt(31)
	v_lshlrev_b32_e32 v210, 16, v210
	v_mul_f32_e32 v0, v0, v210
	v_mul_f32_e32 v210, 0xbfb8aa3b, v210
	v_exp_f32_e32 v210, v210
	s_nop 0
	v_add_f32_e32 v210, 1.0, v210
	v_rcp_f32_e32 v210, v210
	s_nop 0
	v_mul_f32_e32 v0, v0, v210
	v_cvt_pk_bf16_f32 v0, v0, v0
	global_store_short v[6:7], v0, off
	v_mul_f32_e32 v0, v56, v54
	s_waitcnt vmcnt(31)
	v_lshlrev_b32_e32 v9, 16, v64
	v_mul_f32_e32 v0, v0, v9
	v_mul_f32_e32 v9, 0xbfb8aa3b, v9
	v_exp_f32_e32 v9, v9
	s_nop 0
	v_add_f32_e32 v9, 1.0, v9
	v_rcp_f32_e32 v9, v9
	s_nop 0
	v_mul_f32_e32 v0, v0, v9
	v_cvt_pk_bf16_f32 v0, v0, v0
	global_store_short v[6:7], v0, off offset:64
	v_mul_f32_e32 v0, v40, v54
	s_waitcnt vmcnt(31)
	v_lshlrev_b32_e32 v9, 16, v65
	v_mul_f32_e32 v0, v0, v9
	v_mul_f32_e32 v9, 0xbfb8aa3b, v9
	v_exp_f32_e32 v9, v9
	s_nop 0
	v_add_f32_e32 v9, 1.0, v9
	v_rcp_f32_e32 v9, v9
	s_nop 0
	v_mul_f32_e32 v0, v0, v9
	v_cvt_pk_bf16_f32 v0, v0, v0
	global_store_short v[6:7], v0, off offset:128
	v_mul_f32_e32 v0, v24, v54
	s_waitcnt vmcnt(31)
	v_lshlrev_b32_e32 v9, 16, v66
	v_mul_f32_e32 v0, v0, v9
	v_mul_f32_e32 v9, 0xbfb8aa3b, v9
	v_exp_f32_e32 v9, v9
	s_nop 0
	v_add_f32_e32 v9, 1.0, v9
	v_rcp_f32_e32 v9, v9
	s_nop 0
	v_mul_f32_e32 v0, v0, v9
	v_cvt_pk_bf16_f32 v0, v0, v0
	global_store_short v[6:7], v0, off offset:192
	v_add_u32_e32 v0, 0xaa00, v4
	v_lshl_add_u64 v[6:7], v[0:1], 1, v[2:3]
	v_mul_f32_e32 v0, v73, v49
	s_waitcnt vmcnt(31)
	v_lshlrev_b32_e32 v9, 16, v67
	v_mul_f32_e32 v0, v0, v9
	v_mul_f32_e32 v9, 0xbfb8aa3b, v9
	v_exp_f32_e32 v9, v9
	s_nop 0
	v_add_f32_e32 v9, 1.0, v9
	v_rcp_f32_e32 v9, v9
	s_nop 0
	v_mul_f32_e32 v0, v0, v9
	v_cvt_pk_bf16_f32 v0, v0, v0
	global_store_short v[6:7], v0, off
	v_mul_f32_e32 v0, v57, v49
	s_waitcnt vmcnt(31)
	v_lshlrev_b32_e32 v9, 16, v68
	v_mul_f32_e32 v0, v0, v9
	v_mul_f32_e32 v9, 0xbfb8aa3b, v9
	v_exp_f32_e32 v9, v9
	s_nop 0
	v_add_f32_e32 v9, 1.0, v9
	v_rcp_f32_e32 v9, v9
	s_nop 0
	v_mul_f32_e32 v0, v0, v9
	v_cvt_pk_bf16_f32 v0, v0, v0
	global_store_short v[6:7], v0, off offset:64
	v_mul_f32_e32 v0, v41, v49
	s_waitcnt vmcnt(31)
	v_lshlrev_b32_e32 v9, 16, v69
	v_mul_f32_e32 v0, v0, v9
	v_mul_f32_e32 v9, 0xbfb8aa3b, v9
	v_exp_f32_e32 v9, v9
	s_nop 0
	v_add_f32_e32 v9, 1.0, v9
	v_rcp_f32_e32 v9, v9
	s_nop 0
	v_mul_f32_e32 v0, v0, v9
	v_cvt_pk_bf16_f32 v0, v0, v0
	global_store_short v[6:7], v0, off offset:128
	v_mul_f32_e32 v0, v25, v49
	s_waitcnt vmcnt(31)
	v_lshlrev_b32_e32 v9, 16, v70
	v_mul_f32_e32 v0, v0, v9
	v_mul_f32_e32 v9, 0xbfb8aa3b, v9
	v_exp_f32_e32 v9, v9
	s_nop 0
	v_add_f32_e32 v9, 1.0, v9
	v_rcp_f32_e32 v9, v9
	s_nop 0
	v_mul_f32_e32 v0, v0, v9
	v_cvt_pk_bf16_f32 v0, v0, v0
	global_store_short v[6:7], v0, off offset:192
	v_add_u32_e32 v0, 0xb400, v4
	v_lshl_add_u64 v[6:7], v[0:1], 1, v[2:3]
	v_mul_f32_e32 v0, v74, v36
	s_waitcnt vmcnt(31)
	v_lshlrev_b32_e32 v9, 16, v71
	v_mul_f32_e32 v0, v0, v9
	v_mul_f32_e32 v9, 0xbfb8aa3b, v9
	v_exp_f32_e32 v9, v9
	s_nop 0
	v_add_f32_e32 v9, 1.0, v9
	v_rcp_f32_e32 v9, v9
	s_nop 0
	v_mul_f32_e32 v0, v0, v9
	v_cvt_pk_bf16_f32 v0, v0, v0
	global_store_short v[6:7], v0, off
	v_mul_f32_e32 v0, v58, v36
	s_waitcnt vmcnt(31)
	v_lshlrev_b32_e32 v9, 16, v72
	v_mul_f32_e32 v0, v0, v9
	v_mul_f32_e32 v9, 0xbfb8aa3b, v9
	v_exp_f32_e32 v9, v9
	s_nop 0
	v_add_f32_e32 v9, 1.0, v9
	v_rcp_f32_e32 v9, v9
	s_nop 0
	v_mul_f32_e32 v0, v0, v9
	v_cvt_pk_bf16_f32 v0, v0, v0
	global_store_short v[6:7], v0, off offset:64
	v_mul_f32_e32 v0, v42, v36
	s_waitcnt vmcnt(31)
	v_lshlrev_b32_e32 v9, 16, v55
	v_mul_f32_e32 v0, v0, v9
	v_mul_f32_e32 v9, 0xbfb8aa3b, v9
	v_exp_f32_e32 v9, v9
	s_nop 0
	v_add_f32_e32 v9, 1.0, v9
	v_rcp_f32_e32 v9, v9
	s_nop 0
	v_mul_f32_e32 v0, v0, v9
	v_cvt_pk_bf16_f32 v0, v0, v0
	global_store_short v[6:7], v0, off offset:128
	v_mul_f32_e32 v0, v26, v36
	s_waitcnt vmcnt(31)
	v_lshlrev_b32_e32 v9, 16, v53
	v_mul_f32_e32 v0, v0, v9
	v_mul_f32_e32 v9, 0xbfb8aa3b, v9
	v_exp_f32_e32 v9, v9
	s_nop 0
	v_add_f32_e32 v9, 1.0, v9
	v_rcp_f32_e32 v9, v9
	s_nop 0
	v_mul_f32_e32 v0, v0, v9
	v_cvt_pk_bf16_f32 v0, v0, v0
	global_store_short v[6:7], v0, off offset:192
	v_add_u32_e32 v0, 0xbe00, v4
	v_lshl_add_u64 v[6:7], v[0:1], 1, v[2:3]
	v_mul_f32_e32 v0, v75, v33
	s_waitcnt vmcnt(31)
	v_lshlrev_b32_e32 v9, 16, v52
	v_mul_f32_e32 v0, v0, v9
	v_mul_f32_e32 v9, 0xbfb8aa3b, v9
	v_exp_f32_e32 v9, v9
	s_nop 0
	v_add_f32_e32 v9, 1.0, v9
	v_rcp_f32_e32 v9, v9
	s_nop 0
	v_mul_f32_e32 v0, v0, v9
	v_cvt_pk_bf16_f32 v0, v0, v0
	global_store_short v[6:7], v0, off
	v_mul_f32_e32 v0, v59, v33
	s_waitcnt vmcnt(31)
	v_lshlrev_b32_e32 v9, 16, v51
	v_mul_f32_e32 v0, v0, v9
	v_mul_f32_e32 v9, 0xbfb8aa3b, v9
	v_exp_f32_e32 v9, v9
	s_nop 0
	v_add_f32_e32 v9, 1.0, v9
	v_rcp_f32_e32 v9, v9
	s_nop 0
	v_mul_f32_e32 v0, v0, v9
	v_cvt_pk_bf16_f32 v0, v0, v0
	global_store_short v[6:7], v0, off offset:64
	v_mul_f32_e32 v0, v43, v33
	s_waitcnt vmcnt(31)
	v_lshlrev_b32_e32 v9, 16, v50
	v_mul_f32_e32 v0, v0, v9
	v_mul_f32_e32 v9, 0xbfb8aa3b, v9
	v_exp_f32_e32 v9, v9
	s_nop 0
	v_add_f32_e32 v9, 1.0, v9
	v_rcp_f32_e32 v9, v9
	s_nop 0
	v_mul_f32_e32 v0, v0, v9
	v_cvt_pk_bf16_f32 v0, v0, v0
	global_store_short v[6:7], v0, off offset:128
	v_mul_f32_e32 v0, v27, v33
	s_waitcnt vmcnt(31)
	v_lshlrev_b32_e32 v9, 16, v48
	v_mul_f32_e32 v0, v0, v9
	v_mul_f32_e32 v9, 0xbfb8aa3b, v9
	v_exp_f32_e32 v9, v9
	s_nop 0
	v_add_f32_e32 v9, 1.0, v9
	v_rcp_f32_e32 v9, v9
	s_nop 0
	v_mul_f32_e32 v0, v0, v9
	v_cvt_pk_bf16_f32 v0, v0, v0
	global_store_short v[6:7], v0, off offset:192
	v_add_u32_e32 v0, 0xf000, v4
	v_lshl_add_u64 v[6:7], v[0:1], 1, v[2:3]
	v_mul_f32_e32 v0, v76, v32
	s_waitcnt vmcnt(31)
	v_lshlrev_b32_e32 v9, 16, v39
	v_mul_f32_e32 v0, v0, v9
	v_mul_f32_e32 v9, 0xbfb8aa3b, v9
	v_exp_f32_e32 v9, v9
	s_nop 0
	v_add_f32_e32 v9, 1.0, v9
	v_rcp_f32_e32 v9, v9
	s_nop 0
	v_mul_f32_e32 v0, v0, v9
	v_cvt_pk_bf16_f32 v0, v0, v0
	global_store_short v[6:7], v0, off
	v_mul_f32_e32 v0, v60, v32
	s_waitcnt vmcnt(31)
	v_lshlrev_b32_e32 v9, 16, v38
	v_mul_f32_e32 v0, v0, v9
	v_mul_f32_e32 v9, 0xbfb8aa3b, v9
	v_exp_f32_e32 v9, v9
	s_nop 0
	v_add_f32_e32 v9, 1.0, v9
	v_rcp_f32_e32 v9, v9
	s_nop 0
	v_mul_f32_e32 v0, v0, v9
	v_cvt_pk_bf16_f32 v0, v0, v0
	global_store_short v[6:7], v0, off offset:64
	v_mul_f32_e32 v0, v44, v32
	s_waitcnt vmcnt(31)
	v_lshlrev_b32_e32 v9, 16, v37
	v_mul_f32_e32 v0, v0, v9
	v_mul_f32_e32 v9, 0xbfb8aa3b, v9
	v_exp_f32_e32 v9, v9
	s_nop 0
	v_add_f32_e32 v9, 1.0, v9
	v_rcp_f32_e32 v9, v9
	s_nop 0
	v_mul_f32_e32 v0, v0, v9
	v_cvt_pk_bf16_f32 v0, v0, v0
	global_store_short v[6:7], v0, off offset:128
	v_mul_f32_e32 v0, v28, v32
	s_waitcnt vmcnt(31)
	v_lshlrev_b32_e32 v9, 16, v35
	v_mul_f32_e32 v0, v0, v9
	v_mul_f32_e32 v9, 0xbfb8aa3b, v9
	v_exp_f32_e32 v9, v9
	s_nop 0
	v_add_f32_e32 v9, 1.0, v9
	v_rcp_f32_e32 v9, v9
	s_nop 0
	v_mul_f32_e32 v0, v0, v9
	v_cvt_pk_bf16_f32 v0, v0, v0
	global_store_short v[6:7], v0, off offset:192
	v_add_u32_e32 v0, 0xfa00, v4
	v_lshl_add_u64 v[6:7], v[0:1], 1, v[2:3]
	v_mul_f32_e32 v0, v77, v23
	s_waitcnt vmcnt(31)
	v_lshlrev_b32_e32 v9, 16, v34
	v_mul_f32_e32 v0, v0, v9
	v_mul_f32_e32 v9, 0xbfb8aa3b, v9
	v_exp_f32_e32 v9, v9
	s_nop 0
	v_add_f32_e32 v9, 1.0, v9
	v_rcp_f32_e32 v9, v9
	s_nop 0
	v_mul_f32_e32 v0, v0, v9
	v_cvt_pk_bf16_f32 v0, v0, v0
	global_store_short v[6:7], v0, off
	v_mul_f32_e32 v0, v61, v23
	s_waitcnt vmcnt(31)
	v_lshlrev_b32_e32 v9, 16, v21
	v_mul_f32_e32 v0, v0, v9
	v_mul_f32_e32 v9, 0xbfb8aa3b, v9
	v_exp_f32_e32 v9, v9
	s_nop 0
	v_add_f32_e32 v9, 1.0, v9
	v_rcp_f32_e32 v9, v9
	s_nop 0
	v_mul_f32_e32 v0, v0, v9
	v_cvt_pk_bf16_f32 v0, v0, v0
	global_store_short v[6:7], v0, off offset:64
	v_mul_f32_e32 v0, v45, v23
	s_waitcnt vmcnt(31)
	v_lshlrev_b32_e32 v9, 16, v20
	v_mul_f32_e32 v0, v0, v9
	v_mul_f32_e32 v9, 0xbfb8aa3b, v9
	v_exp_f32_e32 v9, v9
	s_nop 0
	v_add_f32_e32 v9, 1.0, v9
	v_rcp_f32_e32 v9, v9
	s_nop 0
	v_mul_f32_e32 v0, v0, v9
	v_cvt_pk_bf16_f32 v0, v0, v0
	global_store_short v[6:7], v0, off offset:128
	v_mul_f32_e32 v0, v29, v23
	s_waitcnt vmcnt(31)
	v_lshlrev_b32_e32 v9, 16, v17
	v_mul_f32_e32 v0, v0, v9
	v_mul_f32_e32 v9, 0xbfb8aa3b, v9
	v_exp_f32_e32 v9, v9
	s_nop 0
	v_add_f32_e32 v9, 1.0, v9
	v_rcp_f32_e32 v9, v9
	s_nop 0
	v_mul_f32_e32 v0, v0, v9
	v_cvt_pk_bf16_f32 v0, v0, v0
	global_store_short v[6:7], v0, off offset:192
	v_add_u32_e32 v0, 0x10400, v4
	v_lshl_add_u64 v[6:7], v[0:1], 1, v[2:3]
	v_mul_f32_e32 v0, v78, v22
	s_waitcnt vmcnt(31)
	v_lshlrev_b32_e32 v9, 16, v16
	v_mul_f32_e32 v0, v0, v9
	v_mul_f32_e32 v9, 0xbfb8aa3b, v9
	v_exp_f32_e32 v9, v9
	s_nop 0
	v_add_f32_e32 v9, 1.0, v9
	v_rcp_f32_e32 v9, v9
	s_nop 0
	v_mul_f32_e32 v0, v0, v9
	v_cvt_pk_bf16_f32 v0, v0, v0
	global_store_short v[6:7], v0, off
	v_mul_f32_e32 v0, v62, v22
	s_waitcnt vmcnt(31)
	v_lshlrev_b32_e32 v9, 16, v15
	v_mul_f32_e32 v0, v0, v9
	v_mul_f32_e32 v9, 0xbfb8aa3b, v9
	v_exp_f32_e32 v9, v9
	s_nop 0
	v_add_f32_e32 v9, 1.0, v9
	v_rcp_f32_e32 v9, v9
	s_nop 0
	v_mul_f32_e32 v0, v0, v9
	v_cvt_pk_bf16_f32 v0, v0, v0
	global_store_short v[6:7], v0, off offset:64
	v_mul_f32_e32 v0, v46, v22
	s_waitcnt vmcnt(31)
	v_lshlrev_b32_e32 v9, 16, v14
	v_mul_f32_e32 v0, v0, v9
	v_mul_f32_e32 v9, 0xbfb8aa3b, v9
	v_exp_f32_e32 v9, v9
	s_nop 0
	v_add_f32_e32 v9, 1.0, v9
	v_rcp_f32_e32 v9, v9
	s_nop 0
	v_mul_f32_e32 v0, v0, v9
	v_cvt_pk_bf16_f32 v0, v0, v0
	global_store_short v[6:7], v0, off offset:128
	v_mul_f32_e32 v0, v30, v22
	s_waitcnt vmcnt(31)
	v_lshlrev_b32_e32 v9, 16, v13
	v_mul_f32_e32 v0, v0, v9
	v_mul_f32_e32 v9, 0xbfb8aa3b, v9
	v_exp_f32_e32 v9, v9
	s_nop 0
	v_add_f32_e32 v9, 1.0, v9
	v_rcp_f32_e32 v9, v9
	s_nop 0
	v_mul_f32_e32 v0, v0, v9
	v_cvt_pk_bf16_f32 v0, v0, v0
	global_store_short v[6:7], v0, off offset:192
	v_add_u32_e32 v0, 0x10e00, v4
	v_lshl_add_u64 v[2:3], v[0:1], 1, v[2:3]
	v_mul_f32_e32 v0, v79, v5
	s_waitcnt vmcnt(31)
	v_lshlrev_b32_e32 v4, 16, v12
	v_mul_f32_e32 v0, v0, v4
	v_mul_f32_e32 v4, 0xbfb8aa3b, v4
	v_exp_f32_e32 v4, v4
	s_nop 0
	v_add_f32_e32 v4, 1.0, v4
	v_rcp_f32_e32 v4, v4
	s_nop 0
	v_mul_f32_e32 v0, v0, v4
	v_cvt_pk_bf16_f32 v0, v0, v0
	global_store_short v[2:3], v0, off
	v_mul_f32_e32 v0, v63, v5
	s_waitcnt vmcnt(31)
	v_lshlrev_b32_e32 v4, 16, v11
	v_mul_f32_e32 v0, v0, v4
	v_mul_f32_e32 v4, 0xbfb8aa3b, v4
	v_exp_f32_e32 v4, v4
	s_nop 0
	v_add_f32_e32 v4, 1.0, v4
	v_rcp_f32_e32 v4, v4
	s_nop 0
	v_mul_f32_e32 v0, v0, v4
	v_cvt_pk_bf16_f32 v0, v0, v0
	global_store_short v[2:3], v0, off offset:64
	v_mul_f32_e32 v0, v47, v5
	s_waitcnt vmcnt(31)
	v_lshlrev_b32_e32 v4, 16, v10
	v_mul_f32_e32 v0, v0, v4
	v_mul_f32_e32 v4, 0xbfb8aa3b, v4
	v_exp_f32_e32 v4, v4
	s_nop 0
	v_add_f32_e32 v4, 1.0, v4
	v_rcp_f32_e32 v4, v4
	s_nop 0
	v_mul_f32_e32 v0, v0, v4
	v_cvt_pk_bf16_f32 v0, v0, v0
	global_store_short v[2:3], v0, off offset:128
	v_mul_f32_e32 v0, v31, v5
	s_waitcnt vmcnt(31)
	v_lshlrev_b32_e32 v4, 16, v8
	v_mul_f32_e32 v0, v0, v4
	v_mul_f32_e32 v4, 0xbfb8aa3b, v4
	v_exp_f32_e32 v4, v4
	s_nop 0
	v_add_f32_e32 v4, 1.0, v4
	v_rcp_f32_e32 v4, v4
	s_nop 0
	v_mul_f32_e32 v0, v0, v4
	v_cvt_pk_bf16_f32 v0, v0, v0
	global_store_short v[2:3], v0, off offset:192
	s_cbranch_vccnz .LBB0_1071
.LBB0_1074:
	s_xor_b64 s[12:13], s[0:1], -1
	s_and_b64 s[0:1], s[0:1], exec
	s_cselect_b32 s19, s31, s30
	s_lshl_b32 s18, s19, 8
	s_or_b32 s2, s18, s34
	v_add_u32_e32 v18, s2, v162
	s_movk_i32 s0, 0x3400
	v_mad_i64_i32 v[6:7], s[0:1], v18, s0, v[156:157]
	global_load_dwordx4 v[22:25], v[6:7], off
	global_load_dwordx4 v[26:29], v[6:7], off offset:128
	v_ashrrev_i32_e32 v19, 31, v18
	v_lshlrev_b64 v[2:3], 9, v[18:19]
	v_lshl_add_u64 v[20:21], v[154:155], 0, v[2:3]
	global_load_dwordx4 v[30:33], v[20:21], off
	global_load_dwordx4 v[34:37], v[20:21], off offset:16
	global_load_dwordx4 v[38:41], v[20:21], off offset:32
	global_load_dwordx4 v[42:45], v[20:21], off offset:48
	global_load_dwordx4 v[46:49], v[6:7], off offset:32
	global_load_dwordx4 v[10:13], v[6:7], off offset:64
	global_load_dwordx4 v[2:5], v[6:7], off offset:96
	global_load_dwordx4 v[50:53], v[6:7], off offset:160
	global_load_dwordx4 v[14:17], v[6:7], off offset:192
	s_nop 0
	global_load_dwordx4 v[6:9], v[6:7], off offset:224
	v_mov_b32_e32 v159, v1
	v_lshlrev_b64 v[18:19], 8, v[18:19]
	v_lshl_add_u64 v[18:19], s[90:91], 0, v[18:19]
	s_lshl_b32 s37, s19, 2
	s_add_i32 s37, s37, 4
	s_mul_i32 s38, s19, 0x1a0000
	s_mov_b32 s39, 0
	v_mov_b32_e32 v179, 0
	v_mov_b32_e32 v177, 0xf149f2ca
	s_mov_b32 s40, 0
	s_mov_b32 s41, 0
	s_mov_b32 s42, 0
	s_mov_b32 s43, 0
	s_waitcnt vmcnt(11)
	v_lshlrev_b32_e32 v55, 16, v22
	s_waitcnt vmcnt(10)
	v_lshlrev_b32_e32 v54, 16, v26
	v_and_b32_e32 v57, 0xffff0000, v22
	v_and_b32_e32 v56, 0xffff0000, v26
	v_lshlrev_b32_e32 v59, 16, v23
	v_lshlrev_b32_e32 v58, 16, v27
	v_and_b32_e32 v23, 0xffff0000, v23
	v_and_b32_e32 v22, 0xffff0000, v27
	v_lshlrev_b32_e32 v27, 16, v24
	v_lshlrev_b32_e32 v26, 16, v28
	v_and_b32_e32 v61, 0xffff0000, v24
	v_and_b32_e32 v60, 0xffff0000, v28
	v_lshlrev_b32_e32 v63, 16, v25
	v_lshlrev_b32_e32 v62, 16, v29
	v_and_b32_e32 v25, 0xffff0000, v25
	v_and_b32_e32 v24, 0xffff0000, v29
	s_waitcnt vmcnt(9)
	v_pk_mul_f32 v[28:29], v[30:31], v[54:55] op_sel:[0,1] op_sel_hi:[1,0]
	v_pk_mul_f32 v[30:31], v[30:31], v[54:55]
	v_pk_mul_f32 v[54:55], v[32:33], v[56:57] op_sel:[0,1] op_sel_hi:[1,0]
	v_pk_mul_f32 v[32:33], v[32:33], v[56:57]
	s_waitcnt vmcnt(8)
	v_pk_mul_f32 v[56:57], v[34:35], v[58:59] op_sel:[0,1] op_sel_hi:[1,0]
	v_pk_mul_f32 v[34:35], v[34:35], v[58:59]
	v_pk_mul_f32 v[58:59], v[36:37], v[22:23] op_sel:[0,1] op_sel_hi:[1,0]
	v_pk_mul_f32 v[22:23], v[36:37], v[22:23]
	s_waitcnt vmcnt(7)
	v_pk_mul_f32 v[36:37], v[38:39], v[26:27] op_sel:[0,1] op_sel_hi:[1,0]
	v_pk_mul_f32 v[26:27], v[38:39], v[26:27]
	v_pk_mul_f32 v[38:39], v[40:41], v[60:61] op_sel:[0,1] op_sel_hi:[1,0]
	v_pk_mul_f32 v[40:41], v[40:41], v[60:61]
	s_waitcnt vmcnt(6)
	v_pk_mul_f32 v[60:61], v[42:43], v[62:63] op_sel:[0,1] op_sel_hi:[1,0]
	v_pk_mul_f32 v[42:43], v[42:43], v[62:63]
	v_pk_mul_f32 v[62:63], v[44:45], v[24:25] op_sel:[0,1] op_sel_hi:[1,0]
	v_pk_mul_f32 v[24:25], v[44:45], v[24:25]
	v_sub_f32_e32 v0, v28, v29
	v_add_f32_e32 v28, v30, v31
	v_sub_f32_e32 v29, v54, v55
	v_add_f32_e32 v30, v32, v33
	v_sub_f32_e32 v31, v56, v57
	v_add_f32_e32 v32, v34, v35
	v_sub_f32_e32 v33, v58, v59
	v_add_f32_e32 v22, v22, v23
	v_sub_f32_e32 v23, v36, v37
	v_add_f32_e32 v26, v26, v27
	v_sub_f32_e32 v27, v38, v39
	v_add_f32_e32 v34, v40, v41
	v_sub_f32_e32 v35, v60, v61
	v_add_f32_e32 v36, v42, v43
	v_sub_f32_e32 v37, v62, v63
	v_add_f32_e32 v24, v24, v25
	v_mul_f32_e32 v25, 0x3e0293ee, v28
	v_mul_f32_e32 v28, 0x3e0293ee, v29
	v_mul_f32_e32 v29, 0x3e0293ee, v30
	v_mul_f32_e32 v30, 0x3e0293ee, v31
	v_mul_f32_e32 v31, 0x3e0293ee, v32
	v_mul_f32_e32 v32, 0x3e0293ee, v33
	v_mul_f32_e32 v22, 0x3e0293ee, v22
	v_mul_f32_e32 v23, 0x3e0293ee, v23
	v_mul_f32_e32 v26, 0x3e0293ee, v26
	v_mul_f32_e32 v27, 0x3e0293ee, v27
	v_mul_f32_e32 v33, 0x3e0293ee, v34
	v_mul_f32_e32 v34, 0x3e0293ee, v35
	v_mul_f32_e32 v35, 0x3e0293ee, v36
	v_mul_f32_e32 v36, 0x3e0293ee, v37
	v_mul_f32_e32 v24, 0x3e0293ee, v24
	v_mul_f32_e32 v0, 0x3e0293ee, v0
	v_cvt_pk_bf16_f32 v112, v0, v28
	v_cvt_pk_bf16_f32 v113, v30, v32
	v_cvt_pk_bf16_f32 v114, v23, v27
	v_cvt_pk_bf16_f32 v115, v34, v36
	v_cvt_pk_bf16_f32 v116, v25, v29
	v_cvt_pk_bf16_f32 v117, v31, v22
	v_cvt_pk_bf16_f32 v118, v26, v33
	v_cvt_pk_bf16_f32 v119, v35, v24
	global_load_dwordx4 v[22:25], v[20:21], off offset:128
	global_load_dwordx4 v[26:29], v[20:21], off offset:144
	global_load_dwordx4 v[30:33], v[20:21], off offset:160
	global_load_dwordx4 v[34:37], v[20:21], off offset:176
	s_waitcnt vmcnt(9)
	v_lshlrev_b32_e32 v39, 16, v46
	s_waitcnt vmcnt(6)
	v_lshlrev_b32_e32 v38, 16, v50
	v_and_b32_e32 v41, 0xffff0000, v46
	v_and_b32_e32 v40, 0xffff0000, v50
	v_lshlrev_b32_e32 v43, 16, v47
	v_lshlrev_b32_e32 v42, 16, v51
	v_and_b32_e32 v45, 0xffff0000, v47
	v_and_b32_e32 v44, 0xffff0000, v51
	v_lshlrev_b32_e32 v47, 16, v48
	v_lshlrev_b32_e32 v46, 16, v52
	v_and_b32_e32 v51, 0xffff0000, v48
	v_and_b32_e32 v50, 0xffff0000, v52
	v_lshlrev_b32_e32 v55, 16, v49
	v_lshlrev_b32_e32 v54, 16, v53
	v_and_b32_e32 v49, 0xffff0000, v49
	v_and_b32_e32 v48, 0xffff0000, v53
	s_waitcnt vmcnt(3)
	v_pk_mul_f32 v[52:53], v[22:23], v[38:39] op_sel:[0,1] op_sel_hi:[1,0]
	v_pk_mul_f32 v[22:23], v[22:23], v[38:39]
	v_pk_mul_f32 v[38:39], v[24:25], v[40:41] op_sel:[0,1] op_sel_hi:[1,0]
	v_pk_mul_f32 v[24:25], v[24:25], v[40:41]
	s_waitcnt vmcnt(2)
	v_pk_mul_f32 v[40:41], v[26:27], v[42:43] op_sel:[0,1] op_sel_hi:[1,0]
	v_pk_mul_f32 v[26:27], v[26:27], v[42:43]
	v_pk_mul_f32 v[42:43], v[28:29], v[44:45] op_sel:[0,1] op_sel_hi:[1,0]
	v_pk_mul_f32 v[28:29], v[28:29], v[44:45]
	s_waitcnt vmcnt(1)
	v_pk_mul_f32 v[44:45], v[30:31], v[46:47] op_sel:[0,1] op_sel_hi:[1,0]
	v_pk_mul_f32 v[30:31], v[30:31], v[46:47]
	v_pk_mul_f32 v[46:47], v[32:33], v[50:51] op_sel:[0,1] op_sel_hi:[1,0]
	v_pk_mul_f32 v[32:33], v[32:33], v[50:51]
	s_waitcnt vmcnt(0)
	v_pk_mul_f32 v[50:51], v[34:35], v[54:55] op_sel:[0,1] op_sel_hi:[1,0]
	v_pk_mul_f32 v[34:35], v[34:35], v[54:55]
	v_pk_mul_f32 v[54:55], v[36:37], v[48:49] op_sel:[0,1] op_sel_hi:[1,0]
	v_pk_mul_f32 v[36:37], v[36:37], v[48:49]
	v_add_f32_e32 v22, v22, v23
	v_sub_f32_e32 v23, v38, v39
	v_add_f32_e32 v24, v24, v25
	v_sub_f32_e32 v25, v40, v41
	v_add_f32_e32 v26, v26, v27
	v_sub_f32_e32 v27, v42, v43
	v_add_f32_e32 v28, v28, v29
	v_sub_f32_e32 v29, v44, v45
	v_add_f32_e32 v30, v30, v31
	v_sub_f32_e32 v31, v46, v47
	v_add_f32_e32 v32, v32, v33
	v_sub_f32_e32 v33, v50, v51
	v_add_f32_e32 v34, v34, v35
	v_sub_f32_e32 v35, v54, v55
	v_add_f32_e32 v36, v36, v37
	v_sub_f32_e32 v0, v52, v53
	v_mul_f32_e32 v22, 0x3e0293ee, v22
	v_mul_f32_e32 v23, 0x3e0293ee, v23
	v_mul_f32_e32 v24, 0x3e0293ee, v24
	v_mul_f32_e32 v25, 0x3e0293ee, v25
	v_mul_f32_e32 v26, 0x3e0293ee, v26
	v_mul_f32_e32 v27, 0x3e0293ee, v27
	v_mul_f32_e32 v28, 0x3e0293ee, v28
	v_mul_f32_e32 v29, 0x3e0293ee, v29
	v_mul_f32_e32 v30, 0x3e0293ee, v30
	v_mul_f32_e32 v31, 0x3e0293ee, v31
	v_mul_f32_e32 v32, 0x3e0293ee, v32
	v_mul_f32_e32 v33, 0x3e0293ee, v33
	v_mul_f32_e32 v34, 0x3e0293ee, v34
	v_mul_f32_e32 v35, 0x3e0293ee, v35
	v_mul_f32_e32 v36, 0x3e0293ee, v36
	v_mul_f32_e32 v0, 0x3e0293ee, v0
	v_cvt_pk_bf16_f32 v120, v0, v23
	v_cvt_pk_bf16_f32 v121, v25, v27
	v_cvt_pk_bf16_f32 v122, v29, v31
	v_cvt_pk_bf16_f32 v123, v33, v35
	v_cvt_pk_bf16_f32 v124, v22, v24
	v_cvt_pk_bf16_f32 v125, v26, v28
	v_cvt_pk_bf16_f32 v126, v30, v32
	v_cvt_pk_bf16_f32 v127, v34, v36
	global_load_dwordx4 v[22:25], v[20:21], off offset:256
	global_load_dwordx4 v[26:29], v[20:21], off offset:272
	global_load_dwordx4 v[30:33], v[20:21], off offset:288
	global_load_dwordx4 v[34:37], v[20:21], off offset:304
	v_lshlrev_b32_e32 v39, 16, v10
	v_lshlrev_b32_e32 v38, 16, v14
	v_and_b32_e32 v41, 0xffff0000, v10
	v_and_b32_e32 v40, 0xffff0000, v14
	v_lshlrev_b32_e32 v43, 16, v11
	v_lshlrev_b32_e32 v42, 16, v15
	v_and_b32_e32 v11, 0xffff0000, v11
	v_and_b32_e32 v10, 0xffff0000, v15
	v_lshlrev_b32_e32 v15, 16, v12
	v_lshlrev_b32_e32 v14, 16, v16
	v_and_b32_e32 v45, 0xffff0000, v12
	v_and_b32_e32 v44, 0xffff0000, v16
	v_lshlrev_b32_e32 v47, 16, v13
	v_lshlrev_b32_e32 v46, 16, v17
	v_and_b32_e32 v13, 0xffff0000, v13
	v_and_b32_e32 v12, 0xffff0000, v17
	s_waitcnt vmcnt(3)
	v_pk_mul_f32 v[16:17], v[22:23], v[38:39] op_sel:[0,1] op_sel_hi:[1,0]
	v_pk_mul_f32 v[22:23], v[22:23], v[38:39]
	v_pk_mul_f32 v[38:39], v[24:25], v[40:41] op_sel:[0,1] op_sel_hi:[1,0]
	v_pk_mul_f32 v[24:25], v[24:25], v[40:41]
	s_waitcnt vmcnt(2)
	v_pk_mul_f32 v[40:41], v[26:27], v[42:43] op_sel:[0,1] op_sel_hi:[1,0]
	v_pk_mul_f32 v[26:27], v[26:27], v[42:43]
	v_pk_mul_f32 v[42:43], v[28:29], v[10:11] op_sel:[0,1] op_sel_hi:[1,0]
	v_pk_mul_f32 v[10:11], v[28:29], v[10:11]
	s_waitcnt vmcnt(1)
	v_pk_mul_f32 v[28:29], v[30:31], v[14:15] op_sel:[0,1] op_sel_hi:[1,0]
	v_pk_mul_f32 v[14:15], v[30:31], v[14:15]
	v_pk_mul_f32 v[30:31], v[32:33], v[44:45] op_sel:[0,1] op_sel_hi:[1,0]
	v_pk_mul_f32 v[32:33], v[32:33], v[44:45]
	s_waitcnt vmcnt(0)
	v_pk_mul_f32 v[44:45], v[34:35], v[46:47] op_sel:[0,1] op_sel_hi:[1,0]
	v_pk_mul_f32 v[34:35], v[34:35], v[46:47]
	v_pk_mul_f32 v[46:47], v[36:37], v[12:13] op_sel:[0,1] op_sel_hi:[1,0]
	v_pk_mul_f32 v[12:13], v[36:37], v[12:13]
	v_sub_f32_e32 v0, v16, v17
	v_add_f32_e32 v16, v22, v23
	v_sub_f32_e32 v17, v38, v39
	v_add_f32_e32 v22, v24, v25
	v_sub_f32_e32 v23, v40, v41
	v_add_f32_e32 v24, v26, v27
	v_sub_f32_e32 v25, v42, v43
	v_add_f32_e32 v10, v10, v11
	v_sub_f32_e32 v11, v28, v29
	v_add_f32_e32 v14, v14, v15
	v_sub_f32_e32 v15, v30, v31
	v_add_f32_e32 v26, v32, v33
	v_sub_f32_e32 v27, v44, v45
	v_add_f32_e32 v28, v34, v35
	v_sub_f32_e32 v29, v46, v47
	v_add_f32_e32 v12, v12, v13
	v_mul_f32_e32 v13, 0x3e0293ee, v16
	v_mul_f32_e32 v16, 0x3e0293ee, v17
	v_mul_f32_e32 v17, 0x3e0293ee, v22
	v_mul_f32_e32 v22, 0x3e0293ee, v23
	v_mul_f32_e32 v23, 0x3e0293ee, v24
	v_mul_f32_e32 v24, 0x3e0293ee, v25
	v_mul_f32_e32 v10, 0x3e0293ee, v10
	v_mul_f32_e32 v11, 0x3e0293ee, v11
	v_mul_f32_e32 v14, 0x3e0293ee, v14
	v_mul_f32_e32 v15, 0x3e0293ee, v15
	v_mul_f32_e32 v25, 0x3e0293ee, v26
	v_mul_f32_e32 v26, 0x3e0293ee, v27
	v_mul_f32_e32 v27, 0x3e0293ee, v28
	v_mul_f32_e32 v28, 0x3e0293ee, v29
	v_mul_f32_e32 v12, 0x3e0293ee, v12
	v_mul_f32_e32 v0, 0x3e0293ee, v0
	v_cvt_pk_bf16_f32 v128, v0, v16
	v_cvt_pk_bf16_f32 v129, v22, v24
	v_cvt_pk_bf16_f32 v130, v11, v15
	v_cvt_pk_bf16_f32 v131, v26, v28
	v_cvt_pk_bf16_f32 v132, v13, v17
	v_cvt_pk_bf16_f32 v133, v23, v10
	v_cvt_pk_bf16_f32 v134, v14, v25
	v_cvt_pk_bf16_f32 v135, v27, v12
	global_load_dwordx4 v[10:13], v[20:21], off offset:384
	global_load_dwordx4 v[14:17], v[20:21], off offset:400
	global_load_dwordx4 v[22:25], v[20:21], off offset:416
	global_load_dwordx4 v[26:29], v[20:21], off offset:432
	v_lshlrev_b32_e32 v21, 16, v2
	v_lshlrev_b32_e32 v20, 16, v6
	v_and_b32_e32 v31, 0xffff0000, v2
	v_and_b32_e32 v30, 0xffff0000, v6
	v_lshlrev_b32_e32 v33, 16, v3
	v_lshlrev_b32_e32 v32, 16, v7
	v_and_b32_e32 v3, 0xffff0000, v3
	v_and_b32_e32 v2, 0xffff0000, v7
	v_lshlrev_b32_e32 v7, 16, v4
	v_lshlrev_b32_e32 v6, 16, v8
	v_and_b32_e32 v35, 0xffff0000, v4
	v_and_b32_e32 v34, 0xffff0000, v8
	v_lshlrev_b32_e32 v37, 16, v5
	v_lshlrev_b32_e32 v36, 16, v9
	v_and_b32_e32 v5, 0xffff0000, v5
	v_and_b32_e32 v4, 0xffff0000, v9
	v_mov_b32_e32 v38, v198
	s_waitcnt vmcnt(3)
	v_pk_mul_f32 v[8:9], v[10:11], v[20:21] op_sel:[0,1] op_sel_hi:[1,0]
	v_pk_mul_f32 v[10:11], v[10:11], v[20:21]
	v_pk_mul_f32 v[20:21], v[12:13], v[30:31] op_sel:[0,1] op_sel_hi:[1,0]
	v_pk_mul_f32 v[12:13], v[12:13], v[30:31]
	s_waitcnt vmcnt(2)
	v_pk_mul_f32 v[30:31], v[14:15], v[32:33] op_sel:[0,1] op_sel_hi:[1,0]
	v_pk_mul_f32 v[14:15], v[14:15], v[32:33]
	v_pk_mul_f32 v[32:33], v[16:17], v[2:3] op_sel:[0,1] op_sel_hi:[1,0]
	v_pk_mul_f32 v[2:3], v[16:17], v[2:3]
	s_waitcnt vmcnt(1)
	v_pk_mul_f32 v[16:17], v[22:23], v[6:7] op_sel:[0,1] op_sel_hi:[1,0]
	v_pk_mul_f32 v[6:7], v[22:23], v[6:7]
	v_pk_mul_f32 v[22:23], v[24:25], v[34:35] op_sel:[0,1] op_sel_hi:[1,0]
	v_pk_mul_f32 v[24:25], v[24:25], v[34:35]
	s_waitcnt vmcnt(0)
	v_pk_mul_f32 v[34:35], v[26:27], v[36:37] op_sel:[0,1] op_sel_hi:[1,0]
	v_pk_mul_f32 v[26:27], v[26:27], v[36:37]
	v_pk_mul_f32 v[36:37], v[28:29], v[4:5] op_sel:[0,1] op_sel_hi:[1,0]
	v_pk_mul_f32 v[4:5], v[28:29], v[4:5]
	v_sub_f32_e32 v0, v8, v9
	v_add_f32_e32 v8, v10, v11
	v_sub_f32_e32 v9, v20, v21
	v_add_f32_e32 v10, v12, v13
	v_sub_f32_e32 v11, v30, v31
	v_add_f32_e32 v12, v14, v15
	v_sub_f32_e32 v13, v32, v33
	v_add_f32_e32 v2, v2, v3
	v_sub_f32_e32 v3, v16, v17
	v_add_f32_e32 v6, v6, v7
	v_sub_f32_e32 v7, v22, v23
	v_add_f32_e32 v14, v24, v25
	v_sub_f32_e32 v15, v34, v35
	v_add_f32_e32 v16, v26, v27
	v_sub_f32_e32 v17, v36, v37
	v_add_f32_e32 v4, v4, v5
	v_mul_f32_e32 v0, 0x3e0293ee, v0
	v_mul_f32_e32 v5, 0x3e0293ee, v8
	v_mul_f32_e32 v8, 0x3e0293ee, v9
	v_mul_f32_e32 v9, 0x3e0293ee, v10
	v_mul_f32_e32 v10, 0x3e0293ee, v11
	v_mul_f32_e32 v11, 0x3e0293ee, v12
	v_mul_f32_e32 v12, 0x3e0293ee, v13
	v_mul_f32_e32 v2, 0x3e0293ee, v2
	v_mul_f32_e32 v3, 0x3e0293ee, v3
	v_mul_f32_e32 v6, 0x3e0293ee, v6
	v_mul_f32_e32 v7, 0x3e0293ee, v7
	v_mul_f32_e32 v13, 0x3e0293ee, v14
	v_mul_f32_e32 v14, 0x3e0293ee, v15
	v_mul_f32_e32 v15, 0x3e0293ee, v16
	v_mul_f32_e32 v16, 0x3e0293ee, v17
	v_mul_f32_e32 v4, 0x3e0293ee, v4
	v_cvt_pk_bf16_f32 v136, v0, v8
	v_cvt_pk_bf16_f32 v137, v10, v12
	v_cvt_pk_bf16_f32 v138, v3, v7
	v_cvt_pk_bf16_f32 v139, v14, v16
	v_cvt_pk_bf16_f32 v140, v5, v9
	v_cvt_pk_bf16_f32 v141, v11, v2
	v_cvt_pk_bf16_f32 v142, v6, v13
	v_cvt_pk_bf16_f32 v143, v15, v4
	global_load_dwordx4 v[144:147], v[18:19], off
	v_readfirstlane_b32 s0, v38
	v_bfe_u32 v8, v38, 4, 2
	s_ashr_i32 s20, s0, 6
	v_bfe_u32 v0, v38, 2, 3
	v_lshrrev_b32_e32 v3, 1, v38
	v_bitop3_b32 v6, v8, v38, 15 bitop3:0x78
	s_lshl_b32 s0, s20, 3
	s_lshl_b32 s1, s20, 2
	v_and_b32_e32 v3, 8, v3
	v_lshlrev_b32_e32 v9, 3, v6
	v_bitop3_b32 v0, s0, v215, v0 bitop3:0xc8
	s_and_b32 s1, s1, 4
	v_or_b32_e32 v6, s0, v8
	v_or3_b32 v0, v3, v0, s1
	v_mul_lo_u32 v3, v6, s21
	v_mul_u32_u24_e32 v6, 0x1a00, v0
	v_or_b32_e32 v0, v3, v9
	v_or_b32_e32 v3, 4, v8
	v_and_b32_e32 v2, 15, v38
	v_lshlrev_b32_e32 v5, 3, v38
	v_or_b32_e32 v3, s0, v3
	s_lshl_b32 s0, s20, 11
	s_add_i32 s1, 0, 0x10000
	v_and_b32_e32 v4, 32, v38
	v_and_b32_e32 v5, 24, v5
	v_bitop3_b32 v2, v8, v2, 4 bitop3:0x36
	s_add_i32 s35, s1, s0
	v_lshlrev_b32_e32 v10, 3, v2
	v_mul_lo_u32 v2, v3, s21
	v_or3_b32 v158, v4, v5, v6
	v_lshl_add_u64 v[6:7], v[0:1], 1, s[4:5]
	s_mov_b32 m0, s35
	s_add_i32 s36, s0, 0
	v_or_b32_e32 v2, v2, v10
	global_load_lds_dwordx4 v[6:7], off
	v_lshl_add_u64 v[6:7], v[158:159], 1, s[6:7]
	s_mov_b32 m0, s36
	v_mov_b32_e32 v3, v1
	s_or_b32 s14, s0, 0x400
	v_or_b32_e32 v4, 64, v158
	global_load_lds_dwordx4 v[6:7], off
	v_lshl_add_u64 v[6:7], v[2:3], 1, s[4:5]
	s_add_i32 m0, s1, s14
	v_mov_b32_e32 v5, v1
	global_load_lds_dwordx4 v[6:7], off
	v_lshl_add_u64 v[4:5], v[4:5], 1, s[6:7]
	s_add_i32 m0, s36, 0x400
	v_add_u32_e32 v0, 0x68000, v0
	s_add_i32 s1, 0, 0x14000
	global_load_lds_dwordx4 v[4:5], off
	v_lshl_add_u64 v[4:5], v[0:1], 1, s[4:5]
	s_add_i32 m0, s1, s0
	v_add_u32_e32 v0, 0x68000, v158
	global_load_lds_dwordx4 v[4:5], off
	v_lshl_add_u64 v[4:5], v[0:1], 1, s[6:7]
	s_add_i32 m0, s36, 0x4000
	v_add_u32_e32 v0, 0x68000, v2
	global_load_lds_dwordx4 v[4:5], off
	v_lshl_add_u64 v[2:3], v[0:1], 1, s[4:5]
	s_add_i32 m0, s1, s14
	v_add_u32_e32 v0, 0x68040, v158
	global_load_lds_dwordx4 v[2:3], off
	v_lshl_add_u64 v[2:3], v[0:1], 1, s[6:7]
	s_add_i32 m0, s36, 0x4400
	v_and_b32_e32 v4, 0x3fffffc0, v38
	global_load_lds_dwordx4 v[2:3], off
	v_readlane_b32 s0, v254, 1
	v_and_b32_e32 v2, 31, v38
	v_bfe_u32 v3, v38, 5, 1
	v_lshl_add_u32 v165, v4, 2, s0
	v_lshlrev_b32_e32 v166, 8, v2
	v_lshl_add_u32 v173, v2, 2, v165
	v_add_u32_e32 v2, s18, v164
	v_add_u32_e32 v159, s18, v163
	v_and_b32_e32 v0, 63, v38
	v_lshlrev_b32_e32 v5, 4, v38
	v_lshlrev_b32_e32 v167, 4, v3
	v_lshlrev_b32_e32 v174, 2, v3
	v_ashrrev_i32_e32 v3, 31, v2
	v_readlane_b32 s18, v253, 59
	v_lshlrev_b32_e32 v4, 3, v0
	v_and_b32_e32 v6, 0xc0, v5
	v_lshlrev_b32_e32 v7, 1, v38
	s_cmp_gt_i32 s20, 3
	v_lshlrev_b64 v[2:3], 8, v[2:3]
	v_readlane_b32 s19, v253, 60
	v_and_or_b32 v6, v4, 24, v6
	v_and_b32_e32 v7, 32, v7
	v_and_b32_e32 v4, 0x100, v4
	s_movk_i32 s0, 0x70
	s_cselect_b64 s[14:15], -1, 0
	s_cmp_lt_i32 s20, 4
	v_lshl_add_u64 v[160:161], s[18:19], 0, v[2:3]
	s_mul_i32 s18, s20, 0xd000
	v_or3_b32 v4, v6, v7, v4
	v_and_b32_e32 v6, 0x70, v5
	v_bitop3_b32 v168, v167, v5, s0 bitop3:0x78
	s_movk_i32 s0, 0x60
	s_cselect_b64 s[16:17], -1, 0
	s_add_i32 s19, s18, 0xd6800
	v_bitop3_b32 v171, v167, v6, s0 bitop3:0x36
	v_cmp_gt_u32_e64 s[0:1], 32, v0
	v_mov_b32_e32 v0, s19
	v_mad_u32_u24 v0, v8, s21, v0
	s_add_i32 s18, s18, 0xd0000
	v_or_b32_e32 v175, v0, v10
	v_mov_b32_e32 v0, s18
	s_waitcnt vmcnt(4)
	v_mad_u32_u24 v0, v8, s21, v0
	v_mov_b32_e32 v14, v1
	v_mov_b32_e32 v15, v1
	v_bitop3_b32 v169, v167, v6, 32 bitop3:0x36
	v_bitop3_b32 v170, v167, v6, 64 bitop3:0x36
	v_add_u32_e32 v172, 0, v4
	v_or_b32_e32 v176, v0, v9
	v_mov_b32_e32 v0, v1
	v_mov_b32_e32 v2, v1
	v_mov_b32_e32 v3, v1
	v_mov_b32_e32 v4, v1
	v_mov_b32_e32 v5, v1
	v_mov_b32_e32 v6, v1
	v_mov_b32_e32 v7, v1
	v_mov_b32_e32 v8, v1
	v_mov_b32_e32 v9, v1
	v_mov_b32_e32 v10, v1
	v_mov_b32_e32 v11, v1
	v_mov_b32_e32 v12, v1
	v_mov_b32_e32 v13, v1
	v_mov_b64_e32 v[30:31], v[14:15]
	v_mov_b64_e32 v[46:47], v[14:15]
	v_mov_b64_e32 v[62:63], v[14:15]
	v_mov_b64_e32 v[78:79], v[14:15]
	v_mov_b64_e32 v[94:95], v[14:15]
	v_mov_b64_e32 v[110:111], v[14:15]
	s_add_i32 s38, s38, 0x208000
	s_mov_b64 s[20:21], 0
	v_mov_b64_e32 v[28:29], v[12:13]
	v_mov_b64_e32 v[26:27], v[10:11]
	v_mov_b64_e32 v[24:25], v[8:9]
	v_mov_b64_e32 v[22:23], v[6:7]
	v_mov_b64_e32 v[20:21], v[4:5]
	v_mov_b64_e32 v[18:19], v[2:3]
	v_mov_b64_e32 v[16:17], v[0:1]
	v_mov_b64_e32 v[44:45], v[12:13]
	v_mov_b64_e32 v[42:43], v[10:11]
	v_mov_b64_e32 v[40:41], v[8:9]
	v_mov_b64_e32 v[38:39], v[6:7]
	v_mov_b64_e32 v[36:37], v[4:5]
	v_mov_b64_e32 v[34:35], v[2:3]
	v_mov_b64_e32 v[32:33], v[0:1]
	v_mov_b64_e32 v[60:61], v[12:13]
	v_mov_b64_e32 v[58:59], v[10:11]
	v_mov_b64_e32 v[56:57], v[8:9]
	v_mov_b64_e32 v[54:55], v[6:7]
	v_mov_b64_e32 v[52:53], v[4:5]
	v_mov_b64_e32 v[50:51], v[2:3]
	v_mov_b64_e32 v[48:49], v[0:1]
	v_mov_b64_e32 v[76:77], v[12:13]
	v_mov_b64_e32 v[74:75], v[10:11]
	v_mov_b64_e32 v[72:73], v[8:9]
	v_mov_b64_e32 v[70:71], v[6:7]
	v_mov_b64_e32 v[68:69], v[4:5]
	v_mov_b64_e32 v[66:67], v[2:3]
	v_mov_b64_e32 v[64:65], v[0:1]
	v_mov_b64_e32 v[92:93], v[12:13]
	v_mov_b64_e32 v[90:91], v[10:11]
	v_mov_b64_e32 v[88:89], v[8:9]
	v_mov_b64_e32 v[86:87], v[6:7]
	v_mov_b64_e32 v[84:85], v[4:5]
	v_mov_b64_e32 v[82:83], v[2:3]
	v_mov_b64_e32 v[80:81], v[0:1]
	v_mov_b64_e32 v[108:109], v[12:13]
	v_mov_b64_e32 v[106:107], v[10:11]
	v_mov_b64_e32 v[104:105], v[8:9]
	v_mov_b64_e32 v[102:103], v[6:7]
	v_mov_b64_e32 v[100:101], v[4:5]
	v_mov_b64_e32 v[98:99], v[2:3]
	v_mov_b64_e32 v[96:97], v[0:1]
	s_waitcnt vmcnt(4) lgkmcnt(0)
	s_barrier

.LBB0_1095:
	s_add_i32 s18, s41, 1
	s_cmp_lg_u32 s41, 2
	s_cselect_b32 s41, s18, 0
	s_add_i32 s18, s42, 1
	s_and_b32 s42, s18, 3
	s_add_i32 s43, s43, 1
	s_add_i32 s40, s40, 0x68000
	s_add_i32 s39, s39, 64
	s_cmp_lg_u32 s38, s40
	v_lshl_add_u64 v[160:161], v[160:161], 0, 8
	s_waitcnt vmcnt(4) lgkmcnt(0)
	s_barrier
	s_cbranch_scc0 .LBB0_1097
	v_mov_b32_e32 v145, v147
	v_mov_b32_e32 v144, v146
	v_mov_b64_e32 v[146:147], v[14:15]
	s_branch .LBB0_1075

.LBB0_1127:
	s_or_b64 exec, exec, s[16:17]
	v_ashrrev_i32_e32 v2, 1, v2
	v_and_b32_e32 v8, 0xffffffe0, v2
	v_lshlrev_b32_e32 v0, 1, v0
	v_lshl_add_u64 v[6:7], s[28:29], 0, v[0:1]
	v_lshl_add_u64 v[2:3], s[30:31], 0, v[0:1]
	v_lshl_or_b32 v0, v4, 2, v8
	v_add_u32_e32 v8, s2, v0
	s_movk_i32 s40, 0x2500
	s_waitcnt lgkmcnt(0)
	v_mul_lo_u32 v0, v8, s40
	v_lshl_add_u32 v90, v4, 4, v5
	ds_read_b128 v[80:83], v90
	ds_read_b128 v[98:101], v90 offset:32
	v_add_u32_e32 v4, 0x2500, v0
	v_mov_b32_e32 v5, v1
	v_lshl_add_u64 v[10:11], v[4:5], 1, v[6:7]
	v_add_u32_e32 v4, 0x4a00, v0
	v_lshl_add_u64 v[12:13], v[4:5], 1, v[6:7]
	v_add_u32_e32 v4, 0x6f00, v0
	v_lshl_add_u64 v[14:15], v[4:5], 1, v[6:7]
	v_add_u32_e32 v4, 0x12800, v0
	s_waitcnt lgkmcnt(1)
	v_rcp_f32_e32 v107, v80
	v_rcp_f32_e32 v102, v81
	v_lshl_add_u64 v[80:81], v[4:5], 1, v[6:7]
	v_add_u32_e32 v4, 0x14d00, v0
	v_rcp_f32_e32 v97, v82
	v_rcp_f32_e32 v95, v83
	v_lshl_add_u64 v[82:83], v[4:5], 1, v[6:7]
	v_add_u32_e32 v4, 0x17200, v0
	v_lshl_add_u64 v[84:85], v[4:5], 1, v[6:7]
	v_add_u32_e32 v4, 0x19700, v0
	s_movk_i32 s2, 0xa00
	v_lshl_add_u64 v[88:89], v[0:1], 1, v[6:7]
	v_lshl_add_u64 v[86:87], v[4:5], 1, v[6:7]
	v_mul_lo_u32 v4, v8, s2
	v_lshl_add_u64 v[8:9], v[4:5], 1, v[2:3]
	v_mul_f32_e32 v5, v64, v107
	global_load_ushort v201, v[88:89], off
	s_waitcnt lgkmcnt(0)
	v_rcp_f32_e32 v94, v98
	v_rcp_f32_e32 v93, v99
	v_rcp_f32_e32 v92, v100
	v_rcp_f32_e32 v91, v101
	v_mul_f32_e32 v48, v48, v107
	v_mul_f32_e32 v32, v32, v107
	v_mul_f32_e32 v16, v16, v107
	s_mov_b64 s[16:17], 0
	s_and_b64 vcc, exec, s[34:35]
	v_mov_b32_e32 v200, v5
	global_load_ushort v110, v[88:89], off offset:64
	global_load_ushort v111, v[88:89], off offset:128
	global_load_ushort v112, v[88:89], off offset:192
	global_load_ushort v113, v[10:11], off
	global_load_ushort v114, v[10:11], off offset:64
	global_load_ushort v115, v[10:11], off offset:128
	global_load_ushort v116, v[10:11], off offset:192
	global_load_ushort v117, v[12:13], off
	global_load_ushort v118, v[12:13], off offset:64
	global_load_ushort v108, v[12:13], off offset:128
	global_load_ushort v106, v[12:13], off offset:192
	global_load_ushort v105, v[14:15], off
	global_load_ushort v104, v[14:15], off offset:64
	global_load_ushort v103, v[14:15], off offset:128
	global_load_ushort v101, v[14:15], off offset:192
	global_load_ushort v100, v[80:81], off
	global_load_ushort v99, v[80:81], off offset:64
	global_load_ushort v98, v[80:81], off offset:128
	global_load_ushort v96, v[80:81], off offset:192
	global_load_ushort v89, v[82:83], off
	global_load_ushort v88, v[82:83], off offset:64
	s_nop 0
	global_load_ushort v81, v[82:83], off offset:128
	global_load_ushort v80, v[82:83], off offset:192
	global_load_ushort v64, v[84:85], off
	global_load_ushort v15, v[84:85], off offset:64
	global_load_ushort v14, v[84:85], off offset:128
	global_load_ushort v13, v[84:85], off offset:192
	global_load_ushort v12, v[86:87], off
	global_load_ushort v11, v[86:87], off offset:64
	global_load_ushort v10, v[86:87], off offset:128
	global_load_ushort v5, v[86:87], off offset:192
	s_waitcnt vmcnt(31)
	v_lshlrev_b32_e32 v201, 16, v201
	v_mul_f32_e32 v200, v200, v201
	v_mul_f32_e32 v201, 0xbfb8aa3b, v201
	v_exp_f32_e32 v201, v201
	s_nop 0
	v_add_f32_e32 v201, 1.0, v201
	v_rcp_f32_e32 v201, v201
	s_nop 0
	v_mul_f32_e32 v109, v200, v201
	v_cvt_pk_bf16_f32 v82, v109, v109
	global_store_short v[8:9], v82, off
	s_waitcnt vmcnt(31)
	v_lshlrev_b32_e32 v82, 16, v110
	v_mul_f32_e32 v48, v48, v82
	v_mul_f32_e32 v82, 0xbfb8aa3b, v82
	v_exp_f32_e32 v82, v82
	s_waitcnt vmcnt(7)
	v_lshlrev_b32_e32 v15, 16, v15
	v_add_f32_e32 v82, 1.0, v82
	v_rcp_f32_e32 v82, v82
	s_waitcnt vmcnt(6)
	v_lshlrev_b32_e32 v14, 16, v14
	s_waitcnt vmcnt(5)
	v_lshlrev_b32_e32 v13, 16, v13
	s_waitcnt vmcnt(4)
	v_lshlrev_b32_e32 v12, 16, v12
	v_mul_f32_e32 v48, v48, v82
	v_cvt_pk_bf16_f32 v48, v48, v48
	global_store_short v[8:9], v48, off offset:64
	v_lshlrev_b32_e32 v48, 16, v111
	v_mul_f32_e32 v32, v32, v48
	v_mul_f32_e32 v48, 0xbfb8aa3b, v48
	v_exp_f32_e32 v48, v48
	s_waitcnt vmcnt(4)
	v_lshlrev_b32_e32 v11, 16, v11
	s_waitcnt vmcnt(3)
	v_lshlrev_b32_e32 v10, 16, v10
	s_waitcnt vmcnt(2)
	v_lshlrev_b32_e32 v5, 16, v5
	v_add_f32_e32 v48, 1.0, v48
	v_rcp_f32_e32 v48, v48
	s_nop 0
	v_mul_f32_e32 v32, v32, v48
	v_cvt_pk_bf16_f32 v32, v32, v32
	global_store_short v[8:9], v32, off offset:128
	v_lshlrev_b32_e32 v32, 16, v112
	v_mul_f32_e32 v16, v16, v32
	v_mul_f32_e32 v32, 0xbfb8aa3b, v32
	v_exp_f32_e32 v32, v32
	s_nop 0
	v_add_f32_e32 v32, 1.0, v32
	v_rcp_f32_e32 v32, v32
	s_nop 0
	v_mul_f32_e32 v16, v16, v32
	v_cvt_pk_bf16_f32 v16, v16, v16
	global_store_short v[8:9], v16, off offset:192
	v_mul_f32_e32 v16, v65, v102
	v_lshlrev_b32_e32 v32, 16, v113
	v_mul_f32_e32 v16, v16, v32
	v_mul_f32_e32 v32, 0xbfb8aa3b, v32
	v_exp_f32_e32 v32, v32
	v_add_u32_e32 v8, 0xa00, v4
	v_mov_b32_e32 v9, v1
	v_lshl_add_u64 v[8:9], v[8:9], 1, v[2:3]
	v_add_f32_e32 v32, 1.0, v32
	v_rcp_f32_e32 v32, v32
	s_nop 0
	v_mul_f32_e32 v16, v16, v32
	v_cvt_pk_bf16_f32 v16, v16, v16
	global_store_short v[8:9], v16, off
	v_mul_f32_e32 v16, v49, v102
	v_lshlrev_b32_e32 v32, 16, v114
	v_mul_f32_e32 v16, v16, v32
	v_mul_f32_e32 v32, 0xbfb8aa3b, v32
	v_exp_f32_e32 v32, v32
	s_nop 0
	v_add_f32_e32 v32, 1.0, v32
	v_rcp_f32_e32 v32, v32
	s_nop 0
	v_mul_f32_e32 v16, v16, v32
	v_cvt_pk_bf16_f32 v16, v16, v16
	global_store_short v[8:9], v16, off offset:64
	v_mul_f32_e32 v16, v33, v102
	v_lshlrev_b32_e32 v32, 16, v115
	v_mul_f32_e32 v16, v16, v32
	v_mul_f32_e32 v32, 0xbfb8aa3b, v32
	v_exp_f32_e32 v32, v32
	s_nop 0
	v_add_f32_e32 v32, 1.0, v32
	v_rcp_f32_e32 v32, v32
	s_nop 0
	v_mul_f32_e32 v16, v16, v32
	v_cvt_pk_bf16_f32 v16, v16, v16
	global_store_short v[8:9], v16, off offset:128
	v_mul_f32_e32 v16, v17, v102
	v_lshlrev_b32_e32 v17, 16, v116
	v_mul_f32_e32 v16, v16, v17
	v_mul_f32_e32 v17, 0xbfb8aa3b, v17
	v_exp_f32_e32 v17, v17
	s_nop 0
	v_add_f32_e32 v17, 1.0, v17
	v_rcp_f32_e32 v17, v17
	s_nop 0
	v_mul_f32_e32 v16, v16, v17
	v_cvt_pk_bf16_f32 v16, v16, v16
	global_store_short v[8:9], v16, off offset:192
	v_mul_f32_e32 v16, v66, v97
	v_lshlrev_b32_e32 v17, 16, v117
	v_mul_f32_e32 v16, v16, v17
	v_mul_f32_e32 v17, 0xbfb8aa3b, v17
	v_exp_f32_e32 v17, v17
	v_add_u32_e32 v8, 0x1400, v4
	v_mov_b32_e32 v9, v1
	v_lshl_add_u64 v[8:9], v[8:9], 1, v[2:3]
	v_add_f32_e32 v17, 1.0, v17
	v_rcp_f32_e32 v17, v17
	s_nop 0
	v_mul_f32_e32 v16, v16, v17
	v_cvt_pk_bf16_f32 v16, v16, v16
	global_store_short v[8:9], v16, off
	v_mul_f32_e32 v16, v50, v97
	v_lshlrev_b32_e32 v17, 16, v118
	v_mul_f32_e32 v16, v16, v17
	v_mul_f32_e32 v17, 0xbfb8aa3b, v17
	v_exp_f32_e32 v17, v17
	s_nop 0
	v_add_f32_e32 v17, 1.0, v17
	v_rcp_f32_e32 v17, v17
	s_nop 0
	v_mul_f32_e32 v16, v16, v17
	v_cvt_pk_bf16_f32 v16, v16, v16
	global_store_short v[8:9], v16, off offset:64
	v_mul_f32_e32 v16, v34, v97
	v_lshlrev_b32_e32 v17, 16, v108
	v_mul_f32_e32 v16, v16, v17
	v_mul_f32_e32 v17, 0xbfb8aa3b, v17
	v_exp_f32_e32 v17, v17
	s_nop 0
	v_add_f32_e32 v17, 1.0, v17
	v_rcp_f32_e32 v17, v17
	s_nop 0
	v_mul_f32_e32 v16, v16, v17
	v_cvt_pk_bf16_f32 v16, v16, v16
	global_store_short v[8:9], v16, off offset:128
	v_mul_f32_e32 v16, v18, v97
	v_lshlrev_b32_e32 v17, 16, v106
	v_mul_f32_e32 v16, v16, v17
	v_mul_f32_e32 v17, 0xbfb8aa3b, v17
	v_exp_f32_e32 v17, v17
	s_nop 0
	v_add_f32_e32 v17, 1.0, v17
	v_rcp_f32_e32 v17, v17
	s_nop 0
	v_mul_f32_e32 v16, v16, v17
	v_cvt_pk_bf16_f32 v16, v16, v16
	global_store_short v[8:9], v16, off offset:192
	v_mul_f32_e32 v16, v67, v95
	v_lshlrev_b32_e32 v17, 16, v105
	v_mul_f32_e32 v16, v16, v17
	v_mul_f32_e32 v17, 0xbfb8aa3b, v17
	v_exp_f32_e32 v17, v17
	v_add_u32_e32 v8, 0x1e00, v4
	v_mov_b32_e32 v9, v1
	v_lshl_add_u64 v[8:9], v[8:9], 1, v[2:3]
	v_add_f32_e32 v17, 1.0, v17
	v_rcp_f32_e32 v17, v17
	s_nop 0
	v_mul_f32_e32 v16, v16, v17
	v_cvt_pk_bf16_f32 v16, v16, v16
	global_store_short v[8:9], v16, off
	v_mul_f32_e32 v16, v51, v95
	v_lshlrev_b32_e32 v17, 16, v104
	v_mul_f32_e32 v16, v16, v17
	v_mul_f32_e32 v17, 0xbfb8aa3b, v17
	v_exp_f32_e32 v17, v17
	s_nop 0
	v_add_f32_e32 v17, 1.0, v17
	v_rcp_f32_e32 v17, v17
	s_nop 0
	v_mul_f32_e32 v16, v16, v17
	v_cvt_pk_bf16_f32 v16, v16, v16
	global_store_short v[8:9], v16, off offset:64
	v_mul_f32_e32 v16, v35, v95
	v_lshlrev_b32_e32 v17, 16, v103
	v_mul_f32_e32 v16, v16, v17
	v_mul_f32_e32 v17, 0xbfb8aa3b, v17
	v_exp_f32_e32 v17, v17
	s_nop 0
	v_add_f32_e32 v17, 1.0, v17
	v_rcp_f32_e32 v17, v17
	s_nop 0
	v_mul_f32_e32 v16, v16, v17
	v_cvt_pk_bf16_f32 v16, v16, v16
	global_store_short v[8:9], v16, off offset:128
	v_mul_f32_e32 v16, v19, v95
	v_lshlrev_b32_e32 v17, 16, v101
	v_mul_f32_e32 v16, v16, v17
	v_mul_f32_e32 v17, 0xbfb8aa3b, v17
	v_exp_f32_e32 v17, v17
	s_nop 0
	v_add_f32_e32 v17, 1.0, v17
	v_rcp_f32_e32 v17, v17
	s_nop 0
	v_mul_f32_e32 v16, v16, v17
	v_cvt_pk_bf16_f32 v16, v16, v16
	global_store_short v[8:9], v16, off offset:192
	v_mul_f32_e32 v16, v68, v94
	v_lshlrev_b32_e32 v17, 16, v100
	v_mul_f32_e32 v16, v16, v17
	v_mul_f32_e32 v17, 0xbfb8aa3b, v17
	v_exp_f32_e32 v17, v17
	v_add_u32_e32 v8, 0x5000, v4
	v_mov_b32_e32 v9, v1
	v_lshl_add_u64 v[8:9], v[8:9], 1, v[2:3]
	v_add_f32_e32 v17, 1.0, v17
	v_rcp_f32_e32 v17, v17
	s_nop 0
	v_mul_f32_e32 v16, v16, v17
	v_cvt_pk_bf16_f32 v16, v16, v16
	global_store_short v[8:9], v16, off
	v_mul_f32_e32 v16, v52, v94
	v_lshlrev_b32_e32 v17, 16, v99
	v_mul_f32_e32 v16, v16, v17
	v_mul_f32_e32 v17, 0xbfb8aa3b, v17
	v_exp_f32_e32 v17, v17
	s_nop 0
	v_add_f32_e32 v17, 1.0, v17
	v_rcp_f32_e32 v17, v17
	s_nop 0
	v_mul_f32_e32 v16, v16, v17
	v_cvt_pk_bf16_f32 v16, v16, v16
	global_store_short v[8:9], v16, off offset:64
	v_mul_f32_e32 v16, v36, v94
	v_lshlrev_b32_e32 v17, 16, v98
	v_mul_f32_e32 v16, v16, v17
	v_mul_f32_e32 v17, 0xbfb8aa3b, v17
	v_exp_f32_e32 v17, v17
	s_nop 0
	v_add_f32_e32 v17, 1.0, v17
	v_rcp_f32_e32 v17, v17
	s_nop 0
	v_mul_f32_e32 v16, v16, v17
	v_cvt_pk_bf16_f32 v16, v16, v16
	global_store_short v[8:9], v16, off offset:128
	v_mul_f32_e32 v16, v20, v94
	v_lshlrev_b32_e32 v17, 16, v96
	v_mul_f32_e32 v16, v16, v17
	v_mul_f32_e32 v17, 0xbfb8aa3b, v17
	v_exp_f32_e32 v17, v17
	s_nop 0
	v_add_f32_e32 v17, 1.0, v17
	v_rcp_f32_e32 v17, v17
	s_nop 0
	v_mul_f32_e32 v16, v16, v17
	v_cvt_pk_bf16_f32 v16, v16, v16
	global_store_short v[8:9], v16, off offset:192
	v_mul_f32_e32 v16, v69, v93
	v_lshlrev_b32_e32 v17, 16, v89
	v_mul_f32_e32 v16, v16, v17
	v_mul_f32_e32 v17, 0xbfb8aa3b, v17
	v_exp_f32_e32 v17, v17
	v_add_u32_e32 v8, 0x5a00, v4
	v_mov_b32_e32 v9, v1
	v_lshl_add_u64 v[8:9], v[8:9], 1, v[2:3]
	v_add_f32_e32 v17, 1.0, v17
	v_rcp_f32_e32 v17, v17
	s_nop 0
	v_mul_f32_e32 v16, v16, v17
	v_cvt_pk_bf16_f32 v16, v16, v16
	global_store_short v[8:9], v16, off
	v_mul_f32_e32 v16, v53, v93
	v_lshlrev_b32_e32 v17, 16, v88
	v_mul_f32_e32 v16, v16, v17
	v_mul_f32_e32 v17, 0xbfb8aa3b, v17
	v_exp_f32_e32 v17, v17
	s_nop 0
	v_add_f32_e32 v17, 1.0, v17
	v_rcp_f32_e32 v17, v17
	s_nop 0
	v_mul_f32_e32 v16, v16, v17
	v_cvt_pk_bf16_f32 v16, v16, v16
	global_store_short v[8:9], v16, off offset:64
	v_mul_f32_e32 v16, v37, v93
	v_lshlrev_b32_e32 v17, 16, v81
	v_mul_f32_e32 v16, v16, v17
	v_mul_f32_e32 v17, 0xbfb8aa3b, v17
	v_exp_f32_e32 v17, v17
	s_nop 0
	v_add_f32_e32 v17, 1.0, v17
	v_rcp_f32_e32 v17, v17
	s_nop 0
	v_mul_f32_e32 v16, v16, v17
	v_cvt_pk_bf16_f32 v16, v16, v16
	global_store_short v[8:9], v16, off offset:128
	v_mul_f32_e32 v16, v21, v93
	v_lshlrev_b32_e32 v17, 16, v80
	v_mul_f32_e32 v16, v16, v17
	v_mul_f32_e32 v17, 0xbfb8aa3b, v17
	v_exp_f32_e32 v17, v17
	s_nop 0
	v_add_f32_e32 v17, 1.0, v17
	v_rcp_f32_e32 v17, v17
	s_nop 0
	v_mul_f32_e32 v16, v16, v17
	v_cvt_pk_bf16_f32 v16, v16, v16
	global_store_short v[8:9], v16, off offset:192
	v_mul_f32_e32 v16, v70, v92
	v_lshlrev_b32_e32 v17, 16, v64
	v_mul_f32_e32 v16, v16, v17
	v_mul_f32_e32 v17, 0xbfb8aa3b, v17
	v_exp_f32_e32 v17, v17
	v_add_u32_e32 v8, 0x6400, v4
	v_mov_b32_e32 v9, v1
	v_lshl_add_u64 v[8:9], v[8:9], 1, v[2:3]
	v_add_f32_e32 v17, 1.0, v17
	v_rcp_f32_e32 v17, v17
	s_nop 0
	v_mul_f32_e32 v16, v16, v17
	v_cvt_pk_bf16_f32 v16, v16, v16
	global_store_short v[8:9], v16, off
	v_mul_f32_e32 v16, v54, v92
	v_mul_f32_e32 v16, v16, v15
	v_mul_f32_e32 v15, 0xbfb8aa3b, v15
	v_exp_f32_e32 v15, v15
	s_nop 0
	v_add_f32_e32 v15, 1.0, v15
	v_rcp_f32_e32 v15, v15
	s_nop 0
	v_mul_f32_e32 v15, v16, v15
	v_cvt_pk_bf16_f32 v15, v15, v15
	global_store_short v[8:9], v15, off offset:64
	v_mul_f32_e32 v15, v38, v92
	v_mul_f32_e32 v15, v15, v14
	v_mul_f32_e32 v14, 0xbfb8aa3b, v14
	v_exp_f32_e32 v14, v14
	s_nop 0
	v_add_f32_e32 v14, 1.0, v14
	v_rcp_f32_e32 v14, v14
	s_nop 0
	v_mul_f32_e32 v14, v15, v14
	v_cvt_pk_bf16_f32 v14, v14, v14
	global_store_short v[8:9], v14, off offset:128
	v_mul_f32_e32 v14, v22, v92
	v_mul_f32_e32 v14, v14, v13
	v_mul_f32_e32 v13, 0xbfb8aa3b, v13
	v_exp_f32_e32 v13, v13
	s_nop 0
	v_add_f32_e32 v13, 1.0, v13
	v_rcp_f32_e32 v13, v13
	s_nop 0
	v_mul_f32_e32 v13, v14, v13
	v_cvt_pk_bf16_f32 v13, v13, v13
	global_store_short v[8:9], v13, off offset:192
	v_mul_f32_e32 v13, v71, v91
	v_mul_f32_e32 v13, v13, v12
	v_mul_f32_e32 v12, 0xbfb8aa3b, v12
	v_exp_f32_e32 v12, v12
	v_add_u32_e32 v8, 0x6e00, v4
	v_mov_b32_e32 v9, v1
	v_lshl_add_u64 v[8:9], v[8:9], 1, v[2:3]
	v_add_f32_e32 v12, 1.0, v12
	v_rcp_f32_e32 v12, v12
	s_nop 0
	v_mul_f32_e32 v12, v13, v12
	v_cvt_pk_bf16_f32 v12, v12, v12
	global_store_short v[8:9], v12, off
	v_mul_f32_e32 v12, v55, v91
	v_mul_f32_e32 v12, v12, v11
	v_mul_f32_e32 v11, 0xbfb8aa3b, v11
	v_exp_f32_e32 v11, v11
	s_nop 0
	v_add_f32_e32 v11, 1.0, v11
	v_rcp_f32_e32 v11, v11
	s_nop 0
	v_mul_f32_e32 v11, v12, v11
	v_cvt_pk_bf16_f32 v11, v11, v11
	global_store_short v[8:9], v11, off offset:64
	v_mul_f32_e32 v11, v39, v91
	v_mul_f32_e32 v11, v11, v10
	v_mul_f32_e32 v10, 0xbfb8aa3b, v10
	v_exp_f32_e32 v10, v10
	s_nop 0
	v_add_f32_e32 v10, 1.0, v10
	v_rcp_f32_e32 v10, v10
	s_nop 0
	v_mul_f32_e32 v10, v11, v10
	v_cvt_pk_bf16_f32 v10, v10, v10
	global_store_short v[8:9], v10, off offset:128
	v_mul_f32_e32 v10, v23, v91
	v_mul_f32_e32 v10, v10, v5
	v_mul_f32_e32 v5, 0xbfb8aa3b, v5
	v_exp_f32_e32 v5, v5
	s_nop 0
	v_add_f32_e32 v5, 1.0, v5
	v_rcp_f32_e32 v5, v5
	s_nop 0
	v_mul_f32_e32 v5, v10, v5
	v_cvt_pk_bf16_f32 v5, v5, v5
	global_store_short v[8:9], v5, off offset:192
	v_add_u32_e32 v8, 0x25000, v0
	v_mov_b32_e32 v9, v1
	v_lshl_add_u64 v[34:35], v[8:9], 1, v[6:7]
	ds_read_b128 v[12:15], v90 offset:64
	ds_read_b128 v[50:53], v90 offset:96
	global_load_ushort v200, v[34:35], off
	v_add_u32_e32 v8, 0x27500, v0
	v_lshl_add_u64 v[20:21], v[8:9], 1, v[6:7]
	v_add_u32_e32 v8, 0x29a00, v0
	v_lshl_add_u64 v[10:11], v[8:9], 1, v[6:7]
	v_add_u32_e32 v8, 0x2bf00, v0
	s_waitcnt lgkmcnt(1)
	v_rcp_f32_e32 v54, v12
	v_rcp_f32_e32 v49, v13
	v_lshl_add_u64 v[12:13], v[8:9], 1, v[6:7]
	v_add_u32_e32 v8, 0x37800, v0
	v_rcp_f32_e32 v36, v14
	v_rcp_f32_e32 v33, v15
	v_lshl_add_u64 v[14:15], v[8:9], 1, v[6:7]
	v_add_u32_e32 v8, 0x39d00, v0
	v_lshl_add_u64 v[16:17], v[8:9], 1, v[6:7]
	v_add_u32_e32 v8, 0x3c200, v0
	v_add_u32_e32 v0, 0x3e700, v0
	v_lshl_add_u64 v[18:19], v[8:9], 1, v[6:7]
	v_lshl_add_u64 v[8:9], v[0:1], 1, v[6:7]
	v_add_u32_e32 v0, 0xa000, v4
	v_lshl_add_u64 v[6:7], v[0:1], 1, v[2:3]
	v_mul_f32_e32 v0, v72, v54
	s_waitcnt lgkmcnt(0)
	v_rcp_f32_e32 v32, v50
	v_rcp_f32_e32 v23, v51
	v_rcp_f32_e32 v22, v52
	v_rcp_f32_e32 v5, v53
	global_load_ushort v64, v[34:35], off offset:64
	global_load_ushort v65, v[34:35], off offset:128
	global_load_ushort v66, v[34:35], off offset:192
	global_load_ushort v67, v[20:21], off
	global_load_ushort v68, v[20:21], off offset:64
	global_load_ushort v69, v[20:21], off offset:128
	global_load_ushort v70, v[20:21], off offset:192
	global_load_ushort v71, v[10:11], off
	global_load_ushort v72, v[10:11], off offset:64
	global_load_ushort v55, v[10:11], off offset:128
	global_load_ushort v53, v[10:11], off offset:192
	global_load_ushort v52, v[12:13], off
	global_load_ushort v51, v[12:13], off offset:64
	global_load_ushort v50, v[12:13], off offset:128
	global_load_ushort v48, v[12:13], off offset:192
	global_load_ushort v39, v[14:15], off
	global_load_ushort v38, v[14:15], off offset:64
	global_load_ushort v37, v[14:15], off offset:128
	global_load_ushort v35, v[14:15], off offset:192
	global_load_ushort v34, v[16:17], off
	global_load_ushort v21, v[16:17], off offset:64
	global_load_ushort v20, v[16:17], off offset:128
	s_nop 0
	global_load_ushort v17, v[16:17], off offset:192
	s_nop 0
	global_load_ushort v16, v[18:19], off
	global_load_ushort v15, v[18:19], off offset:64
	global_load_ushort v14, v[18:19], off offset:128
	global_load_ushort v13, v[18:19], off offset:192
	global_load_ushort v12, v[8:9], off
	global_load_ushort v11, v[8:9], off offset:64
	global_load_ushort v10, v[8:9], off offset:128
	s_nop 0
	global_load_ushort v8, v[8:9], off offset:192
	s_waitcnt vmcnt(31)
	v_lshlrev_b32_e32 v200, 16, v200
	v_mul_f32_e32 v0, v0, v200
	v_mul_f32_e32 v200, 0xbfb8aa3b, v200
	v_exp_f32_e32 v200, v200
	s_nop 0
	v_add_f32_e32 v200, 1.0, v200
	v_rcp_f32_e32 v200, v200
	s_nop 0
	v_mul_f32_e32 v0, v0, v200
	v_cvt_pk_bf16_f32 v0, v0, v0
	global_store_short v[6:7], v0, off
	v_mul_f32_e32 v0, v56, v54
	s_waitcnt vmcnt(31)
	v_lshlrev_b32_e32 v9, 16, v64
	v_mul_f32_e32 v0, v0, v9
	v_mul_f32_e32 v9, 0xbfb8aa3b, v9
	v_exp_f32_e32 v9, v9
	s_nop 0
	v_add_f32_e32 v9, 1.0, v9
	v_rcp_f32_e32 v9, v9
	s_nop 0
	v_mul_f32_e32 v0, v0, v9
	v_cvt_pk_bf16_f32 v0, v0, v0
	global_store_short v[6:7], v0, off offset:64
	v_mul_f32_e32 v0, v40, v54
	s_waitcnt vmcnt(31)
	v_lshlrev_b32_e32 v9, 16, v65
	v_mul_f32_e32 v0, v0, v9
	v_mul_f32_e32 v9, 0xbfb8aa3b, v9
	v_exp_f32_e32 v9, v9
	s_nop 0
	v_add_f32_e32 v9, 1.0, v9
	v_rcp_f32_e32 v9, v9
	s_nop 0
	v_mul_f32_e32 v0, v0, v9
	v_cvt_pk_bf16_f32 v0, v0, v0
	global_store_short v[6:7], v0, off offset:128
	v_mul_f32_e32 v0, v24, v54
	s_waitcnt vmcnt(31)
	v_lshlrev_b32_e32 v9, 16, v66
	v_mul_f32_e32 v0, v0, v9
	v_mul_f32_e32 v9, 0xbfb8aa3b, v9
	v_exp_f32_e32 v9, v9
	s_nop 0
	v_add_f32_e32 v9, 1.0, v9
	v_rcp_f32_e32 v9, v9
	s_nop 0
	v_mul_f32_e32 v0, v0, v9
	v_cvt_pk_bf16_f32 v0, v0, v0
	global_store_short v[6:7], v0, off offset:192
	v_add_u32_e32 v0, 0xaa00, v4
	v_lshl_add_u64 v[6:7], v[0:1], 1, v[2:3]
	v_mul_f32_e32 v0, v73, v49
	s_waitcnt vmcnt(31)
	v_lshlrev_b32_e32 v9, 16, v67
	v_mul_f32_e32 v0, v0, v9
	v_mul_f32_e32 v9, 0xbfb8aa3b, v9
	v_exp_f32_e32 v9, v9
	s_nop 0
	v_add_f32_e32 v9, 1.0, v9
	v_rcp_f32_e32 v9, v9
	s_nop 0
	v_mul_f32_e32 v0, v0, v9
	v_cvt_pk_bf16_f32 v0, v0, v0
	global_store_short v[6:7], v0, off
	v_mul_f32_e32 v0, v57, v49
	s_waitcnt vmcnt(31)
	v_lshlrev_b32_e32 v9, 16, v68
	v_mul_f32_e32 v0, v0, v9
	v_mul_f32_e32 v9, 0xbfb8aa3b, v9
	v_exp_f32_e32 v9, v9
	s_nop 0
	v_add_f32_e32 v9, 1.0, v9
	v_rcp_f32_e32 v9, v9
	s_nop 0
	v_mul_f32_e32 v0, v0, v9
	v_cvt_pk_bf16_f32 v0, v0, v0
	global_store_short v[6:7], v0, off offset:64
	v_mul_f32_e32 v0, v41, v49
	s_waitcnt vmcnt(31)
	v_lshlrev_b32_e32 v9, 16, v69
	v_mul_f32_e32 v0, v0, v9
	v_mul_f32_e32 v9, 0xbfb8aa3b, v9
	v_exp_f32_e32 v9, v9
	s_nop 0
	v_add_f32_e32 v9, 1.0, v9
	v_rcp_f32_e32 v9, v9
	s_nop 0
	v_mul_f32_e32 v0, v0, v9
	v_cvt_pk_bf16_f32 v0, v0, v0
	global_store_short v[6:7], v0, off offset:128
	v_mul_f32_e32 v0, v25, v49
	s_waitcnt vmcnt(31)
	v_lshlrev_b32_e32 v9, 16, v70
	v_mul_f32_e32 v0, v0, v9
	v_mul_f32_e32 v9, 0xbfb8aa3b, v9
	v_exp_f32_e32 v9, v9
	s_nop 0
	v_add_f32_e32 v9, 1.0, v9
	v_rcp_f32_e32 v9, v9
	s_nop 0
	v_mul_f32_e32 v0, v0, v9
	v_cvt_pk_bf16_f32 v0, v0, v0
	global_store_short v[6:7], v0, off offset:192
	v_add_u32_e32 v0, 0xb400, v4
	v_lshl_add_u64 v[6:7], v[0:1], 1, v[2:3]
	v_mul_f32_e32 v0, v74, v36
	s_waitcnt vmcnt(31)
	v_lshlrev_b32_e32 v9, 16, v71
	v_mul_f32_e32 v0, v0, v9
	v_mul_f32_e32 v9, 0xbfb8aa3b, v9
	v_exp_f32_e32 v9, v9
	s_nop 0
	v_add_f32_e32 v9, 1.0, v9
	v_rcp_f32_e32 v9, v9
	s_nop 0
	v_mul_f32_e32 v0, v0, v9
	v_cvt_pk_bf16_f32 v0, v0, v0
	global_store_short v[6:7], v0, off
	v_mul_f32_e32 v0, v58, v36
	s_waitcnt vmcnt(31)
	v_lshlrev_b32_e32 v9, 16, v72
	v_mul_f32_e32 v0, v0, v9
	v_mul_f32_e32 v9, 0xbfb8aa3b, v9
	v_exp_f32_e32 v9, v9
	s_nop 0
	v_add_f32_e32 v9, 1.0, v9
	v_rcp_f32_e32 v9, v9
	s_nop 0
	v_mul_f32_e32 v0, v0, v9
	v_cvt_pk_bf16_f32 v0, v0, v0
	global_store_short v[6:7], v0, off offset:64
	v_mul_f32_e32 v0, v42, v36
	s_waitcnt vmcnt(31)
	v_lshlrev_b32_e32 v9, 16, v55
	v_mul_f32_e32 v0, v0, v9
	v_mul_f32_e32 v9, 0xbfb8aa3b, v9
	v_exp_f32_e32 v9, v9
	s_nop 0
	v_add_f32_e32 v9, 1.0, v9
	v_rcp_f32_e32 v9, v9
	s_nop 0
	v_mul_f32_e32 v0, v0, v9
	v_cvt_pk_bf16_f32 v0, v0, v0
	global_store_short v[6:7], v0, off offset:128
	v_mul_f32_e32 v0, v26, v36
	s_waitcnt vmcnt(31)
	v_lshlrev_b32_e32 v9, 16, v53
	v_mul_f32_e32 v0, v0, v9
	v_mul_f32_e32 v9, 0xbfb8aa3b, v9
	v_exp_f32_e32 v9, v9
	s_nop 0
	v_add_f32_e32 v9, 1.0, v9
	v_rcp_f32_e32 v9, v9
	s_nop 0
	v_mul_f32_e32 v0, v0, v9
	v_cvt_pk_bf16_f32 v0, v0, v0
	global_store_short v[6:7], v0, off offset:192
	v_add_u32_e32 v0, 0xbe00, v4
	v_lshl_add_u64 v[6:7], v[0:1], 1, v[2:3]
	v_mul_f32_e32 v0, v75, v33
	s_waitcnt vmcnt(31)
	v_lshlrev_b32_e32 v9, 16, v52
	v_mul_f32_e32 v0, v0, v9
	v_mul_f32_e32 v9, 0xbfb8aa3b, v9
	v_exp_f32_e32 v9, v9
	s_nop 0
	v_add_f32_e32 v9, 1.0, v9
	v_rcp_f32_e32 v9, v9
	s_nop 0
	v_mul_f32_e32 v0, v0, v9
	v_cvt_pk_bf16_f32 v0, v0, v0
	global_store_short v[6:7], v0, off
	v_mul_f32_e32 v0, v59, v33
	s_waitcnt vmcnt(31)
	v_lshlrev_b32_e32 v9, 16, v51
	v_mul_f32_e32 v0, v0, v9
	v_mul_f32_e32 v9, 0xbfb8aa3b, v9
	v_exp_f32_e32 v9, v9
	s_nop 0
	v_add_f32_e32 v9, 1.0, v9
	v_rcp_f32_e32 v9, v9
	s_nop 0
	v_mul_f32_e32 v0, v0, v9
	v_cvt_pk_bf16_f32 v0, v0, v0
	global_store_short v[6:7], v0, off offset:64
	v_mul_f32_e32 v0, v43, v33
	s_waitcnt vmcnt(31)
	v_lshlrev_b32_e32 v9, 16, v50
	v_mul_f32_e32 v0, v0, v9
	v_mul_f32_e32 v9, 0xbfb8aa3b, v9
	v_exp_f32_e32 v9, v9
	s_nop 0
	v_add_f32_e32 v9, 1.0, v9
	v_rcp_f32_e32 v9, v9
	s_nop 0
	v_mul_f32_e32 v0, v0, v9
	v_cvt_pk_bf16_f32 v0, v0, v0
	global_store_short v[6:7], v0, off offset:128
	v_mul_f32_e32 v0, v27, v33
	s_waitcnt vmcnt(31)
	v_lshlrev_b32_e32 v9, 16, v48
	v_mul_f32_e32 v0, v0, v9
	v_mul_f32_e32 v9, 0xbfb8aa3b, v9
	v_exp_f32_e32 v9, v9
	s_nop 0
	v_add_f32_e32 v9, 1.0, v9
	v_rcp_f32_e32 v9, v9
	s_nop 0
	v_mul_f32_e32 v0, v0, v9
	v_cvt_pk_bf16_f32 v0, v0, v0
	global_store_short v[6:7], v0, off offset:192
	v_add_u32_e32 v0, 0xf000, v4
	v_lshl_add_u64 v[6:7], v[0:1], 1, v[2:3]
	v_mul_f32_e32 v0, v76, v32
	s_waitcnt vmcnt(31)
	v_lshlrev_b32_e32 v9, 16, v39
	v_mul_f32_e32 v0, v0, v9
	v_mul_f32_e32 v9, 0xbfb8aa3b, v9
	v_exp_f32_e32 v9, v9
	s_nop 0
	v_add_f32_e32 v9, 1.0, v9
	v_rcp_f32_e32 v9, v9
	s_nop 0
	v_mul_f32_e32 v0, v0, v9
	v_cvt_pk_bf16_f32 v0, v0, v0
	global_store_short v[6:7], v0, off
	v_mul_f32_e32 v0, v60, v32
	s_waitcnt vmcnt(31)
	v_lshlrev_b32_e32 v9, 16, v38
	v_mul_f32_e32 v0, v0, v9
	v_mul_f32_e32 v9, 0xbfb8aa3b, v9
	v_exp_f32_e32 v9, v9
	s_nop 0
	v_add_f32_e32 v9, 1.0, v9
	v_rcp_f32_e32 v9, v9
	s_nop 0
	v_mul_f32_e32 v0, v0, v9
	v_cvt_pk_bf16_f32 v0, v0, v0
	global_store_short v[6:7], v0, off offset:64
	v_mul_f32_e32 v0, v44, v32
	s_waitcnt vmcnt(31)
	v_lshlrev_b32_e32 v9, 16, v37
	v_mul_f32_e32 v0, v0, v9
	v_mul_f32_e32 v9, 0xbfb8aa3b, v9
	v_exp_f32_e32 v9, v9
	s_nop 0
	v_add_f32_e32 v9, 1.0, v9
	v_rcp_f32_e32 v9, v9
	s_nop 0
	v_mul_f32_e32 v0, v0, v9
	v_cvt_pk_bf16_f32 v0, v0, v0
	global_store_short v[6:7], v0, off offset:128
	v_mul_f32_e32 v0, v28, v32
	s_waitcnt vmcnt(31)
	v_lshlrev_b32_e32 v9, 16, v35
	v_mul_f32_e32 v0, v0, v9
	v_mul_f32_e32 v9, 0xbfb8aa3b, v9
	v_exp_f32_e32 v9, v9
	s_nop 0
	v_add_f32_e32 v9, 1.0, v9
	v_rcp_f32_e32 v9, v9
	s_nop 0
	v_mul_f32_e32 v0, v0, v9
	v_cvt_pk_bf16_f32 v0, v0, v0
	global_store_short v[6:7], v0, off offset:192
	v_add_u32_e32 v0, 0xfa00, v4
	v_lshl_add_u64 v[6:7], v[0:1], 1, v[2:3]
	v_mul_f32_e32 v0, v77, v23
	s_waitcnt vmcnt(31)
	v_lshlrev_b32_e32 v9, 16, v34
	v_mul_f32_e32 v0, v0, v9
	v_mul_f32_e32 v9, 0xbfb8aa3b, v9
	v_exp_f32_e32 v9, v9
	s_nop 0
	v_add_f32_e32 v9, 1.0, v9
	v_rcp_f32_e32 v9, v9
	s_nop 0
	v_mul_f32_e32 v0, v0, v9
	v_cvt_pk_bf16_f32 v0, v0, v0
	global_store_short v[6:7], v0, off
	v_mul_f32_e32 v0, v61, v23
	s_waitcnt vmcnt(31)
	v_lshlrev_b32_e32 v9, 16, v21
	v_mul_f32_e32 v0, v0, v9
	v_mul_f32_e32 v9, 0xbfb8aa3b, v9
	v_exp_f32_e32 v9, v9
	s_nop 0
	v_add_f32_e32 v9, 1.0, v9
	v_rcp_f32_e32 v9, v9
	s_nop 0
	v_mul_f32_e32 v0, v0, v9
	v_cvt_pk_bf16_f32 v0, v0, v0
	global_store_short v[6:7], v0, off offset:64
	v_mul_f32_e32 v0, v45, v23
	s_waitcnt vmcnt(31)
	v_lshlrev_b32_e32 v9, 16, v20
	v_mul_f32_e32 v0, v0, v9
	v_mul_f32_e32 v9, 0xbfb8aa3b, v9
	v_exp_f32_e32 v9, v9
	s_nop 0
	v_add_f32_e32 v9, 1.0, v9
	v_rcp_f32_e32 v9, v9
	s_nop 0
	v_mul_f32_e32 v0, v0, v9
	v_cvt_pk_bf16_f32 v0, v0, v0
	global_store_short v[6:7], v0, off offset:128
	v_mul_f32_e32 v0, v29, v23
	s_waitcnt vmcnt(31)
	v_lshlrev_b32_e32 v9, 16, v17
	v_mul_f32_e32 v0, v0, v9
	v_mul_f32_e32 v9, 0xbfb8aa3b, v9
	v_exp_f32_e32 v9, v9
	s_nop 0
	v_add_f32_e32 v9, 1.0, v9
	v_rcp_f32_e32 v9, v9
	s_nop 0
	v_mul_f32_e32 v0, v0, v9
	v_cvt_pk_bf16_f32 v0, v0, v0
	global_store_short v[6:7], v0, off offset:192
	v_add_u32_e32 v0, 0x10400, v4
	v_lshl_add_u64 v[6:7], v[0:1], 1, v[2:3]
	v_mul_f32_e32 v0, v78, v22
	s_waitcnt vmcnt(31)
	v_lshlrev_b32_e32 v9, 16, v16
	v_mul_f32_e32 v0, v0, v9
	v_mul_f32_e32 v9, 0xbfb8aa3b, v9
	v_exp_f32_e32 v9, v9
	s_nop 0
	v_add_f32_e32 v9, 1.0, v9
	v_rcp_f32_e32 v9, v9
	s_nop 0
	v_mul_f32_e32 v0, v0, v9
	v_cvt_pk_bf16_f32 v0, v0, v0
	global_store_short v[6:7], v0, off
	v_mul_f32_e32 v0, v62, v22
	s_waitcnt vmcnt(31)
	v_lshlrev_b32_e32 v9, 16, v15
	v_mul_f32_e32 v0, v0, v9
	v_mul_f32_e32 v9, 0xbfb8aa3b, v9
	v_exp_f32_e32 v9, v9
	s_nop 0
	v_add_f32_e32 v9, 1.0, v9
	v_rcp_f32_e32 v9, v9
	s_nop 0
	v_mul_f32_e32 v0, v0, v9
	v_cvt_pk_bf16_f32 v0, v0, v0
	global_store_short v[6:7], v0, off offset:64
	v_mul_f32_e32 v0, v46, v22
	s_waitcnt vmcnt(31)
	v_lshlrev_b32_e32 v9, 16, v14
	v_mul_f32_e32 v0, v0, v9
	v_mul_f32_e32 v9, 0xbfb8aa3b, v9
	v_exp_f32_e32 v9, v9
	s_nop 0
	v_add_f32_e32 v9, 1.0, v9
	v_rcp_f32_e32 v9, v9
	s_nop 0
	v_mul_f32_e32 v0, v0, v9
	v_cvt_pk_bf16_f32 v0, v0, v0
	global_store_short v[6:7], v0, off offset:128
	v_mul_f32_e32 v0, v30, v22
	s_waitcnt vmcnt(31)
	v_lshlrev_b32_e32 v9, 16, v13
	v_mul_f32_e32 v0, v0, v9
	v_mul_f32_e32 v9, 0xbfb8aa3b, v9
	v_exp_f32_e32 v9, v9
	s_nop 0
	v_add_f32_e32 v9, 1.0, v9
	v_rcp_f32_e32 v9, v9
	s_nop 0
	v_mul_f32_e32 v0, v0, v9
	v_cvt_pk_bf16_f32 v0, v0, v0
	global_store_short v[6:7], v0, off offset:192
	v_add_u32_e32 v0, 0x10e00, v4
	v_lshl_add_u64 v[2:3], v[0:1], 1, v[2:3]
	v_mul_f32_e32 v0, v79, v5
	s_waitcnt vmcnt(31)
	v_lshlrev_b32_e32 v4, 16, v12
	v_mul_f32_e32 v0, v0, v4
	v_mul_f32_e32 v4, 0xbfb8aa3b, v4
	v_exp_f32_e32 v4, v4
	s_nop 0
	v_add_f32_e32 v4, 1.0, v4
	v_rcp_f32_e32 v4, v4
	s_nop 0
	v_mul_f32_e32 v0, v0, v4
	v_cvt_pk_bf16_f32 v0, v0, v0
	global_store_short v[2:3], v0, off
	v_mul_f32_e32 v0, v63, v5
	s_waitcnt vmcnt(31)
	v_lshlrev_b32_e32 v4, 16, v11
	v_mul_f32_e32 v0, v0, v4
	v_mul_f32_e32 v4, 0xbfb8aa3b, v4
	v_exp_f32_e32 v4, v4
	s_nop 0
	v_add_f32_e32 v4, 1.0, v4
	v_rcp_f32_e32 v4, v4
	s_nop 0
	v_mul_f32_e32 v0, v0, v4
	v_cvt_pk_bf16_f32 v0, v0, v0
	global_store_short v[2:3], v0, off offset:64
	v_mul_f32_e32 v0, v47, v5
	s_waitcnt vmcnt(31)
	v_lshlrev_b32_e32 v4, 16, v10
	v_mul_f32_e32 v0, v0, v4
	v_mul_f32_e32 v4, 0xbfb8aa3b, v4
	v_exp_f32_e32 v4, v4
	s_nop 0
	v_add_f32_e32 v4, 1.0, v4
	v_rcp_f32_e32 v4, v4
	s_nop 0
	v_mul_f32_e32 v0, v0, v4
	v_cvt_pk_bf16_f32 v0, v0, v0
	global_store_short v[2:3], v0, off offset:128
	v_mul_f32_e32 v0, v31, v5
	s_waitcnt vmcnt(31)
	v_lshlrev_b32_e32 v4, 16, v8
	v_mul_f32_e32 v0, v0, v4
	v_mul_f32_e32 v4, 0xbfb8aa3b, v4
	v_exp_f32_e32 v4, v4
	s_nop 0
	v_add_f32_e32 v4, 1.0, v4
	v_rcp_f32_e32 v4, v4
	s_nop 0
	v_mul_f32_e32 v0, v0, v4
	v_cvt_pk_bf16_f32 v0, v0, v0
	global_store_short v[2:3], v0, off offset:192
	s_cbranch_vccnz .LBB0_1103
.LBB0_1128:
	s_xor_b64 s[34:35], s[16:17], -1
	s_and_b64 s[16:17], s[16:17], exec
	s_cselect_b32 s16, s51, s50
	s_lshl_b32 s52, s16, 8
	s_or_b32 s2, s52, s49
	v_add_u32_e32 v0, s2, v158
	s_movk_i32 s17, 0x4a00
	v_mad_i64_i32 v[30:31], s[20:21], v0, s17, v[150:151]
	global_load_dwordx4 v[2:5], v[30:31], off
	global_load_dwordx4 v[6:9], v[30:31], off offset:32
	global_load_dwordx4 v[10:13], v[30:31], off offset:64
	global_load_dwordx4 v[14:17], v[30:31], off offset:96
	global_load_dwordx4 v[18:21], v[30:31], off offset:128
	global_load_dwordx4 v[22:25], v[30:31], off offset:160
	global_load_dwordx4 v[26:29], v[30:31], off offset:192
	s_nop 0
	global_load_dwordx4 v[30:33], v[30:31], off offset:224
	v_mov_b32_e32 v153, v1
	s_lshl_b32 s57, s16, 2
	s_add_i32 s57, s57, 4
	v_readlane_b32 s16, v254, 1
	v_add_u32_e32 v170, s52, v157
	s_mov_b32 s56, 2
	v_or_b32_e32 v171, 31, v170
	s_mov_b32 s58, 0
	v_mov_b32_e32 v169, 0
	v_mov_b32_e32 v173, 0xf149f2ca
	s_movk_i32 s59, 0xff00
	s_mov_b32 s60, 0
	s_mov_b32 s53, 0
	s_waitcnt vmcnt(7)
	v_lshlrev_b32_e32 v0, 16, v2
	v_and_b32_e32 v2, 0xffff0000, v2
	s_waitcnt vmcnt(6)
	v_lshlrev_b32_e32 v39, 16, v8
	v_and_b32_e32 v8, 0xffff0000, v8
	v_mul_f32_e32 v0, 0x3e0293ee, v0
	v_lshlrev_b32_e32 v34, 16, v3
	v_and_b32_e32 v3, 0xffff0000, v3
	v_lshlrev_b32_e32 v35, 16, v4
	v_and_b32_e32 v4, 0xffff0000, v4
	v_lshlrev_b32_e32 v36, 16, v5
	v_and_b32_e32 v5, 0xffff0000, v5
	v_lshlrev_b32_e32 v37, 16, v6
	v_and_b32_e32 v6, 0xffff0000, v6
	v_lshlrev_b32_e32 v38, 16, v7
	v_and_b32_e32 v7, 0xffff0000, v7
	v_mul_f32_e32 v2, 0x3e0293ee, v2
	v_mul_f32_e32 v8, 0x3e0293ee, v8
	v_cvt_pk_bf16_f32 v112, v0, v2
	s_waitcnt vmcnt(4)
	v_and_b32_e32 v0, 0xffff0000, v17
	v_lshlrev_b32_e32 v40, 16, v9
	v_and_b32_e32 v9, 0xffff0000, v9
	v_lshlrev_b32_e32 v41, 16, v10
	v_and_b32_e32 v10, 0xffff0000, v10
	v_lshlrev_b32_e32 v42, 16, v11
	v_and_b32_e32 v11, 0xffff0000, v11
	v_lshlrev_b32_e32 v43, 16, v12
	v_and_b32_e32 v12, 0xffff0000, v12
	v_lshlrev_b32_e32 v44, 16, v13
	v_and_b32_e32 v13, 0xffff0000, v13
	v_lshlrev_b32_e32 v45, 16, v14
	v_and_b32_e32 v14, 0xffff0000, v14
	v_lshlrev_b32_e32 v46, 16, v15
	v_and_b32_e32 v15, 0xffff0000, v15
	v_lshlrev_b32_e32 v47, 16, v16
	v_and_b32_e32 v16, 0xffff0000, v16
	v_lshlrev_b32_e32 v48, 16, v17
	v_mul_f32_e32 v34, 0x3e0293ee, v34
	v_mul_f32_e32 v3, 0x3e0293ee, v3
	v_mul_f32_e32 v35, 0x3e0293ee, v35
	v_mul_f32_e32 v4, 0x3e0293ee, v4
	v_mul_f32_e32 v36, 0x3e0293ee, v36
	v_mul_f32_e32 v5, 0x3e0293ee, v5
	v_mul_f32_e32 v37, 0x3e0293ee, v37
	v_mul_f32_e32 v6, 0x3e0293ee, v6
	v_mul_f32_e32 v38, 0x3e0293ee, v38
	v_mul_f32_e32 v7, 0x3e0293ee, v7
	v_mul_f32_e32 v39, 0x3e0293ee, v39
	v_cvt_pk_bf16_f32 v113, v34, v3
	v_cvt_pk_bf16_f32 v114, v35, v4
	v_cvt_pk_bf16_f32 v115, v36, v5
	v_cvt_pk_bf16_f32 v116, v37, v6
	v_cvt_pk_bf16_f32 v117, v38, v7
	v_cvt_pk_bf16_f32 v118, v39, v8
	v_mul_f32_e32 v0, 0x3e0293ee, v0
	s_waitcnt vmcnt(3)
	v_and_b32_e32 v8, 0xffff0000, v21
	v_mul_f32_e32 v40, 0x3e0293ee, v40
	v_mul_f32_e32 v9, 0x3e0293ee, v9
	v_mul_f32_e32 v41, 0x3e0293ee, v41
	v_mul_f32_e32 v10, 0x3e0293ee, v10
	v_mul_f32_e32 v42, 0x3e0293ee, v42
	v_mul_f32_e32 v11, 0x3e0293ee, v11
	v_mul_f32_e32 v43, 0x3e0293ee, v43
	v_mul_f32_e32 v12, 0x3e0293ee, v12
	v_mul_f32_e32 v44, 0x3e0293ee, v44
	v_mul_f32_e32 v13, 0x3e0293ee, v13
	v_mul_f32_e32 v45, 0x3e0293ee, v45
	v_mul_f32_e32 v14, 0x3e0293ee, v14
	v_mul_f32_e32 v46, 0x3e0293ee, v46
	v_mul_f32_e32 v15, 0x3e0293ee, v15
	v_mul_f32_e32 v47, 0x3e0293ee, v47
	v_mul_f32_e32 v16, 0x3e0293ee, v16
	v_mul_f32_e32 v48, 0x3e0293ee, v48
	v_cvt_pk_bf16_f32 v119, v40, v9
	v_cvt_pk_bf16_f32 v120, v41, v10
	v_cvt_pk_bf16_f32 v121, v42, v11
	v_cvt_pk_bf16_f32 v122, v43, v12
	v_cvt_pk_bf16_f32 v123, v44, v13
	v_cvt_pk_bf16_f32 v124, v45, v14
	v_cvt_pk_bf16_f32 v125, v46, v15
	v_cvt_pk_bf16_f32 v126, v47, v16
	v_cvt_pk_bf16_f32 v127, v48, v0
	v_lshlrev_b32_e32 v0, 16, v18
	v_and_b32_e32 v2, 0xffff0000, v18
	v_lshlrev_b32_e32 v3, 16, v19
	v_and_b32_e32 v4, 0xffff0000, v19
	v_lshlrev_b32_e32 v5, 16, v20
	v_and_b32_e32 v6, 0xffff0000, v20
	v_lshlrev_b32_e32 v7, 16, v21
	v_mul_f32_e32 v8, 0x3e0293ee, v8
	v_mul_f32_e32 v0, 0x3e0293ee, v0
	v_mul_f32_e32 v2, 0x3e0293ee, v2
	v_mul_f32_e32 v3, 0x3e0293ee, v3
	v_mul_f32_e32 v4, 0x3e0293ee, v4
	v_mul_f32_e32 v5, 0x3e0293ee, v5
	v_mul_f32_e32 v6, 0x3e0293ee, v6
	v_mul_f32_e32 v7, 0x3e0293ee, v7
	v_cvt_pk_bf16_f32 v128, v0, v2
	v_cvt_pk_bf16_f32 v129, v3, v4
	v_cvt_pk_bf16_f32 v130, v5, v6
	v_cvt_pk_bf16_f32 v131, v7, v8
	s_waitcnt vmcnt(2)
	v_and_b32_e32 v8, 0xffff0000, v25
	v_lshlrev_b32_e32 v0, 16, v22
	v_and_b32_e32 v2, 0xffff0000, v22
	v_lshlrev_b32_e32 v3, 16, v23
	v_and_b32_e32 v4, 0xffff0000, v23
	v_lshlrev_b32_e32 v5, 16, v24
	v_and_b32_e32 v6, 0xffff0000, v24
	v_lshlrev_b32_e32 v7, 16, v25
	v_mul_f32_e32 v8, 0x3e0293ee, v8
	v_mul_f32_e32 v0, 0x3e0293ee, v0
	v_mul_f32_e32 v2, 0x3e0293ee, v2
	v_mul_f32_e32 v3, 0x3e0293ee, v3
	v_mul_f32_e32 v4, 0x3e0293ee, v4
	v_mul_f32_e32 v5, 0x3e0293ee, v5
	v_mul_f32_e32 v6, 0x3e0293ee, v6
	v_mul_f32_e32 v7, 0x3e0293ee, v7
	v_cvt_pk_bf16_f32 v132, v0, v2
	v_cvt_pk_bf16_f32 v133, v3, v4
	v_cvt_pk_bf16_f32 v134, v5, v6
	v_cvt_pk_bf16_f32 v135, v7, v8
	s_waitcnt vmcnt(1)
	v_and_b32_e32 v8, 0xffff0000, v29
	v_lshlrev_b32_e32 v0, 16, v26
	v_and_b32_e32 v2, 0xffff0000, v26
	v_lshlrev_b32_e32 v3, 16, v27
	v_and_b32_e32 v4, 0xffff0000, v27
	v_lshlrev_b32_e32 v5, 16, v28
	v_and_b32_e32 v6, 0xffff0000, v28
	v_lshlrev_b32_e32 v7, 16, v29
	v_mul_f32_e32 v8, 0x3e0293ee, v8
	v_mul_f32_e32 v0, 0x3e0293ee, v0
	v_mul_f32_e32 v2, 0x3e0293ee, v2
	v_mul_f32_e32 v3, 0x3e0293ee, v3
	v_mul_f32_e32 v4, 0x3e0293ee, v4
	v_mul_f32_e32 v5, 0x3e0293ee, v5
	v_mul_f32_e32 v6, 0x3e0293ee, v6
	v_mul_f32_e32 v7, 0x3e0293ee, v7
	v_cvt_pk_bf16_f32 v136, v0, v2
	v_cvt_pk_bf16_f32 v137, v3, v4
	v_cvt_pk_bf16_f32 v138, v5, v6
	v_cvt_pk_bf16_f32 v139, v7, v8
	s_waitcnt vmcnt(0)
	v_and_b32_e32 v8, 0xffff0000, v33
	v_lshlrev_b32_e32 v0, 16, v30
	v_and_b32_e32 v2, 0xffff0000, v30
	v_lshlrev_b32_e32 v3, 16, v31
	v_and_b32_e32 v4, 0xffff0000, v31
	v_lshlrev_b32_e32 v5, 16, v32
	v_and_b32_e32 v6, 0xffff0000, v32
	v_lshlrev_b32_e32 v7, 16, v33
	v_mul_f32_e32 v8, 0x3e0293ee, v8
	v_mul_f32_e32 v0, 0x3e0293ee, v0
	v_mul_f32_e32 v2, 0x3e0293ee, v2
	v_mul_f32_e32 v3, 0x3e0293ee, v3
	v_mul_f32_e32 v4, 0x3e0293ee, v4
	v_mul_f32_e32 v5, 0x3e0293ee, v5
	v_mul_f32_e32 v6, 0x3e0293ee, v6
	v_mul_f32_e32 v7, 0x3e0293ee, v7
	v_cvt_pk_bf16_f32 v140, v0, v2
	v_cvt_pk_bf16_f32 v141, v3, v4
	v_cvt_pk_bf16_f32 v142, v5, v6
	v_cvt_pk_bf16_f32 v143, v7, v8
	v_mov_b32_e32 v8, v198
	v_mov_b32_e32 v3, 0xfffff3
	v_readfirstlane_b32 s17, v8
	s_ashr_i32 s20, s17, 6
	s_lshl_b32 s17, s20, 3
	v_bfe_u32 v0, v8, 2, 3
	v_bitop3_b32 v0, s17, v3, v0 bitop3:0xc8
	v_lshrrev_b32_e32 v3, 1, v8
	s_lshl_b32 s21, s20, 2
	v_bfe_u32 v9, v8, 4, 2
	v_and_b32_e32 v3, 8, v3
	s_and_b32 s21, s21, 4
	v_or3_b32 v0, v3, v0, s21
	v_bitop3_b32 v6, v9, v8, 15 bitop3:0x78
	v_mul_u32_u24_e32 v5, 0x2500, v0
	v_or_b32_e32 v0, s17, v9
	v_lshlrev_b32_e32 v10, 3, v6
	v_or_b32_e32 v6, 4, v9
	v_and_b32_e32 v2, 15, v8
	v_lshlrev_b32_e32 v4, 3, v8
	v_mul_lo_u32 v0, v0, s40
	v_or_b32_e32 v6, s17, v6
	s_lshl_b32 s17, s20, 11
	s_add_i32 s21, 0, 0x10000
	v_and_b32_e32 v3, 32, v8
	v_and_b32_e32 v4, 24, v4
	v_or_b32_e32 v0, v0, v10
	v_bitop3_b32 v2, v9, v2, 4 bitop3:0x36
	s_add_i32 s54, s21, s17
	v_lshlrev_b32_e32 v11, 3, v2
	v_mul_lo_u32 v2, v6, s40
	v_or3_b32 v152, v3, v4, v5
	v_lshl_add_u64 v[6:7], v[0:1], 1, s[24:25]
	s_mov_b32 m0, s54
	s_add_i32 s55, s17, 0
	v_or_b32_e32 v2, v2, v11
	global_load_lds_dwordx4 v[6:7], off
	v_lshl_add_u64 v[6:7], v[152:153], 1, s[26:27]
	s_mov_b32 m0, s55
	v_mov_b32_e32 v3, v1
	s_or_b32 s36, s17, 0x400
	v_or_b32_e32 v4, 64, v152
	global_load_lds_dwordx4 v[6:7], off
	v_lshl_add_u64 v[6:7], v[2:3], 1, s[24:25]
	s_add_i32 m0, s21, s36
	v_mov_b32_e32 v5, v1
	global_load_lds_dwordx4 v[6:7], off
	v_lshl_add_u64 v[4:5], v[4:5], 1, s[26:27]
	s_add_i32 m0, s55, 0x400
	v_add_u32_e32 v0, 0x94000, v0
	s_add_i32 s21, 0, 0x14000
	global_load_lds_dwordx4 v[4:5], off
	v_lshl_add_u64 v[4:5], v[0:1], 1, s[24:25]
	s_add_i32 m0, s21, s17
	v_add_u32_e32 v0, 0x94000, v152
	global_load_lds_dwordx4 v[4:5], off
	v_lshl_add_u64 v[4:5], v[0:1], 1, s[26:27]
	s_add_i32 m0, s55, 0x4000
	v_add_u32_e32 v0, 0x94000, v2
	global_load_lds_dwordx4 v[4:5], off
	v_lshl_add_u64 v[2:3], v[0:1], 1, s[24:25]
	s_add_i32 m0, s21, s36
	v_add_u32_e32 v0, 0x94040, v152
	global_load_lds_dwordx4 v[2:3], off
	v_lshl_add_u64 v[2:3], v[0:1], 1, s[26:27]
	s_add_i32 m0, s55, 0x4400
	v_and_b32_e32 v0, 63, v8
	global_load_lds_dwordx4 v[2:3], off
	v_and_b32_e32 v4, 0x3fffffc0, v8
	v_lshlrev_b32_e32 v5, 4, v8
	s_cmp_gt_i32 s20, 3
	v_bfe_u32 v3, v8, 5, 1
	v_lshl_add_u32 v166, v4, 2, s16
	v_lshlrev_b32_e32 v4, 3, v0
	v_and_b32_e32 v6, 0xc0, v5
	v_lshlrev_b32_e32 v7, 1, v8
	s_cselect_b64 s[36:37], -1, 0
	s_cmp_lt_i32 s20, 4
	v_and_or_b32 v6, v4, 24, v6
	v_and_b32_e32 v7, 32, v7
	v_and_b32_e32 v4, 0x100, v4
	v_lshlrev_b32_e32 v167, 4, v3
	s_movk_i32 s16, 0x70
	s_cselect_b64 s[38:39], -1, 0
	s_add_i32 s21, 0, 0x22800
	s_mul_i32 s20, s20, 0x12800
	v_or3_b32 v4, v6, v7, v4
	v_and_b32_e32 v6, 0x70, v5
	v_bitop3_b32 v174, v167, v5, s16 bitop3:0x78
	s_movk_i32 s16, 0x60
	v_add_u32_e32 v179, s21, v167
	s_add_i32 s21, s20, 0x131400
	v_bitop3_b32 v177, v167, v6, s16 bitop3:0x36
	v_cmp_gt_u32_e64 s[16:17], 32, v0
	v_mov_b32_e32 v0, s21
	v_mad_u32_u24 v0, v9, s40, v0
	s_add_i32 s20, s20, 0x128000
	v_or_b32_e32 v181, v0, v11
	v_mov_b32_e32 v0, s20
	v_and_b32_e32 v2, 31, v8
	s_waitcnt vmcnt(4)
	v_mad_u32_u24 v0, v9, s40, v0
	v_mov_b32_e32 v14, v1
	v_mov_b32_e32 v15, v1
	v_lshlrev_b32_e32 v172, 8, v2
	v_bitop3_b32 v175, v167, v6, 32 bitop3:0x36
	v_bitop3_b32 v176, v167, v6, 64 bitop3:0x36
	v_add_u32_e32 v153, 0, v4
	v_lshl_add_u32 v168, v2, 2, v166
	v_mad_i32_i24 v180, v3, -4, v158
	v_or_b32_e32 v182, v0, v10
	v_mov_b32_e32 v0, v1
	v_mov_b32_e32 v2, v1
	v_mov_b32_e32 v3, v1
	v_mov_b32_e32 v4, v1
	v_mov_b32_e32 v5, v1
	v_mov_b32_e32 v6, v1
	v_mov_b32_e32 v7, v1
	v_mov_b32_e32 v8, v1
	v_mov_b32_e32 v9, v1
	v_mov_b32_e32 v10, v1
	v_mov_b32_e32 v11, v1
	v_mov_b32_e32 v12, v1
	v_mov_b32_e32 v13, v1
	v_mov_b64_e32 v[30:31], v[14:15]
	v_mov_b64_e32 v[46:47], v[14:15]
	v_mov_b64_e32 v[62:63], v[14:15]
	v_mov_b64_e32 v[78:79], v[14:15]
	v_mov_b64_e32 v[94:95], v[14:15]
	v_mov_b64_e32 v[110:111], v[14:15]
	s_mov_b64 s[40:41], 0
	v_mov_b64_e32 v[28:29], v[12:13]
	v_mov_b64_e32 v[26:27], v[10:11]
	v_mov_b64_e32 v[24:25], v[8:9]
	v_mov_b64_e32 v[22:23], v[6:7]
	v_mov_b64_e32 v[20:21], v[4:5]
	v_mov_b64_e32 v[18:19], v[2:3]
	v_mov_b64_e32 v[16:17], v[0:1]
	v_mov_b64_e32 v[44:45], v[12:13]
	v_mov_b64_e32 v[42:43], v[10:11]
	v_mov_b64_e32 v[40:41], v[8:9]
	v_mov_b64_e32 v[38:39], v[6:7]
	v_mov_b64_e32 v[36:37], v[4:5]
	v_mov_b64_e32 v[34:35], v[2:3]
	v_mov_b64_e32 v[32:33], v[0:1]
	v_mov_b64_e32 v[60:61], v[12:13]
	v_mov_b64_e32 v[58:59], v[10:11]
	v_mov_b64_e32 v[56:57], v[8:9]
	v_mov_b64_e32 v[54:55], v[6:7]
	v_mov_b64_e32 v[52:53], v[4:5]
	v_mov_b64_e32 v[50:51], v[2:3]
	v_mov_b64_e32 v[48:49], v[0:1]
	v_mov_b64_e32 v[76:77], v[12:13]
	v_mov_b64_e32 v[74:75], v[10:11]
	v_mov_b64_e32 v[72:73], v[8:9]
	v_mov_b64_e32 v[70:71], v[6:7]
	v_mov_b64_e32 v[68:69], v[4:5]
	v_mov_b64_e32 v[66:67], v[2:3]
	v_mov_b64_e32 v[64:65], v[0:1]
	v_mov_b64_e32 v[92:93], v[12:13]
	v_mov_b64_e32 v[90:91], v[10:11]
	v_mov_b64_e32 v[88:89], v[8:9]
	v_mov_b64_e32 v[86:87], v[6:7]
	v_mov_b64_e32 v[84:85], v[4:5]
	v_mov_b64_e32 v[82:83], v[2:3]
	v_mov_b64_e32 v[80:81], v[0:1]
	v_mov_b64_e32 v[108:109], v[12:13]
	v_mov_b64_e32 v[106:107], v[10:11]
	v_mov_b64_e32 v[104:105], v[8:9]
	v_mov_b64_e32 v[102:103], v[6:7]
	v_mov_b64_e32 v[100:101], v[4:5]
	v_mov_b64_e32 v[98:99], v[2:3]
	v_mov_b64_e32 v[96:97], v[0:1]
	s_waitcnt vmcnt(4) lgkmcnt(0)
	s_barrier
	s_branch .LBB0_1130
.LBB0_1129:
	s_add_i32 s20, s60, 1
	s_cmp_lg_u32 s60, 2
	s_cselect_b32 s60, s20, 0
	s_add_i32 s20, s53, 1
	s_and_b32 s53, s20, 3
	s_add_i32 s59, s59, 64
	s_add_i32 s58, s58, 0x94000
	s_add_i32 s56, s56, 1
	v_add_u32_e32 v179, 0x100, v179
	s_cmp_lg_u32 s52, s59
	v_subrev_u32_e32 v180, 64, v180
	s_waitcnt vmcnt(4) lgkmcnt(0)
	s_barrier
	s_cbranch_scc0 .LBB0_1152

.LBB0_1247:
	s_or_b64 exec, exec, s[0:1]
	s_lshl_b32 s0, s10, 7
	s_ashr_i32 s1, s0, 31
	s_lshl_b64 s[0:1], s[0:1], 1
	v_readlane_b32 s2, v253, 2
	s_add_u32 s4, s2, s0
	v_readlane_b32 s2, v253, 3
	s_addc_u32 s5, s2, s1
	v_readlane_b32 s6, v251, 9
	v_readlane_b32 s7, v251, 10
	s_add_u32 s0, s6, s0
	s_addc_u32 s1, s7, s1
	v_lshlrev_b32_e32 v0, 1, v0
	v_lshl_add_u64 v[70:71], s[4:5], 0, v[0:1]
	v_lshl_add_u64 v[66:67], s[0:1], 0, v[0:1]
	v_lshlrev_b32_e32 v0, 2, v72
	v_and_b32_e32 v0, 0xffffff00, v0
	v_lshl_or_b32 v0, v68, 5, v0
	s_waitcnt lgkmcnt(0)
	v_add_u32_e32 v72, s31, v0
	s_movk_i32 s0, 0x2200
	v_lshl_add_u32 v90, v68, 4, v69
	v_mul_lo_u32 v0, v72, s0
	ds_read_b128 v[78:81], v90
	ds_read_b128 v[98:101], v90 offset:32
	v_add_u32_e32 v68, 0x11000, v0
	v_mov_b32_e32 v69, v1
	v_lshl_add_u64 v[74:75], v[68:69], 1, v[70:71]
	v_add_u32_e32 v68, 0x22000, v0
	v_lshl_add_u64 v[76:77], v[68:69], 1, v[70:71]
	v_add_u32_e32 v68, 0x33000, v0
	s_waitcnt lgkmcnt(1)
	v_rcp_f32_e32 v107, v78
	v_rcp_f32_e32 v102, v79
	v_lshl_add_u64 v[78:79], v[68:69], 1, v[70:71]
	v_add_u32_e32 v68, 0x88000, v0
	v_rcp_f32_e32 v97, v80
	v_rcp_f32_e32 v95, v81
	v_lshl_add_u64 v[80:81], v[68:69], 1, v[70:71]
	v_add_u32_e32 v68, 0x99000, v0
	v_lshl_add_u64 v[82:83], v[68:69], 1, v[70:71]
	v_add_u32_e32 v68, 0xaa000, v0
	v_lshl_add_u64 v[84:85], v[68:69], 1, v[70:71]
	v_add_u32_e32 v68, 0xbb000, v0
	s_movk_i32 s0, 0x500
	v_lshl_add_u64 v[88:89], v[0:1], 1, v[70:71]
	v_lshl_add_u64 v[86:87], v[68:69], 1, v[70:71]
	v_mul_lo_u32 v68, v72, s0
	v_lshl_add_u64 v[72:73], v[68:69], 1, v[66:67]
	global_load_ushort v201, v[88:89], off
	v_mul_f32_e32 v50, v50, v107
	s_waitcnt lgkmcnt(0)
	v_rcp_f32_e32 v94, v98
	v_rcp_f32_e32 v93, v99
	v_rcp_f32_e32 v92, v100
	v_rcp_f32_e32 v91, v101
	v_mul_f32_e32 v34, v34, v107
	v_mul_f32_e32 v18, v18, v107
	v_mul_f32_e32 v2, v2, v107
	v_mul_f32_e32 v4, v4, v97
	s_add_i32 s30, s30, s80
	s_cmpk_gt_i32 s30, 0xbf
	v_mov_b32_e32 v200, v50
	global_load_ushort v110, v[88:89], off offset:64
	global_load_ushort v111, v[88:89], off offset:128
	global_load_ushort v112, v[88:89], off offset:192
	global_load_ushort v113, v[74:75], off
	global_load_ushort v114, v[74:75], off offset:64
	global_load_ushort v115, v[74:75], off offset:128
	global_load_ushort v116, v[74:75], off offset:192
	global_load_ushort v117, v[76:77], off
	global_load_ushort v118, v[76:77], off offset:64
	global_load_ushort v108, v[76:77], off offset:128
	global_load_ushort v106, v[76:77], off offset:192
	global_load_ushort v105, v[78:79], off
	global_load_ushort v104, v[78:79], off offset:64
	global_load_ushort v103, v[78:79], off offset:128
	global_load_ushort v101, v[78:79], off offset:192
	global_load_ushort v100, v[80:81], off
	global_load_ushort v99, v[80:81], off offset:64
	global_load_ushort v98, v[80:81], off offset:128
	global_load_ushort v96, v[80:81], off offset:192
	global_load_ushort v89, v[82:83], off
	global_load_ushort v88, v[82:83], off offset:64
	s_nop 0
	global_load_ushort v81, v[82:83], off offset:128
	global_load_ushort v80, v[82:83], off offset:192
	global_load_ushort v79, v[84:85], off
	global_load_ushort v78, v[84:85], off offset:64
	global_load_ushort v77, v[84:85], off offset:128
	global_load_ushort v76, v[84:85], off offset:192
	global_load_ushort v75, v[86:87], off
	global_load_ushort v74, v[86:87], off offset:64
	global_load_ushort v69, v[86:87], off offset:128
	global_load_ushort v50, v[86:87], off offset:192
	s_waitcnt vmcnt(31)
	v_lshlrev_b32_e32 v201, 16, v201
	v_mul_f32_e32 v200, v200, v201
	v_mul_f32_e32 v201, 0xbfb8aa3b, v201
	v_exp_f32_e32 v201, v201
	s_nop 0
	v_add_f32_e32 v201, 1.0, v201
	v_rcp_f32_e32 v201, v201
	s_nop 0
	v_mul_f32_e32 v109, v201, v200
	v_cvt_pk_bf16_f32 v82, v109, v109
	global_store_short v[72:73], v82, off
	s_waitcnt vmcnt(31)
	v_lshlrev_b32_e32 v82, 16, v110
	v_mul_f32_e32 v34, v34, v82
	v_mul_f32_e32 v82, 0xbfb8aa3b, v82
	v_exp_f32_e32 v82, v82
	s_nop 0
	v_add_f32_e32 v82, 1.0, v82
	v_rcp_f32_e32 v82, v82
	s_nop 0
	v_mul_f32_e32 v34, v34, v82
	v_cvt_pk_bf16_f32 v34, v34, v34
	global_store_short v[72:73], v34, off offset:64
	s_waitcnt vmcnt(31)
	v_lshlrev_b32_e32 v34, 16, v111
	v_mul_f32_e32 v18, v18, v34
	v_mul_f32_e32 v34, 0xbfb8aa3b, v34
	v_exp_f32_e32 v34, v34
	s_nop 0
	v_add_f32_e32 v34, 1.0, v34
	v_rcp_f32_e32 v34, v34
	s_nop 0
	v_mul_f32_e32 v18, v18, v34
	v_cvt_pk_bf16_f32 v18, v18, v18
	global_store_short v[72:73], v18, off offset:128
	s_waitcnt vmcnt(31)
	v_lshlrev_b32_e32 v18, 16, v112
	v_mul_f32_e32 v2, v2, v18
	v_mul_f32_e32 v18, 0xbfb8aa3b, v18
	v_exp_f32_e32 v18, v18
	s_nop 0
	v_add_f32_e32 v18, 1.0, v18
	v_rcp_f32_e32 v18, v18
	s_nop 0
	v_mul_f32_e32 v2, v2, v18
	v_cvt_pk_bf16_f32 v2, v2, v2
	global_store_short v[72:73], v2, off offset:192
	v_mul_f32_e32 v2, v51, v102
	s_waitcnt vmcnt(31)
	v_lshlrev_b32_e32 v18, 16, v113
	v_mul_f32_e32 v2, v2, v18
	v_mul_f32_e32 v18, 0xbfb8aa3b, v18
	v_exp_f32_e32 v18, v18
	v_add_u32_e32 v72, 0x2800, v68
	v_mov_b32_e32 v73, v1
	v_lshl_add_u64 v[72:73], v[72:73], 1, v[66:67]
	v_add_f32_e32 v18, 1.0, v18
	v_rcp_f32_e32 v18, v18
	s_nop 0
	v_mul_f32_e32 v2, v18, v2
	v_cvt_pk_bf16_f32 v2, v2, v2
	global_store_short v[72:73], v2, off
	v_mul_f32_e32 v2, v35, v102
	s_waitcnt vmcnt(31)
	v_lshlrev_b32_e32 v18, 16, v114
	v_mul_f32_e32 v2, v2, v18
	v_mul_f32_e32 v18, 0xbfb8aa3b, v18
	v_exp_f32_e32 v18, v18
	s_nop 0
	v_add_f32_e32 v18, 1.0, v18
	v_rcp_f32_e32 v18, v18
	s_nop 0
	v_mul_f32_e32 v2, v2, v18
	v_cvt_pk_bf16_f32 v2, v2, v2
	global_store_short v[72:73], v2, off offset:64
	v_mul_f32_e32 v2, v19, v102
	s_waitcnt vmcnt(31)
	v_lshlrev_b32_e32 v18, 16, v115
	v_mul_f32_e32 v2, v2, v18
	v_mul_f32_e32 v18, 0xbfb8aa3b, v18
	v_exp_f32_e32 v18, v18
	s_waitcnt vmcnt(29)
	v_lshlrev_b32_e32 v19, 16, v117
	v_add_f32_e32 v18, 1.0, v18
	v_rcp_f32_e32 v18, v18
	s_nop 0
	v_mul_f32_e32 v2, v2, v18
	v_cvt_pk_bf16_f32 v2, v2, v2
	global_store_short v[72:73], v2, off offset:128
	v_mul_f32_e32 v2, v3, v102
	v_lshlrev_b32_e32 v3, 16, v116
	v_mul_f32_e32 v2, v2, v3
	v_mul_f32_e32 v3, 0xbfb8aa3b, v3
	v_exp_f32_e32 v3, v3
	v_mul_f32_e32 v18, v52, v97
	v_mul_f32_e32 v18, v18, v19
	v_mul_f32_e32 v19, 0xbfb8aa3b, v19
	v_exp_f32_e32 v19, v19
	v_add_f32_e32 v3, 1.0, v3
	v_rcp_f32_e32 v3, v3
	v_add_f32_e32 v19, 1.0, v19
	v_rcp_f32_e32 v19, v19
	v_mul_f32_e32 v2, v2, v3
	v_cvt_pk_bf16_f32 v2, v2, v2
	global_store_short v[72:73], v2, off offset:192
	v_add_u32_e32 v2, 0x5000, v68
	v_mov_b32_e32 v3, v1
	v_mul_f32_e32 v18, v19, v18
	v_lshl_add_u64 v[2:3], v[2:3], 1, v[66:67]
	v_cvt_pk_bf16_f32 v18, v18, v18
	global_store_short v[2:3], v18, off
	v_mul_f32_e32 v18, v36, v97
	s_waitcnt vmcnt(31)
	v_lshlrev_b32_e32 v19, 16, v118
	v_mul_f32_e32 v18, v18, v19
	v_mul_f32_e32 v19, 0xbfb8aa3b, v19
	v_exp_f32_e32 v19, v19
	s_nop 0
	v_add_f32_e32 v19, 1.0, v19
	v_rcp_f32_e32 v19, v19
	s_nop 0
	v_mul_f32_e32 v18, v18, v19
	v_cvt_pk_bf16_f32 v18, v18, v18
	global_store_short v[2:3], v18, off offset:64
	v_mul_f32_e32 v18, v20, v97
	s_waitcnt vmcnt(31)
	v_lshlrev_b32_e32 v19, 16, v108
	v_mul_f32_e32 v18, v18, v19
	v_mul_f32_e32 v19, 0xbfb8aa3b, v19
	v_exp_f32_e32 v19, v19
	s_nop 0
	v_add_f32_e32 v19, 1.0, v19
	v_rcp_f32_e32 v19, v19
	s_nop 0
	v_mul_f32_e32 v18, v18, v19
	v_cvt_pk_bf16_f32 v18, v18, v18
	global_store_short v[2:3], v18, off offset:128
	s_waitcnt vmcnt(31)
	v_lshlrev_b32_e32 v18, 16, v106
	v_mul_f32_e32 v4, v4, v18
	v_mul_f32_e32 v18, 0xbfb8aa3b, v18
	v_exp_f32_e32 v18, v18
	s_nop 0
	v_add_f32_e32 v18, 1.0, v18
	v_rcp_f32_e32 v18, v18
	s_nop 0
	v_mul_f32_e32 v4, v4, v18
	v_cvt_pk_bf16_f32 v4, v4, v4
	global_store_short v[2:3], v4, off offset:192
	v_mul_f32_e32 v4, v53, v95
	s_waitcnt vmcnt(31)
	v_lshlrev_b32_e32 v18, 16, v105
	v_mul_f32_e32 v4, v4, v18
	v_mul_f32_e32 v18, 0xbfb8aa3b, v18
	v_exp_f32_e32 v18, v18
	v_add_u32_e32 v2, 0x7800, v68
	v_mov_b32_e32 v3, v1
	v_lshl_add_u64 v[2:3], v[2:3], 1, v[66:67]
	v_add_f32_e32 v18, 1.0, v18
	v_rcp_f32_e32 v18, v18
	s_nop 0
	v_mul_f32_e32 v4, v18, v4
	v_cvt_pk_bf16_f32 v4, v4, v4
	global_store_short v[2:3], v4, off
	v_mul_f32_e32 v4, v37, v95
	s_waitcnt vmcnt(31)
	v_lshlrev_b32_e32 v18, 16, v104
	v_mul_f32_e32 v4, v4, v18
	v_mul_f32_e32 v18, 0xbfb8aa3b, v18
	v_exp_f32_e32 v18, v18
	s_nop 0
	v_add_f32_e32 v18, 1.0, v18
	v_rcp_f32_e32 v18, v18
	s_nop 0
	v_mul_f32_e32 v4, v4, v18
	v_cvt_pk_bf16_f32 v4, v4, v4
	global_store_short v[2:3], v4, off offset:64
	v_mul_f32_e32 v4, v21, v95
	s_waitcnt vmcnt(31)
	v_lshlrev_b32_e32 v18, 16, v103
	v_mul_f32_e32 v4, v4, v18
	v_mul_f32_e32 v18, 0xbfb8aa3b, v18
	v_exp_f32_e32 v18, v18
	s_nop 0
	v_add_f32_e32 v18, 1.0, v18
	v_rcp_f32_e32 v18, v18
	s_nop 0
	v_mul_f32_e32 v4, v4, v18
	v_cvt_pk_bf16_f32 v4, v4, v4
	global_store_short v[2:3], v4, off offset:128
	v_mul_f32_e32 v4, v5, v95
	s_waitcnt vmcnt(31)
	v_lshlrev_b32_e32 v5, 16, v101
	v_mul_f32_e32 v4, v4, v5
	v_mul_f32_e32 v5, 0xbfb8aa3b, v5
	v_exp_f32_e32 v5, v5
	s_nop 0
	v_add_f32_e32 v5, 1.0, v5
	v_rcp_f32_e32 v5, v5
	s_nop 0
	v_mul_f32_e32 v4, v4, v5
	v_cvt_pk_bf16_f32 v4, v4, v4
	global_store_short v[2:3], v4, off offset:192
	v_mul_f32_e32 v4, v54, v94
	s_waitcnt vmcnt(31)
	v_lshlrev_b32_e32 v5, 16, v100
	v_mul_f32_e32 v4, v4, v5
	v_mul_f32_e32 v5, 0xbfb8aa3b, v5
	v_exp_f32_e32 v5, v5
	v_add_u32_e32 v2, 0x14000, v68
	v_mov_b32_e32 v3, v1
	v_lshl_add_u64 v[2:3], v[2:3], 1, v[66:67]
	v_add_f32_e32 v5, 1.0, v5
	v_rcp_f32_e32 v5, v5
	s_nop 0
	v_mul_f32_e32 v4, v5, v4
	v_cvt_pk_bf16_f32 v4, v4, v4
	global_store_short v[2:3], v4, off
	v_mul_f32_e32 v4, v38, v94
	s_waitcnt vmcnt(31)
	v_lshlrev_b32_e32 v5, 16, v99
	v_mul_f32_e32 v4, v4, v5
	v_mul_f32_e32 v5, 0xbfb8aa3b, v5
	v_exp_f32_e32 v5, v5
	s_nop 0
	v_add_f32_e32 v5, 1.0, v5
	v_rcp_f32_e32 v5, v5
	s_nop 0
	v_mul_f32_e32 v4, v4, v5
	v_cvt_pk_bf16_f32 v4, v4, v4
	global_store_short v[2:3], v4, off offset:64
	v_mul_f32_e32 v4, v22, v94
	s_waitcnt vmcnt(31)
	v_lshlrev_b32_e32 v5, 16, v98
	v_mul_f32_e32 v4, v4, v5
	v_mul_f32_e32 v5, 0xbfb8aa3b, v5
	v_exp_f32_e32 v5, v5
	s_nop 0
	v_add_f32_e32 v5, 1.0, v5
	v_rcp_f32_e32 v5, v5
	s_nop 0
	v_mul_f32_e32 v4, v4, v5
	v_cvt_pk_bf16_f32 v4, v4, v4
	global_store_short v[2:3], v4, off offset:128
	v_mul_f32_e32 v4, v6, v94
	s_waitcnt vmcnt(31)
	v_lshlrev_b32_e32 v5, 16, v96
	v_mul_f32_e32 v4, v4, v5
	v_mul_f32_e32 v5, 0xbfb8aa3b, v5
	v_exp_f32_e32 v5, v5
	v_add_u32_e32 v6, 0x121000, v0
	v_add_f32_e32 v5, 1.0, v5
	v_rcp_f32_e32 v5, v5
	s_nop 0
	v_mul_f32_e32 v4, v4, v5
	v_cvt_pk_bf16_f32 v4, v4, v4
	global_store_short v[2:3], v4, off offset:192
	v_mul_f32_e32 v4, v55, v93
	s_waitcnt vmcnt(31)
	v_lshlrev_b32_e32 v5, 16, v89
	v_mul_f32_e32 v4, v4, v5
	v_mul_f32_e32 v5, 0xbfb8aa3b, v5
	v_exp_f32_e32 v5, v5
	v_add_u32_e32 v2, 0x16800, v68
	v_mov_b32_e32 v3, v1
	v_lshl_add_u64 v[2:3], v[2:3], 1, v[66:67]
	v_add_f32_e32 v5, 1.0, v5
	v_rcp_f32_e32 v5, v5
	s_nop 0
	v_mul_f32_e32 v4, v5, v4
	v_cvt_pk_bf16_f32 v4, v4, v4
	global_store_short v[2:3], v4, off
	v_mul_f32_e32 v4, v39, v93
	s_waitcnt vmcnt(31)
	v_lshlrev_b32_e32 v5, 16, v88
	v_mul_f32_e32 v4, v4, v5
	v_mul_f32_e32 v5, 0xbfb8aa3b, v5
	v_exp_f32_e32 v5, v5
	s_nop 0
	v_add_f32_e32 v5, 1.0, v5
	v_rcp_f32_e32 v5, v5
	s_nop 0
	v_mul_f32_e32 v4, v4, v5
	v_cvt_pk_bf16_f32 v4, v4, v4
	global_store_short v[2:3], v4, off offset:64
	v_mul_f32_e32 v4, v23, v93
	s_waitcnt vmcnt(31)
	v_lshlrev_b32_e32 v5, 16, v81
	v_mul_f32_e32 v4, v4, v5
	v_mul_f32_e32 v5, 0xbfb8aa3b, v5
	v_exp_f32_e32 v5, v5
	s_nop 0
	v_add_f32_e32 v5, 1.0, v5
	v_rcp_f32_e32 v5, v5
	s_nop 0
	v_mul_f32_e32 v4, v4, v5
	v_cvt_pk_bf16_f32 v4, v4, v4
	global_store_short v[2:3], v4, off offset:128
	v_mul_f32_e32 v4, v7, v93
	s_waitcnt vmcnt(31)
	v_lshlrev_b32_e32 v5, 16, v80
	v_mul_f32_e32 v4, v4, v5
	v_mul_f32_e32 v5, 0xbfb8aa3b, v5
	v_exp_f32_e32 v5, v5
	v_mov_b32_e32 v7, v1
	v_add_f32_e32 v5, 1.0, v5
	v_rcp_f32_e32 v5, v5
	s_nop 0
	v_mul_f32_e32 v4, v4, v5
	v_cvt_pk_bf16_f32 v4, v4, v4
	global_store_short v[2:3], v4, off offset:192
	v_mul_f32_e32 v4, v56, v92
	s_waitcnt vmcnt(31)
	v_lshlrev_b32_e32 v5, 16, v79
	v_mul_f32_e32 v4, v4, v5
	v_mul_f32_e32 v5, 0xbfb8aa3b, v5
	v_exp_f32_e32 v5, v5
	v_add_u32_e32 v2, 0x19000, v68
	v_mov_b32_e32 v3, v1
	v_lshl_add_u64 v[2:3], v[2:3], 1, v[66:67]
	v_add_f32_e32 v5, 1.0, v5
	v_rcp_f32_e32 v5, v5
	s_nop 0
	v_mul_f32_e32 v4, v5, v4
	v_cvt_pk_bf16_f32 v4, v4, v4
	global_store_short v[2:3], v4, off
	v_mul_f32_e32 v4, v40, v92
	s_waitcnt vmcnt(31)
	v_lshlrev_b32_e32 v5, 16, v78
	v_mul_f32_e32 v4, v4, v5
	v_mul_f32_e32 v5, 0xbfb8aa3b, v5
	v_exp_f32_e32 v5, v5
	s_nop 0
	v_add_f32_e32 v5, 1.0, v5
	v_rcp_f32_e32 v5, v5
	s_nop 0
	v_mul_f32_e32 v4, v4, v5
	v_cvt_pk_bf16_f32 v4, v4, v4
	global_store_short v[2:3], v4, off offset:64
	v_mul_f32_e32 v4, v24, v92
	s_waitcnt vmcnt(31)
	v_lshlrev_b32_e32 v5, 16, v77
	v_mul_f32_e32 v4, v4, v5
	v_mul_f32_e32 v5, 0xbfb8aa3b, v5
	v_exp_f32_e32 v5, v5
	s_nop 0
	v_add_f32_e32 v5, 1.0, v5
	v_rcp_f32_e32 v5, v5
	s_nop 0
	v_mul_f32_e32 v4, v4, v5
	v_cvt_pk_bf16_f32 v4, v4, v4
	global_store_short v[2:3], v4, off offset:128
	v_mul_f32_e32 v4, v8, v92
	s_waitcnt vmcnt(31)
	v_lshlrev_b32_e32 v5, 16, v76
	v_mul_f32_e32 v4, v4, v5
	v_mul_f32_e32 v5, 0xbfb8aa3b, v5
	v_exp_f32_e32 v5, v5
	s_nop 0
	v_add_f32_e32 v5, 1.0, v5
	v_rcp_f32_e32 v5, v5
	s_nop 0
	v_mul_f32_e32 v4, v4, v5
	v_cvt_pk_bf16_f32 v4, v4, v4
	global_store_short v[2:3], v4, off offset:192
	v_mul_f32_e32 v4, v57, v91
	s_waitcnt vmcnt(31)
	v_lshlrev_b32_e32 v5, 16, v75
	v_mul_f32_e32 v4, v4, v5
	v_mul_f32_e32 v5, 0xbfb8aa3b, v5
	v_exp_f32_e32 v5, v5
	v_add_u32_e32 v2, 0x1b800, v68
	v_mov_b32_e32 v3, v1
	v_lshl_add_u64 v[2:3], v[2:3], 1, v[66:67]
	v_add_f32_e32 v5, 1.0, v5
	v_rcp_f32_e32 v5, v5
	s_nop 0
	v_mul_f32_e32 v4, v5, v4
	v_cvt_pk_bf16_f32 v4, v4, v4
	global_store_short v[2:3], v4, off
	v_mul_f32_e32 v4, v41, v91
	s_waitcnt vmcnt(31)
	v_lshlrev_b32_e32 v5, 16, v74
	v_mul_f32_e32 v4, v4, v5
	v_mul_f32_e32 v5, 0xbfb8aa3b, v5
	v_exp_f32_e32 v5, v5
	s_nop 0
	v_add_f32_e32 v5, 1.0, v5
	v_rcp_f32_e32 v5, v5
	s_nop 0
	v_mul_f32_e32 v4, v4, v5
	v_cvt_pk_bf16_f32 v4, v4, v4
	global_store_short v[2:3], v4, off offset:64
	v_mul_f32_e32 v4, v25, v91
	s_waitcnt vmcnt(31)
	v_lshlrev_b32_e32 v5, 16, v69
	v_mul_f32_e32 v4, v4, v5
	v_mul_f32_e32 v5, 0xbfb8aa3b, v5
	v_exp_f32_e32 v5, v5
	v_lshl_add_u64 v[24:25], v[6:7], 1, v[70:71]
	v_add_f32_e32 v5, 1.0, v5
	v_rcp_f32_e32 v5, v5
	s_nop 0
	v_mul_f32_e32 v4, v4, v5
	v_cvt_pk_bf16_f32 v4, v4, v4
	global_store_short v[2:3], v4, off offset:128
	v_mul_f32_e32 v4, v9, v91
	s_waitcnt vmcnt(31)
	v_lshlrev_b32_e32 v5, 16, v50
	v_mul_f32_e32 v4, v4, v5
	v_mul_f32_e32 v5, 0xbfb8aa3b, v5
	v_exp_f32_e32 v5, v5
	s_nop 0
	v_add_f32_e32 v5, 1.0, v5
	v_rcp_f32_e32 v5, v5
	s_nop 0
	v_mul_f32_e32 v4, v4, v5
	v_cvt_pk_bf16_f32 v4, v4, v4
	global_store_short v[2:3], v4, off offset:192
	v_add_u32_e32 v2, 0x110000, v0
	v_mov_b32_e32 v3, v1
	v_lshl_add_u64 v[56:57], v[2:3], 1, v[70:71]
	ds_read_b128 v[2:5], v90 offset:64
	ds_read_b128 v[50:53], v90 offset:96
	global_load_ushort v201, v[56:57], off
	s_waitcnt lgkmcnt(1)
	v_rcp_f32_e32 v69, v2
	v_rcp_f32_e32 v54, v3
	v_add_u32_e32 v2, 0x132000, v0
	v_mov_b32_e32 v3, v1
	v_lshl_add_u64 v[6:7], v[2:3], 1, v[70:71]
	v_add_u32_e32 v2, 0x143000, v0
	v_lshl_add_u64 v[8:9], v[2:3], 1, v[70:71]
	v_add_u32_e32 v2, 0x198000, v0
	v_lshl_add_u64 v[18:19], v[2:3], 1, v[70:71]
	v_add_u32_e32 v2, 0x1a9000, v0
	v_lshl_add_u64 v[20:21], v[2:3], 1, v[70:71]
	v_add_u32_e32 v2, 0x1ba000, v0
	v_add_u32_e32 v0, 0x1cb000, v0
	v_rcp_f32_e32 v41, v4
	v_rcp_f32_e32 v38, v5
	v_lshl_add_u64 v[4:5], v[0:1], 1, v[70:71]
	v_add_u32_e32 v0, 0x28000, v68
	v_lshl_add_u64 v[22:23], v[2:3], 1, v[70:71]
	v_lshl_add_u64 v[2:3], v[0:1], 1, v[66:67]
	v_mul_f32_e32 v0, v58, v69
	s_waitcnt lgkmcnt(0)
	v_rcp_f32_e32 v37, v50
	v_rcp_f32_e32 v36, v51
	v_rcp_f32_e32 v35, v52
	v_rcp_f32_e32 v34, v53
	global_load_ushort v71, v[56:57], off offset:64
	global_load_ushort v72, v[56:57], off offset:128
	global_load_ushort v73, v[56:57], off offset:192
	global_load_ushort v74, v[24:25], off
	global_load_ushort v75, v[24:25], off offset:64
	global_load_ushort v76, v[24:25], off offset:128
	global_load_ushort v77, v[24:25], off offset:192
	global_load_ushort v78, v[6:7], off
	global_load_ushort v79, v[6:7], off offset:64
	global_load_ushort v70, v[6:7], off offset:128
	global_load_ushort v58, v[6:7], off offset:192
	global_load_ushort v57, v[8:9], off
	global_load_ushort v56, v[8:9], off offset:64
	global_load_ushort v55, v[8:9], off offset:128
	global_load_ushort v53, v[8:9], off offset:192
	global_load_ushort v52, v[18:19], off
	global_load_ushort v51, v[18:19], off offset:64
	global_load_ushort v50, v[18:19], off offset:128
	global_load_ushort v40, v[18:19], off offset:192
	global_load_ushort v39, v[20:21], off
	global_load_ushort v25, v[20:21], off offset:64
	global_load_ushort v24, v[20:21], off offset:128
	s_nop 0
	global_load_ushort v21, v[20:21], off offset:192
	s_nop 0
	global_load_ushort v20, v[22:23], off
	global_load_ushort v19, v[22:23], off offset:64
	global_load_ushort v18, v[22:23], off offset:128
	global_load_ushort v9, v[22:23], off offset:192
	global_load_ushort v8, v[4:5], off
	global_load_ushort v7, v[4:5], off offset:64
	global_load_ushort v6, v[4:5], off offset:128
	s_nop 0
	global_load_ushort v4, v[4:5], off offset:192
	s_waitcnt vmcnt(31)
	v_lshlrev_b32_e32 v201, 16, v201
	v_mul_f32_e32 v0, v0, v201
	v_mul_f32_e32 v201, 0xbfb8aa3b, v201
	v_exp_f32_e32 v201, v201
	s_nop 0
	v_add_f32_e32 v201, 1.0, v201
	v_rcp_f32_e32 v201, v201
	s_nop 0
	v_mul_f32_e32 v0, v201, v0
	v_cvt_pk_bf16_f32 v0, v0, v0
	global_store_short v[2:3], v0, off
	v_mul_f32_e32 v0, v42, v69
	s_waitcnt vmcnt(31)
	v_lshlrev_b32_e32 v5, 16, v71
	v_mul_f32_e32 v0, v0, v5
	v_mul_f32_e32 v5, 0xbfb8aa3b, v5
	v_exp_f32_e32 v5, v5
	s_waitcnt vmcnt(1)
	v_lshlrev_b32_e32 v4, 16, v4
	v_add_f32_e32 v5, 1.0, v5
	v_rcp_f32_e32 v5, v5
	s_nop 0
	v_mul_f32_e32 v0, v0, v5
	v_cvt_pk_bf16_f32 v0, v0, v0
	global_store_short v[2:3], v0, off offset:64
	v_mul_f32_e32 v0, v26, v69
	v_lshlrev_b32_e32 v5, 16, v72
	v_mul_f32_e32 v0, v0, v5
	v_mul_f32_e32 v5, 0xbfb8aa3b, v5
	v_exp_f32_e32 v5, v5
	s_nop 0
	v_add_f32_e32 v5, 1.0, v5
	v_rcp_f32_e32 v5, v5
	s_nop 0
	v_mul_f32_e32 v0, v0, v5
	v_cvt_pk_bf16_f32 v0, v0, v0
	global_store_short v[2:3], v0, off offset:128
	v_mul_f32_e32 v0, v10, v69
	v_lshlrev_b32_e32 v5, 16, v73
	v_mul_f32_e32 v0, v0, v5
	v_mul_f32_e32 v5, 0xbfb8aa3b, v5
	v_exp_f32_e32 v5, v5
	s_nop 0
	v_add_f32_e32 v5, 1.0, v5
	v_rcp_f32_e32 v5, v5
	s_nop 0
	v_mul_f32_e32 v0, v0, v5
	v_cvt_pk_bf16_f32 v0, v0, v0
	global_store_short v[2:3], v0, off offset:192
	v_add_u32_e32 v0, 0x2a800, v68
	v_lshl_add_u64 v[2:3], v[0:1], 1, v[66:67]
	v_mul_f32_e32 v0, v59, v54
	v_lshlrev_b32_e32 v5, 16, v74
	v_mul_f32_e32 v0, v0, v5
	v_mul_f32_e32 v5, 0xbfb8aa3b, v5
	v_exp_f32_e32 v5, v5
	s_nop 0
	v_add_f32_e32 v5, 1.0, v5
	v_rcp_f32_e32 v5, v5
	s_nop 0
	v_mul_f32_e32 v0, v5, v0
	v_cvt_pk_bf16_f32 v0, v0, v0
	global_store_short v[2:3], v0, off
	v_mul_f32_e32 v0, v43, v54
	v_lshlrev_b32_e32 v5, 16, v75
	v_mul_f32_e32 v0, v0, v5
	v_mul_f32_e32 v5, 0xbfb8aa3b, v5
	v_exp_f32_e32 v5, v5
	s_nop 0
	v_add_f32_e32 v5, 1.0, v5
	v_rcp_f32_e32 v5, v5
	s_nop 0
	v_mul_f32_e32 v0, v0, v5
	v_cvt_pk_bf16_f32 v0, v0, v0
	global_store_short v[2:3], v0, off offset:64
	v_mul_f32_e32 v0, v27, v54
	v_lshlrev_b32_e32 v5, 16, v76
	v_mul_f32_e32 v0, v0, v5
	v_mul_f32_e32 v5, 0xbfb8aa3b, v5
	v_exp_f32_e32 v5, v5
	s_nop 0
	v_add_f32_e32 v5, 1.0, v5
	v_rcp_f32_e32 v5, v5
	s_nop 0
	v_mul_f32_e32 v0, v0, v5
	v_cvt_pk_bf16_f32 v0, v0, v0
	global_store_short v[2:3], v0, off offset:128
	v_mul_f32_e32 v0, v11, v54
	v_lshlrev_b32_e32 v5, 16, v77
	v_mul_f32_e32 v0, v0, v5
	v_mul_f32_e32 v5, 0xbfb8aa3b, v5
	v_exp_f32_e32 v5, v5
	s_nop 0
	v_add_f32_e32 v5, 1.0, v5
	v_rcp_f32_e32 v5, v5
	s_nop 0
	v_mul_f32_e32 v0, v0, v5
	v_cvt_pk_bf16_f32 v0, v0, v0
	global_store_short v[2:3], v0, off offset:192
	v_add_u32_e32 v0, 0x2d000, v68
	v_lshl_add_u64 v[2:3], v[0:1], 1, v[66:67]
	v_mul_f32_e32 v0, v60, v41
	v_lshlrev_b32_e32 v5, 16, v78
	v_mul_f32_e32 v0, v0, v5
	v_mul_f32_e32 v5, 0xbfb8aa3b, v5
	v_exp_f32_e32 v5, v5
	s_nop 0
	v_add_f32_e32 v5, 1.0, v5
	v_rcp_f32_e32 v5, v5
	s_nop 0
	v_mul_f32_e32 v0, v5, v0
	v_cvt_pk_bf16_f32 v0, v0, v0
	global_store_short v[2:3], v0, off
	v_mul_f32_e32 v0, v44, v41
	v_lshlrev_b32_e32 v5, 16, v79
	v_mul_f32_e32 v0, v0, v5
	v_mul_f32_e32 v5, 0xbfb8aa3b, v5
	v_exp_f32_e32 v5, v5
	s_nop 0
	v_add_f32_e32 v5, 1.0, v5
	v_rcp_f32_e32 v5, v5
	s_nop 0
	v_mul_f32_e32 v0, v0, v5
	v_cvt_pk_bf16_f32 v0, v0, v0
	global_store_short v[2:3], v0, off offset:64
	v_mul_f32_e32 v0, v28, v41
	v_lshlrev_b32_e32 v5, 16, v70
	v_mul_f32_e32 v0, v0, v5
	v_mul_f32_e32 v5, 0xbfb8aa3b, v5
	v_exp_f32_e32 v5, v5
	s_nop 0
	v_add_f32_e32 v5, 1.0, v5
	v_rcp_f32_e32 v5, v5
	s_nop 0
	v_mul_f32_e32 v0, v0, v5
	v_cvt_pk_bf16_f32 v0, v0, v0
	global_store_short v[2:3], v0, off offset:128
	v_mul_f32_e32 v0, v12, v41
	v_lshlrev_b32_e32 v5, 16, v58
	v_mul_f32_e32 v0, v0, v5
	v_mul_f32_e32 v5, 0xbfb8aa3b, v5
	v_exp_f32_e32 v5, v5
	s_nop 0
	v_add_f32_e32 v5, 1.0, v5
	v_rcp_f32_e32 v5, v5
	s_nop 0
	v_mul_f32_e32 v0, v0, v5
	v_cvt_pk_bf16_f32 v0, v0, v0
	global_store_short v[2:3], v0, off offset:192
	v_add_u32_e32 v0, 0x2f800, v68
	v_lshl_add_u64 v[2:3], v[0:1], 1, v[66:67]
	v_mul_f32_e32 v0, v61, v38
	v_lshlrev_b32_e32 v5, 16, v57
	v_mul_f32_e32 v0, v0, v5
	v_mul_f32_e32 v5, 0xbfb8aa3b, v5
	v_exp_f32_e32 v5, v5
	s_nop 0
	v_add_f32_e32 v5, 1.0, v5
	v_rcp_f32_e32 v5, v5
	s_nop 0
	v_mul_f32_e32 v0, v5, v0
	v_cvt_pk_bf16_f32 v0, v0, v0
	global_store_short v[2:3], v0, off
	v_mul_f32_e32 v0, v45, v38
	v_lshlrev_b32_e32 v5, 16, v56
	v_mul_f32_e32 v0, v0, v5
	v_mul_f32_e32 v5, 0xbfb8aa3b, v5
	v_exp_f32_e32 v5, v5
	s_nop 0
	v_add_f32_e32 v5, 1.0, v5
	v_rcp_f32_e32 v5, v5
	s_nop 0
	v_mul_f32_e32 v0, v0, v5
	v_cvt_pk_bf16_f32 v0, v0, v0
	global_store_short v[2:3], v0, off offset:64
	v_mul_f32_e32 v0, v29, v38
	v_lshlrev_b32_e32 v5, 16, v55
	v_mul_f32_e32 v0, v0, v5
	v_mul_f32_e32 v5, 0xbfb8aa3b, v5
	v_exp_f32_e32 v5, v5
	s_nop 0
	v_add_f32_e32 v5, 1.0, v5
	v_rcp_f32_e32 v5, v5
	s_nop 0
	v_mul_f32_e32 v0, v0, v5
	v_cvt_pk_bf16_f32 v0, v0, v0
	global_store_short v[2:3], v0, off offset:128
	v_mul_f32_e32 v0, v13, v38
	v_lshlrev_b32_e32 v5, 16, v53
	v_mul_f32_e32 v0, v0, v5
	v_mul_f32_e32 v5, 0xbfb8aa3b, v5
	v_exp_f32_e32 v5, v5
	s_nop 0
	v_add_f32_e32 v5, 1.0, v5
	v_rcp_f32_e32 v5, v5
	s_nop 0
	v_mul_f32_e32 v0, v0, v5
	v_cvt_pk_bf16_f32 v0, v0, v0
	global_store_short v[2:3], v0, off offset:192
	v_add_u32_e32 v0, 0x3c000, v68
	v_lshl_add_u64 v[2:3], v[0:1], 1, v[66:67]
	v_mul_f32_e32 v0, v62, v37
	v_lshlrev_b32_e32 v5, 16, v52
	v_mul_f32_e32 v0, v0, v5
	v_mul_f32_e32 v5, 0xbfb8aa3b, v5
	v_exp_f32_e32 v5, v5
	s_nop 0
	v_add_f32_e32 v5, 1.0, v5
	v_rcp_f32_e32 v5, v5
	s_nop 0
	v_mul_f32_e32 v0, v5, v0
	v_cvt_pk_bf16_f32 v0, v0, v0
	global_store_short v[2:3], v0, off
	v_mul_f32_e32 v0, v46, v37
	v_lshlrev_b32_e32 v5, 16, v51
	v_mul_f32_e32 v0, v0, v5
	v_mul_f32_e32 v5, 0xbfb8aa3b, v5
	v_exp_f32_e32 v5, v5
	s_nop 0
	v_add_f32_e32 v5, 1.0, v5
	v_rcp_f32_e32 v5, v5
	s_nop 0
	v_mul_f32_e32 v0, v0, v5
	v_cvt_pk_bf16_f32 v0, v0, v0
	global_store_short v[2:3], v0, off offset:64
	v_mul_f32_e32 v0, v30, v37
	v_lshlrev_b32_e32 v5, 16, v50
	v_mul_f32_e32 v0, v0, v5
	v_mul_f32_e32 v5, 0xbfb8aa3b, v5
	v_exp_f32_e32 v5, v5
	s_nop 0
	v_add_f32_e32 v5, 1.0, v5
	v_rcp_f32_e32 v5, v5
	s_nop 0
	v_mul_f32_e32 v0, v0, v5
	v_cvt_pk_bf16_f32 v0, v0, v0
	global_store_short v[2:3], v0, off offset:128
	v_mul_f32_e32 v0, v14, v37
	v_lshlrev_b32_e32 v5, 16, v40
	v_mul_f32_e32 v0, v0, v5
	v_mul_f32_e32 v5, 0xbfb8aa3b, v5
	v_exp_f32_e32 v5, v5
	s_nop 0
	v_add_f32_e32 v5, 1.0, v5
	v_rcp_f32_e32 v5, v5
	s_nop 0
	v_mul_f32_e32 v0, v0, v5
	v_cvt_pk_bf16_f32 v0, v0, v0
	global_store_short v[2:3], v0, off offset:192
	v_add_u32_e32 v0, 0x3e800, v68
	v_lshl_add_u64 v[2:3], v[0:1], 1, v[66:67]
	v_mul_f32_e32 v0, v63, v36
	v_lshlrev_b32_e32 v5, 16, v39
	v_mul_f32_e32 v0, v0, v5
	v_mul_f32_e32 v5, 0xbfb8aa3b, v5
	v_exp_f32_e32 v5, v5
	s_nop 0
	v_add_f32_e32 v5, 1.0, v5
	v_rcp_f32_e32 v5, v5
	s_nop 0
	v_mul_f32_e32 v0, v5, v0
	v_cvt_pk_bf16_f32 v0, v0, v0
	global_store_short v[2:3], v0, off
	v_mul_f32_e32 v0, v47, v36
	v_lshlrev_b32_e32 v5, 16, v25
	v_mul_f32_e32 v0, v0, v5
	v_mul_f32_e32 v5, 0xbfb8aa3b, v5
	v_exp_f32_e32 v5, v5
	s_nop 0
	v_add_f32_e32 v5, 1.0, v5
	v_rcp_f32_e32 v5, v5
	s_nop 0
	v_mul_f32_e32 v0, v0, v5
	v_cvt_pk_bf16_f32 v0, v0, v0
	global_store_short v[2:3], v0, off offset:64
	v_mul_f32_e32 v0, v31, v36
	v_lshlrev_b32_e32 v5, 16, v24
	v_mul_f32_e32 v0, v0, v5
	v_mul_f32_e32 v5, 0xbfb8aa3b, v5
	v_exp_f32_e32 v5, v5
	s_nop 0
	v_add_f32_e32 v5, 1.0, v5
	v_rcp_f32_e32 v5, v5
	s_nop 0
	v_mul_f32_e32 v0, v0, v5
	v_cvt_pk_bf16_f32 v0, v0, v0
	global_store_short v[2:3], v0, off offset:128
	v_mul_f32_e32 v0, v15, v36
	v_lshlrev_b32_e32 v5, 16, v21
	v_mul_f32_e32 v0, v0, v5
	v_mul_f32_e32 v5, 0xbfb8aa3b, v5
	v_exp_f32_e32 v5, v5
	s_nop 0
	v_add_f32_e32 v5, 1.0, v5
	v_rcp_f32_e32 v5, v5
	s_nop 0
	v_mul_f32_e32 v0, v0, v5
	v_cvt_pk_bf16_f32 v0, v0, v0
	global_store_short v[2:3], v0, off offset:192
	v_add_u32_e32 v0, 0x41000, v68
	v_lshl_add_u64 v[2:3], v[0:1], 1, v[66:67]
	v_mul_f32_e32 v0, v64, v35
	v_lshlrev_b32_e32 v5, 16, v20
	v_mul_f32_e32 v0, v0, v5
	v_mul_f32_e32 v5, 0xbfb8aa3b, v5
	v_exp_f32_e32 v5, v5
	s_nop 0
	v_add_f32_e32 v5, 1.0, v5
	v_rcp_f32_e32 v5, v5
	s_nop 0
	v_mul_f32_e32 v0, v5, v0
	v_cvt_pk_bf16_f32 v0, v0, v0
	global_store_short v[2:3], v0, off
	v_mul_f32_e32 v0, v48, v35
	v_lshlrev_b32_e32 v5, 16, v19
	v_mul_f32_e32 v0, v0, v5
	v_mul_f32_e32 v5, 0xbfb8aa3b, v5
	v_exp_f32_e32 v5, v5
	s_nop 0
	v_add_f32_e32 v5, 1.0, v5
	v_rcp_f32_e32 v5, v5
	s_nop 0
	v_mul_f32_e32 v0, v0, v5
	v_cvt_pk_bf16_f32 v0, v0, v0
	global_store_short v[2:3], v0, off offset:64
	v_mul_f32_e32 v0, v32, v35
	v_lshlrev_b32_e32 v5, 16, v18
	v_mul_f32_e32 v0, v0, v5
	v_mul_f32_e32 v5, 0xbfb8aa3b, v5
	v_exp_f32_e32 v5, v5
	s_nop 0
	v_add_f32_e32 v5, 1.0, v5
	v_rcp_f32_e32 v5, v5
	s_nop 0
	v_mul_f32_e32 v0, v0, v5
	v_cvt_pk_bf16_f32 v0, v0, v0
	global_store_short v[2:3], v0, off offset:128
	v_mul_f32_e32 v0, v16, v35
	v_lshlrev_b32_e32 v5, 16, v9
	v_mul_f32_e32 v0, v0, v5
	v_mul_f32_e32 v5, 0xbfb8aa3b, v5
	v_exp_f32_e32 v5, v5
	s_nop 0
	v_add_f32_e32 v5, 1.0, v5
	v_rcp_f32_e32 v5, v5
	s_nop 0
	v_mul_f32_e32 v0, v0, v5
	v_cvt_pk_bf16_f32 v0, v0, v0
	global_store_short v[2:3], v0, off offset:192
	v_add_u32_e32 v0, 0x43800, v68
	v_lshl_add_u64 v[2:3], v[0:1], 1, v[66:67]
	v_mul_f32_e32 v0, v65, v34
	v_lshlrev_b32_e32 v5, 16, v8
	v_mul_f32_e32 v0, v0, v5
	v_mul_f32_e32 v5, 0xbfb8aa3b, v5
	v_exp_f32_e32 v5, v5
	s_nop 0
	v_add_f32_e32 v5, 1.0, v5
	v_rcp_f32_e32 v5, v5
	s_nop 0
	v_mul_f32_e32 v0, v5, v0
	v_cvt_pk_bf16_f32 v0, v0, v0
	global_store_short v[2:3], v0, off
	v_mul_f32_e32 v0, v49, v34
	v_lshlrev_b32_e32 v5, 16, v7
	v_mul_f32_e32 v0, v0, v5
	v_mul_f32_e32 v5, 0xbfb8aa3b, v5
	v_exp_f32_e32 v5, v5
	s_nop 0
	v_add_f32_e32 v5, 1.0, v5
	v_rcp_f32_e32 v5, v5
	s_nop 0
	v_mul_f32_e32 v0, v0, v5
	v_cvt_pk_bf16_f32 v0, v0, v0
	global_store_short v[2:3], v0, off offset:64
	v_mul_f32_e32 v0, v33, v34
	v_lshlrev_b32_e32 v5, 16, v6
	v_mul_f32_e32 v0, v0, v5
	v_mul_f32_e32 v5, 0xbfb8aa3b, v5
	v_exp_f32_e32 v5, v5
	s_nop 0
	v_add_f32_e32 v5, 1.0, v5
	v_rcp_f32_e32 v5, v5
	s_nop 0
	v_mul_f32_e32 v0, v0, v5
	v_cvt_pk_bf16_f32 v0, v0, v0
	global_store_short v[2:3], v0, off offset:128
	v_mul_f32_e32 v0, v17, v34
	v_mul_f32_e32 v0, v0, v4
	v_mul_f32_e32 v4, 0xbfb8aa3b, v4
	v_exp_f32_e32 v4, v4
	s_nop 0
	v_add_f32_e32 v4, 1.0, v4
	v_rcp_f32_e32 v4, v4
	s_nop 0
	v_mul_f32_e32 v0, v0, v4
	v_cvt_pk_bf16_f32 v0, v0, v0
	global_store_short v[2:3], v0, off offset:192
	s_cbranch_scc1 .LBB0_1279

.LBB0_1249:
	v_mov_b32_e32 v0, v198
	s_add_i32 s2, s0, s10
	s_mov_b32 s0, 0x1fffffe0
	v_lshrrev_b32_e32 v66, 1, v0
	v_and_b32_e32 v67, 31, v0
	v_and_or_b32 v66, v66, s0, v67
	v_readlane_b32 s0, v252, 26
	v_readlane_b32 s1, v252, 27
	v_lshl_add_u32 v66, v66, 3, s31
	v_lshrrev_b32_e32 v0, 2, v0
	v_mov_b64_e32 v[68:69], s[0:1]
	s_movk_i32 s0, 0x4400
	v_mad_i64_i32 v[68:69], s[0:1], v66, s0, v[68:69]
	s_lshl_b32 s2, s2, 8
	v_and_b32_e32 v72, 8, v0
	v_lshl_add_u64 v[68:69], v[68:69], 0, s[2:3]
	v_lshlrev_b32_e32 v0, 1, v72
	v_lshl_add_u64 v[70:71], v[68:69], 0, v[0:1]
	global_load_dwordx4 v[84:87], v[70:71], off
	global_load_dwordx4 v[88:91], v[70:71], off offset:128
	v_ashrrev_i32_e32 v67, 31, v66
	v_readlane_b32 s0, v251, 5
	v_lshlrev_b64 v[66:67], 9, v[66:67]
	v_readlane_b32 s1, v251, 6
	v_lshlrev_b32_e32 v0, 3, v72
	s_add_u32 s16, s11, s2
	v_lshl_add_u64 v[66:67], s[0:1], 0, v[66:67]
	v_lshl_add_u64 v[82:83], v[66:67], 0, v[0:1]
	global_load_dwordx4 v[92:95], v[82:83], off
	global_load_dwordx4 v[96:99], v[82:83], off offset:16
	global_load_dwordx4 v[100:103], v[82:83], off offset:32
	global_load_dwordx4 v[104:107], v[82:83], off offset:48
	global_load_dwordx4 v[108:111], v[70:71], off offset:32
	global_load_dwordx4 v[74:77], v[70:71], off offset:64
	global_load_dwordx4 v[66:69], v[70:71], off offset:96
	global_load_dwordx4 v[112:115], v[70:71], off offset:160
	global_load_dwordx4 v[78:81], v[70:71], off offset:192
	s_nop 0
	global_load_dwordx4 v[70:73], v[70:71], off offset:224
	s_addc_u32 s17, s35, 0
	s_and_b64 s[0:1], s[12:13], exec
	s_movk_i32 s0, 0x80
	s_cselect_b32 s2, s0, 0x100
	s_movk_i32 s0, 0x800
	s_cselect_b32 s37, s36, s34
	s_cselect_b32 s38, 8, 4
	s_cselect_b32 s39, 0x200, s0
	s_cselect_b32 s40, 0, 15
	s_add_u32 s18, s16, 0x1200
	s_addc_u32 s19, s17, 0
	v_mov_b32_e32 v189, v1
	v_mov_b32_e32 v191, v1
	v_subrev_u32_e32 v223, s37, v195
	s_mov_b32 s45, 0
	s_mov_b32 s49, 0
	s_mov_b32 s50, 0
	s_mov_b32 s51, 0
	s_mov_b32 s52, 0
	s_waitcnt vmcnt(11)
	v_lshlrev_b32_e32 v117, 16, v84
	s_waitcnt vmcnt(10)
	v_lshlrev_b32_e32 v116, 16, v88
	v_and_b32_e32 v119, 0xffff0000, v84
	v_and_b32_e32 v118, 0xffff0000, v88
	v_lshlrev_b32_e32 v121, 16, v85
	v_lshlrev_b32_e32 v120, 16, v89
	v_and_b32_e32 v85, 0xffff0000, v85
	v_and_b32_e32 v84, 0xffff0000, v89
	v_lshlrev_b32_e32 v89, 16, v86
	v_lshlrev_b32_e32 v88, 16, v90
	v_and_b32_e32 v123, 0xffff0000, v86
	v_and_b32_e32 v122, 0xffff0000, v90
	v_lshlrev_b32_e32 v125, 16, v87
	v_lshlrev_b32_e32 v124, 16, v91
	v_and_b32_e32 v87, 0xffff0000, v87
	v_and_b32_e32 v86, 0xffff0000, v91
	s_waitcnt vmcnt(9)
	v_pk_mul_f32 v[90:91], v[92:93], v[116:117] op_sel:[0,1] op_sel_hi:[1,0]
	v_pk_mul_f32 v[92:93], v[92:93], v[116:117]
	v_pk_mul_f32 v[116:117], v[94:95], v[118:119] op_sel:[0,1] op_sel_hi:[1,0]
	v_pk_mul_f32 v[94:95], v[94:95], v[118:119]
	s_waitcnt vmcnt(8)
	v_pk_mul_f32 v[118:119], v[96:97], v[120:121] op_sel:[0,1] op_sel_hi:[1,0]
	v_pk_mul_f32 v[96:97], v[96:97], v[120:121]
	v_pk_mul_f32 v[120:121], v[98:99], v[84:85] op_sel:[0,1] op_sel_hi:[1,0]
	v_pk_mul_f32 v[84:85], v[98:99], v[84:85]
	s_waitcnt vmcnt(7)
	v_pk_mul_f32 v[98:99], v[100:101], v[88:89] op_sel:[0,1] op_sel_hi:[1,0]
	v_pk_mul_f32 v[88:89], v[100:101], v[88:89]
	v_pk_mul_f32 v[100:101], v[102:103], v[122:123] op_sel:[0,1] op_sel_hi:[1,0]
	v_pk_mul_f32 v[102:103], v[102:103], v[122:123]
	s_waitcnt vmcnt(6)
	v_pk_mul_f32 v[122:123], v[104:105], v[124:125] op_sel:[0,1] op_sel_hi:[1,0]
	v_pk_mul_f32 v[104:105], v[104:105], v[124:125]
	v_pk_mul_f32 v[124:125], v[106:107], v[86:87] op_sel:[0,1] op_sel_hi:[1,0]
	v_add_f32_e32 v84, v84, v85
	v_sub_f32_e32 v0, v90, v91
	v_add_f32_e32 v90, v92, v93
	v_add_f32_e32 v92, v94, v95
	v_add_f32_e32 v94, v96, v97
	v_sub_f32_e32 v85, v98, v99
	v_add_f32_e32 v96, v102, v103
	v_mul_f32_e32 v103, 0x3e0293ee, v84
	v_sub_f32_e32 v84, v124, v125
	v_add_f32_e32 v88, v88, v89
	v_sub_f32_e32 v89, v100, v101
	v_mul_f32_e32 v100, 0x3e0293ee, v85
	v_mul_f32_e32 v101, 0x3e0293ee, v84
	v_pk_mul_f32 v[84:85], v[106:107], v[86:87]
	v_sub_f32_e32 v91, v116, v117
	v_sub_f32_e32 v93, v118, v119
	v_sub_f32_e32 v95, v120, v121
	v_add_f32_e32 v98, v104, v105
	v_add_f32_e32 v84, v84, v85
	v_sub_f32_e32 v97, v122, v123
	v_mul_f32_e32 v90, 0x3e0293ee, v90
	v_mul_f32_e32 v91, 0x3e0293ee, v91
	v_mul_f32_e32 v92, 0x3e0293ee, v92
	v_mul_f32_e32 v93, 0x3e0293ee, v93
	v_mul_f32_e32 v94, 0x3e0293ee, v94
	v_mul_f32_e32 v95, 0x3e0293ee, v95
	v_mul_f32_e32 v88, 0x3e0293ee, v88
	v_mul_f32_e32 v89, 0x3e0293ee, v89
	v_mul_f32_e32 v105, 0x3e0293ee, v98
	v_mul_f32_e32 v84, 0x3e0293ee, v84
	v_mul_f32_e32 v0, 0x3e0293ee, v0
	v_mul_f32_e32 v96, 0x3e0293ee, v96
	v_mul_f32_e32 v97, 0x3e0293ee, v97
	v_cvt_pk_bf16_f32 v98, v0, v91
	v_cvt_pk_bf16_f32 v99, v93, v95
	v_cvt_pk_bf16_f32 v100, v100, v89
	v_cvt_pk_bf16_f32 v101, v97, v101
	v_cvt_pk_bf16_f32 v102, v90, v92
	v_cvt_pk_bf16_f32 v103, v94, v103
	v_cvt_pk_bf16_f32 v104, v88, v96
	v_cvt_pk_bf16_f32 v105, v105, v84
	global_load_dwordx4 v[84:87], v[82:83], off offset:128
	global_load_dwordx4 v[88:91], v[82:83], off offset:144
	global_load_dwordx4 v[92:95], v[82:83], off offset:160
	global_load_dwordx4 v[116:119], v[82:83], off offset:176
	s_waitcnt vmcnt(9)
	v_lshlrev_b32_e32 v97, 16, v108
	s_waitcnt vmcnt(6)
	v_lshlrev_b32_e32 v96, 16, v112
	v_and_b32_e32 v107, 0xffff0000, v108
	v_and_b32_e32 v106, 0xffff0000, v112
	v_lshlrev_b32_e32 v121, 16, v109
	v_lshlrev_b32_e32 v120, 16, v113
	v_and_b32_e32 v109, 0xffff0000, v109
	v_and_b32_e32 v108, 0xffff0000, v113
	v_lshlrev_b32_e32 v113, 16, v110
	v_lshlrev_b32_e32 v112, 16, v114
	v_and_b32_e32 v123, 0xffff0000, v110
	v_and_b32_e32 v122, 0xffff0000, v114
	v_lshlrev_b32_e32 v125, 16, v111
	v_lshlrev_b32_e32 v124, 16, v115
	v_and_b32_e32 v111, 0xffff0000, v111
	v_and_b32_e32 v110, 0xffff0000, v115
	s_waitcnt vmcnt(3)
	v_pk_mul_f32 v[114:115], v[84:85], v[96:97] op_sel:[0,1] op_sel_hi:[1,0]
	v_pk_mul_f32 v[84:85], v[84:85], v[96:97]
	v_pk_mul_f32 v[96:97], v[86:87], v[106:107] op_sel:[0,1] op_sel_hi:[1,0]
	v_pk_mul_f32 v[86:87], v[86:87], v[106:107]
	s_waitcnt vmcnt(2)
	v_pk_mul_f32 v[106:107], v[88:89], v[120:121] op_sel:[0,1] op_sel_hi:[1,0]
	v_pk_mul_f32 v[88:89], v[88:89], v[120:121]
	v_pk_mul_f32 v[120:121], v[90:91], v[108:109] op_sel:[0,1] op_sel_hi:[1,0]
	v_pk_mul_f32 v[90:91], v[90:91], v[108:109]
	s_waitcnt vmcnt(1)
	v_pk_mul_f32 v[108:109], v[92:93], v[112:113] op_sel:[0,1] op_sel_hi:[1,0]
	v_pk_mul_f32 v[92:93], v[92:93], v[112:113]
	v_pk_mul_f32 v[112:113], v[94:95], v[122:123] op_sel:[0,1] op_sel_hi:[1,0]
	v_pk_mul_f32 v[94:95], v[94:95], v[122:123]
	s_waitcnt vmcnt(0)
	v_pk_mul_f32 v[122:123], v[116:117], v[124:125] op_sel:[0,1] op_sel_hi:[1,0]
	v_pk_mul_f32 v[116:117], v[116:117], v[124:125]
	v_pk_mul_f32 v[124:125], v[118:119], v[110:111] op_sel:[0,1] op_sel_hi:[1,0]
	v_pk_mul_f32 v[110:111], v[118:119], v[110:111]
	v_add_f32_e32 v84, v84, v85
	v_sub_f32_e32 v85, v96, v97
	v_add_f32_e32 v86, v86, v87
	v_sub_f32_e32 v87, v106, v107
	v_add_f32_e32 v88, v88, v89
	v_sub_f32_e32 v89, v120, v121
	v_add_f32_e32 v90, v90, v91
	v_sub_f32_e32 v91, v108, v109
	v_add_f32_e32 v92, v92, v93
	v_sub_f32_e32 v93, v112, v113
	v_add_f32_e32 v94, v94, v95
	v_sub_f32_e32 v95, v122, v123
	v_add_f32_e32 v106, v110, v111
	v_sub_f32_e32 v0, v114, v115
	v_add_f32_e32 v96, v116, v117
	v_sub_f32_e32 v97, v124, v125
	v_mul_f32_e32 v84, 0x3e0293ee, v84
	v_mul_f32_e32 v85, 0x3e0293ee, v85
	v_mul_f32_e32 v86, 0x3e0293ee, v86
	v_mul_f32_e32 v87, 0x3e0293ee, v87
	v_mul_f32_e32 v88, 0x3e0293ee, v88
	v_mul_f32_e32 v89, 0x3e0293ee, v89
	v_mul_f32_e32 v90, 0x3e0293ee, v90
	v_mul_f32_e32 v91, 0x3e0293ee, v91
	v_mul_f32_e32 v92, 0x3e0293ee, v92
	v_mul_f32_e32 v93, 0x3e0293ee, v93
	v_mul_f32_e32 v94, 0x3e0293ee, v94
	v_mul_f32_e32 v95, 0x3e0293ee, v95
	v_mul_f32_e32 v113, 0x3e0293ee, v106
	v_mul_f32_e32 v0, 0x3e0293ee, v0
	v_mul_f32_e32 v96, 0x3e0293ee, v96
	v_mul_f32_e32 v97, 0x3e0293ee, v97
	v_cvt_pk_bf16_f32 v106, v0, v85
	v_cvt_pk_bf16_f32 v107, v87, v89
	v_cvt_pk_bf16_f32 v108, v91, v93
	v_cvt_pk_bf16_f32 v109, v95, v97
	v_cvt_pk_bf16_f32 v110, v84, v86
	v_cvt_pk_bf16_f32 v111, v88, v90
	v_cvt_pk_bf16_f32 v112, v92, v94
	v_cvt_pk_bf16_f32 v113, v96, v113
	global_load_dwordx4 v[84:87], v[82:83], off offset:256
	global_load_dwordx4 v[88:91], v[82:83], off offset:272
	global_load_dwordx4 v[92:95], v[82:83], off offset:288
	global_load_dwordx4 v[114:117], v[82:83], off offset:304
	v_lshlrev_b32_e32 v97, 16, v74
	v_lshlrev_b32_e32 v96, 16, v78
	v_and_b32_e32 v119, 0xffff0000, v74
	v_and_b32_e32 v118, 0xffff0000, v78
	v_lshlrev_b32_e32 v121, 16, v75
	v_lshlrev_b32_e32 v120, 16, v79
	v_and_b32_e32 v75, 0xffff0000, v75
	v_and_b32_e32 v74, 0xffff0000, v79
	v_lshlrev_b32_e32 v79, 16, v76
	v_lshlrev_b32_e32 v78, 16, v80
	v_and_b32_e32 v123, 0xffff0000, v76
	v_and_b32_e32 v122, 0xffff0000, v80
	v_lshlrev_b32_e32 v125, 16, v77
	v_lshlrev_b32_e32 v124, 16, v81
	v_and_b32_e32 v77, 0xffff0000, v77
	v_and_b32_e32 v76, 0xffff0000, v81
	s_waitcnt vmcnt(3)
	v_pk_mul_f32 v[80:81], v[84:85], v[96:97] op_sel:[0,1] op_sel_hi:[1,0]
	v_pk_mul_f32 v[84:85], v[84:85], v[96:97]
	v_pk_mul_f32 v[96:97], v[86:87], v[118:119] op_sel:[0,1] op_sel_hi:[1,0]
	v_pk_mul_f32 v[86:87], v[86:87], v[118:119]
	s_waitcnt vmcnt(2)
	v_pk_mul_f32 v[118:119], v[88:89], v[120:121] op_sel:[0,1] op_sel_hi:[1,0]
	v_pk_mul_f32 v[88:89], v[88:89], v[120:121]
	v_pk_mul_f32 v[120:121], v[90:91], v[74:75] op_sel:[0,1] op_sel_hi:[1,0]
	v_pk_mul_f32 v[74:75], v[90:91], v[74:75]
	s_waitcnt vmcnt(1)
	v_pk_mul_f32 v[90:91], v[92:93], v[78:79] op_sel:[0,1] op_sel_hi:[1,0]
	v_pk_mul_f32 v[78:79], v[92:93], v[78:79]
	v_pk_mul_f32 v[92:93], v[94:95], v[122:123] op_sel:[0,1] op_sel_hi:[1,0]
	v_pk_mul_f32 v[94:95], v[94:95], v[122:123]
	s_waitcnt vmcnt(0)
	v_pk_mul_f32 v[122:123], v[114:115], v[124:125] op_sel:[0,1] op_sel_hi:[1,0]
	v_pk_mul_f32 v[114:115], v[114:115], v[124:125]
	v_pk_mul_f32 v[124:125], v[116:117], v[76:77] op_sel:[0,1] op_sel_hi:[1,0]
	v_pk_mul_f32 v[76:77], v[116:117], v[76:77]
	v_sub_f32_e32 v0, v80, v81
	v_add_f32_e32 v80, v84, v85
	v_sub_f32_e32 v81, v96, v97
	v_add_f32_e32 v84, v86, v87
	v_sub_f32_e32 v85, v118, v119
	v_add_f32_e32 v86, v88, v89
	v_sub_f32_e32 v87, v120, v121
	v_add_f32_e32 v74, v74, v75
	v_sub_f32_e32 v75, v90, v91
	v_add_f32_e32 v78, v78, v79
	v_sub_f32_e32 v79, v92, v93
	v_add_f32_e32 v88, v94, v95
	v_sub_f32_e32 v89, v122, v123
	v_add_f32_e32 v90, v114, v115
	v_sub_f32_e32 v91, v124, v125
	v_add_f32_e32 v76, v76, v77
	v_mul_f32_e32 v77, 0x3e0293ee, v80
	v_mul_f32_e32 v80, 0x3e0293ee, v81
	v_mul_f32_e32 v81, 0x3e0293ee, v84
	v_mul_f32_e32 v84, 0x3e0293ee, v85
	v_mul_f32_e32 v85, 0x3e0293ee, v86
	v_mul_f32_e32 v86, 0x3e0293ee, v87
	v_mul_f32_e32 v74, 0x3e0293ee, v74
	v_mul_f32_e32 v75, 0x3e0293ee, v75
	v_mul_f32_e32 v78, 0x3e0293ee, v78
	v_mul_f32_e32 v79, 0x3e0293ee, v79
	v_mul_f32_e32 v87, 0x3e0293ee, v88
	v_mul_f32_e32 v88, 0x3e0293ee, v89
	v_mul_f32_e32 v89, 0x3e0293ee, v90
	v_mul_f32_e32 v90, 0x3e0293ee, v91
	v_mul_f32_e32 v76, 0x3e0293ee, v76
	v_mul_f32_e32 v0, 0x3e0293ee, v0
	v_cvt_pk_bf16_f32 v114, v0, v80
	v_cvt_pk_bf16_f32 v115, v84, v86
	v_cvt_pk_bf16_f32 v116, v75, v79
	v_cvt_pk_bf16_f32 v117, v88, v90
	v_cvt_pk_bf16_f32 v118, v77, v81
	v_cvt_pk_bf16_f32 v119, v85, v74
	v_cvt_pk_bf16_f32 v120, v78, v87
	v_cvt_pk_bf16_f32 v121, v89, v76
	global_load_dwordx4 v[74:77], v[82:83], off offset:384
	global_load_dwordx4 v[78:81], v[82:83], off offset:400
	global_load_dwordx4 v[84:87], v[82:83], off offset:416
	global_load_dwordx4 v[88:91], v[82:83], off offset:432
	v_lshlrev_b32_e32 v83, 16, v66
	v_lshlrev_b32_e32 v82, 16, v70
	v_and_b32_e32 v93, 0xffff0000, v66
	v_and_b32_e32 v92, 0xffff0000, v70
	v_lshlrev_b32_e32 v95, 16, v67
	v_lshlrev_b32_e32 v94, 16, v71
	v_and_b32_e32 v67, 0xffff0000, v67
	v_and_b32_e32 v66, 0xffff0000, v71
	v_lshlrev_b32_e32 v71, 16, v68
	v_lshlrev_b32_e32 v70, 16, v72
	v_and_b32_e32 v97, 0xffff0000, v68
	v_and_b32_e32 v96, 0xffff0000, v72
	v_lshlrev_b32_e32 v123, 16, v69
	v_lshlrev_b32_e32 v122, 16, v73
	v_and_b32_e32 v69, 0xffff0000, v69
	v_and_b32_e32 v68, 0xffff0000, v73
	s_waitcnt vmcnt(3)
	v_pk_mul_f32 v[72:73], v[74:75], v[82:83] op_sel:[0,1] op_sel_hi:[1,0]
	v_pk_mul_f32 v[74:75], v[74:75], v[82:83]
	v_pk_mul_f32 v[82:83], v[76:77], v[92:93] op_sel:[0,1] op_sel_hi:[1,0]
	v_pk_mul_f32 v[76:77], v[76:77], v[92:93]
	s_waitcnt vmcnt(2)
	v_pk_mul_f32 v[92:93], v[78:79], v[94:95] op_sel:[0,1] op_sel_hi:[1,0]
	v_pk_mul_f32 v[78:79], v[78:79], v[94:95]
	v_pk_mul_f32 v[94:95], v[80:81], v[66:67] op_sel:[0,1] op_sel_hi:[1,0]
	v_pk_mul_f32 v[66:67], v[80:81], v[66:67]
	s_waitcnt vmcnt(1)
	v_pk_mul_f32 v[80:81], v[84:85], v[70:71] op_sel:[0,1] op_sel_hi:[1,0]
	v_pk_mul_f32 v[70:71], v[84:85], v[70:71]
	v_pk_mul_f32 v[84:85], v[86:87], v[96:97] op_sel:[0,1] op_sel_hi:[1,0]
	v_pk_mul_f32 v[86:87], v[86:87], v[96:97]
	s_waitcnt vmcnt(0)
	v_pk_mul_f32 v[96:97], v[88:89], v[122:123] op_sel:[0,1] op_sel_hi:[1,0]
	v_pk_mul_f32 v[88:89], v[88:89], v[122:123]
	v_pk_mul_f32 v[122:123], v[90:91], v[68:69] op_sel:[0,1] op_sel_hi:[1,0]
	v_add_f32_e32 v70, v70, v71
	v_pk_mul_f32 v[68:69], v[90:91], v[68:69]
	v_sub_f32_e32 v0, v72, v73
	v_add_f32_e32 v72, v74, v75
	v_sub_f32_e32 v73, v82, v83
	v_add_f32_e32 v74, v76, v77
	v_sub_f32_e32 v75, v92, v93
	v_add_f32_e32 v76, v78, v79
	v_sub_f32_e32 v77, v94, v95
	v_add_f32_e32 v66, v66, v67
	v_sub_f32_e32 v67, v80, v81
	v_sub_f32_e32 v71, v84, v85
	v_add_f32_e32 v78, v86, v87
	v_sub_f32_e32 v79, v96, v97
	v_add_f32_e32 v80, v88, v89
	v_sub_f32_e32 v81, v122, v123
	v_mul_f32_e32 v70, 0x3e0293ee, v70
	v_add_f32_e32 v68, v68, v69
	v_mul_f32_e32 v0, 0x3e0293ee, v0
	v_mul_f32_e32 v69, 0x3e0293ee, v72
	v_mul_f32_e32 v72, 0x3e0293ee, v73
	v_mul_f32_e32 v73, 0x3e0293ee, v74
	v_mul_f32_e32 v74, 0x3e0293ee, v75
	v_mul_f32_e32 v75, 0x3e0293ee, v76
	v_mul_f32_e32 v76, 0x3e0293ee, v77
	v_mul_f32_e32 v66, 0x3e0293ee, v66
	v_mul_f32_e32 v67, 0x3e0293ee, v67
	v_mul_f32_e32 v71, 0x3e0293ee, v71
	v_mul_f32_e32 v77, 0x3e0293ee, v78
	v_mul_f32_e32 v78, 0x3e0293ee, v79
	v_mul_f32_e32 v79, 0x3e0293ee, v80
	v_mul_f32_e32 v80, 0x3e0293ee, v81
	v_cvt_pk_bf16_f32 v122, v0, v72
	v_cvt_pk_bf16_f32 v123, v74, v76
	v_cvt_pk_bf16_f32 v124, v67, v71
	v_cvt_pk_bf16_f32 v125, v78, v80
	v_cvt_pk_bf16_f32 v126, v69, v73
	v_cvt_pk_bf16_f32 v127, v75, v66
	v_cvt_pk_bf16_f32 v128, v70, v77
	v_mov_b32_e32 v70, v198
	v_mul_f32_e32 v68, 0x3e0293ee, v68
	v_cvt_pk_bf16_f32 v129, v79, v68
	v_mov_b32_e32 v80, v1
	v_readfirstlane_b32 s0, v70
	s_ashr_i32 s4, s0, 6
	s_lshl_b32 s5, s4, 3
	v_bfe_u32 v0, v70, 2, 3
	v_lshrrev_b32_e32 v68, 1, v70
	s_lshl_b32 s0, s4, 2
	v_bitop3_b32 v0, s5, v215, v0 bitop3:0xc8
	v_and_b32_e32 v68, 8, v68
	s_and_b32 s0, s0, 4
	v_or3_b32 v0, v68, v0, s0
	s_and_b64 s[0:1], s[12:13], exec
	s_cselect_b32 s41, 2, 3
	v_lshlrev_b32_e32 v0, s41, v0
	v_lshlrev_b32_e32 v69, 3, v70
	v_add_u32_e32 v0, s37, v0
	s_movk_i32 s0, 0x2200
	v_bfe_u32 v66, v70, 4, 2
	v_and_b32_e32 v68, 32, v70
	v_and_b32_e32 v69, 24, v69
	v_mul_lo_u32 v0, v0, s0
	v_or3_b32 v188, v68, v69, v0
	v_or_b32_e32 v0, s5, v66
	v_lshlrev_b32_e32 v0, s41, v0
	v_add_u32_e32 v0, s37, v0
	v_bitop3_b32 v68, v66, v70, 15 bitop3:0x78
	v_mul_lo_u32 v0, v0, s0
	v_lshl_or_b32 v0, v68, 3, v0
	v_or_b32_e32 v68, 4, v66
	v_and_b32_e32 v67, 15, v70
	v_or_b32_e32 v68, s5, v68
	v_bitop3_b32 v66, v66, v67, 4 bitop3:0x36
	v_lshlrev_b32_e32 v67, s41, v68
	v_add_u32_e32 v67, s37, v67
	v_mul_lo_u32 v67, v67, s0
	s_mov_b32 s0, 0x220000
	s_cselect_b32 s42, s0, 0x440000
	s_lshl_b32 s0, s4, 11
	s_add_i32 s1, 0, 0x10000
	s_add_i32 s43, s1, s0
	v_lshl_add_u64 v[68:69], v[0:1], 1, s[16:17]
	s_mov_b32 m0, s43
	s_add_i32 s44, s0, 0
	v_lshl_or_b32 v190, v66, 3, v67
	global_load_lds_dwordx4 v[68:69], off
	v_lshl_add_u64 v[68:69], v[188:189], 1, s[18:19]
	s_mov_b32 m0, s44
	s_or_b32 s5, s0, 0x400
	global_load_lds_dwordx4 v[68:69], off
	v_lshl_add_u64 v[68:69], v[190:191], 1, s[16:17]
	s_add_i32 m0, s1, s5
	v_or_b32_e32 v66, 64, v188
	global_load_lds_dwordx4 v[68:69], off
	s_add_i32 m0, s44, 0x400
	v_mov_b32_e32 v67, v1
	s_cmp_gt_i32 s4, 3
	v_lshl_add_u64 v[68:69], v[66:67], 1, s[18:19]
	s_cselect_b64 s[20:21], -1, 0
	s_cmp_lt_i32 s4, 4
	global_load_lds_dwordx4 v[68:69], off
	s_cselect_b64 s[22:23], -1, 0
	v_add_u32_e32 v68, s42, v0
	v_mov_b32_e32 v69, v1
	s_add_i32 s1, 0, 0x14000
	v_lshl_add_u64 v[68:69], v[68:69], 1, s[16:17]
	s_add_i32 m0, s1, s0
	v_add_u32_e32 v66, s42, v66
	global_load_lds_dwordx4 v[68:69], off
	v_add_u32_e32 v68, s42, v188
	v_mov_b32_e32 v69, v1
	v_lshl_add_u64 v[68:69], v[68:69], 1, s[18:19]
	s_add_i32 m0, s44, 0x4000
	v_lshl_add_u64 v[66:67], v[66:67], 1, s[18:19]
	global_load_lds_dwordx4 v[68:69], off
	v_add_u32_e32 v68, s42, v190
	v_mov_b32_e32 v69, v1
	v_lshl_add_u64 v[68:69], v[68:69], 1, s[16:17]
	s_add_i32 m0, s1, s5
	v_readlane_b32 s0, v254, 1
	global_load_lds_dwordx4 v[68:69], off
	s_add_i32 m0, s44, 0x4400
	v_and_b32_e32 v69, 0x3fffffc0, v70
	global_load_lds_dwordx4 v[66:67], off
	v_and_b32_e32 v66, 63, v70
	v_lshlrev_b32_e32 v71, 4, v70
	v_and_b32_e32 v67, 31, v70
	v_bfe_u32 v68, v70, 5, 1
	v_lshl_add_u32 v189, v69, 2, s0
	v_lshlrev_b32_e32 v69, 3, v66
	v_and_b32_e32 v72, 0xc0, v71
	v_lshlrev_b32_e32 v70, 1, v70
	v_and_or_b32 v72, v69, 24, v72
	v_and_b32_e32 v70, 32, v70
	v_and_b32_e32 v69, 0x100, v69
	v_lshlrev_b32_e32 v199, 4, v68
	s_movk_i32 s0, 0x70
	v_or3_b32 v69, v72, v70, v69
	v_and_b32_e32 v70, 0x70, v71
	v_bitop3_b32 v216, v199, v71, s0 bitop3:0x78
	s_movk_i32 s0, 0x60
	s_and_b64 s[4:5], s[12:13], exec
	v_bitop3_b32 v219, v199, v70, s0 bitop3:0x36
	s_waitcnt vmcnt(4)
	v_cmp_gt_u32_e64 s[0:1], 32, v66
	s_movk_i32 s4, 0x1f8
	v_and_b32_e32 v66, s40, v223
	v_mov_b32_e32 v81, v1
	v_lshlrev_b32_e32 v191, 8, v67
	v_bitop3_b32 v217, v199, v70, 32 bitop3:0x36
	v_bitop3_b32 v218, v199, v70, 64 bitop3:0x36
	v_add_u32_e32 v220, 0, v69
	v_lshl_add_u32 v221, v67, 2, v189
	s_cselect_b32 s46, 0xfc, s4
	v_mul_i32_i24_e32 v222, -4, v68
	v_cmp_eq_u32_e64 s[4:5], 0, v66
	s_lshl_b32 s6, s38, 6
	v_mov_b32_e32 v66, v1
	v_mov_b32_e32 v67, v1
	v_mov_b32_e32 v68, v1
	v_mov_b32_e32 v69, v1
	v_mov_b32_e32 v70, v1
	v_mov_b32_e32 v71, v1
	v_mov_b32_e32 v72, v1
	v_mov_b32_e32 v73, v1
	v_mov_b32_e32 v74, v1
	v_mov_b32_e32 v75, v1
	v_mov_b32_e32 v76, v1
	v_mov_b32_e32 v77, v1
	v_mov_b32_e32 v78, v1
	v_mov_b32_e32 v79, v1
	v_mov_b64_e32 v[96:97], v[80:81]
	s_or_b32 s47, s6, 64
	s_lshl_b32 s48, s42, 1
	s_mov_b64 s[6:7], 0
	v_mov_b32_e32 v200, v0
	v_mov_b64_e32 v[94:95], v[78:79]
	v_mov_b64_e32 v[92:93], v[76:77]
	v_mov_b64_e32 v[90:91], v[74:75]
	v_mov_b64_e32 v[88:89], v[72:73]
	v_mov_b64_e32 v[86:87], v[70:71]
	v_mov_b64_e32 v[84:85], v[68:69]
	v_mov_b64_e32 v[82:83], v[66:67]
	s_waitcnt vmcnt(4) lgkmcnt(0)
	s_barrier
	s_branch .LBB0_1251
.LBB0_1250:
	s_add_i32 s8, s50, 1
	s_cmp_lg_u32 s50, 2
	s_cselect_b32 s50, s8, 0
	s_add_i32 s8, s51, 1
	s_sub_i32 s49, s49, 64
	s_and_b32 s51, s8, 3
	s_add_i32 s52, s52, 1
	s_add_i32 s45, s45, 64
	s_add_i32 s8, s47, s49
	v_add_u32_e32 v188, s42, v188
	v_add_u32_e32 v190, s42, v190
	s_cmp_lg_u32 s8, 0
	v_add_u32_e32 v200, s42, v200
	s_waitcnt vmcnt(4) lgkmcnt(0)
	s_barrier
	s_cbranch_scc0 .LBB0_1275
